# all GEMM MFMA blocks scheduled as accumulate chains (dependence-preserving), incl. peeled first iterations, PLE GEMM and the register-rotating loops
# speedup vs baseline: 1.0086x; 1.0017x over previous
;     __device__ __forceinline__ bool next(int i, Unit& u) const { if (i >= count) return false; const int L = first + i; u.pm = L / nN; u.pn = L % nN; return true; }
; #define PG8_STAGE(bufoff, gbase, voff) do { if constexpr (ABL & 1) break; glds16s<(bufoff)>((voff)[0], (const void*)(gbase), ldsbw); glds16s<(bufoff) + 8192>((voff)[1], (const void*)(gbase), ldsbw); } while (0)
; #define PG8_LDA(dst, b, h) do { if constexpr (ABL & 4) break; _Pragma("unroll") for (int m = 0; m < 4; ++m) _Pragma("unroll") for (int k = 0; k < 2; ++k) dst[m][k] = *(const LAS f16x8*)(lds + PG8_SA(b, h) + aoff + m * 2048 + k * 1024); } while (0)
; #define PG8_LDB(dst, b, h) do { if constexpr (ABL & 4) break; _Pragma("unroll") for (int n = 0; n < 2; ++n) _Pragma("unroll") for (int k = 0; k < 2; ++k) dst[n][k] = *(const LAS f16x8*)(lds + PG8_SB(b, h) + boff + n * 2048 + k * 1024); } while (0)
; #define PG8_MMAF(ai, bj, At, Bt) do { if (t == 0) PG8_MMA0(ai, bj, At, Bt); else PG8_MMA(ai, bj, At, Bt); } while (0)
; #define PG8_WAIT_V(n) asm volatile("s_waitcnt vmcnt(" #n ")" ::: "memory")
; #define PG8_BAR __builtin_amdgcn_s_barrier()
;     ...
;         const bool has_next = S.next(ui + 1, nxt);
;         const char* nA = has_next ? (const char*)g.A + (size_t)nxt.pm * tstep : cA; const char* nB = has_next ? (const char*)g.Bt + (size_t)nxt.pn * tstep : cB;
;         for (int t = 0; t < nt; t += 2) {
;             const bool last = (t == nt - 2);
;             const char* a1 = cA + (size_t)(t + 1) * kstep;
;             const char* a2 = last ? nA : cA + (size_t)(t + 2) * kstep; const char* b2 = last ? nB : cB + (size_t)(t + 2) * kstep;
;             const char* a3 = a2 + kstep; const char* b3 = b2 + kstep;
;             if (last && has_next) S.a_ready(nxt);
;             if constexpr (SP2) {
;             PG8_LDB(B0, 0, 0); PG8_LDB(B1, 0, 1); PG8_SCHED; PG8_LDA(At, 0, 0); PG8_STAGE(PG8_SA(1, 1), a1 + hstep, voffA);
;             PG8_WAIT_V(8); PG8_WAIT_L(0); PG8_BAR; PG8_MMAF(0, 0, At, B0); PG8_MMAF(0, 1, At, B1); PG8_BAR; PG8_SCHED;
;             const bool fin = last && !has_next;
;             PG8_LDA(At, 0, 1); if (!fin) { PG8_STAGE(PG8_SB(0, 0), b2, voffB); PG8_STAGE(PG8_SB(0, 1), b2 + hstep, voffB); PG8_STAGE(PG8_SA(0, 0), a2, voffA); }
;             if (!fin) PG8_WAIT_V(8); else PG8_WAIT_V(2); PG8_WAIT_L(0); PG8_BAR; PG8_MMAF(1, 0, At, B0); PG8_MMAF(1, 1, At, B1); PG8_BAR; PG8_SCHED;
.LBB0_229:
	s_ashr_i32 s53, s52, 31
	s_lshl_b64 s[8:9], s[52:53], 19
	s_add_u32 s54, s74, s8
	s_addc_u32 s55, s75, s9
	s_and_b64 s[8:9], exec, s[4:5]
	ds_read_b128 v[2:5], v236
	ds_read_b128 v[6:9], v236 offset:1024
	ds_read_b128 v[10:13], v236 offset:2048
	ds_read_b128 v[14:17], v236 offset:3072
	ds_read_b128 v[18:21], v237
	ds_read_b128 v[22:25], v237 offset:1024
	ds_read_b128 v[26:29], v237 offset:2048
	ds_read_b128 v[30:33], v237 offset:3072
	s_cselect_b32 s11, s63, s55
	s_cselect_b32 s35, s62, s54
	s_ashr_i32 s1, s0, 31
	s_lshl_b64 s[8:9], s[0:1], 19
	s_add_u32 s56, s90, s8
	s_addc_u32 s57, s91, s9
	s_and_b64 s[8:9], exec, s[4:5]
	s_cselect_b32 s1, s7, s57
	s_cselect_b32 s46, s6, s56
	s_add_u32 s8, s62, 0x100
	s_addc_u32 s9, s63, 0
	s_add_u32 s64, s6, 0x100
	s_addc_u32 s65, s7, 0
	s_add_u32 s24, s62, 0x180
	s_addc_u32 s25, s63, 0
	ds_read_b128 v[34:37], v238
	ds_read_b128 v[38:41], v238 offset:1024
	ds_read_b128 v[42:45], v238 offset:2048
	ds_read_b128 v[46:49], v238 offset:3072
	ds_read_b128 v[50:53], v238 offset:4096
	ds_read_b128 v[54:57], v238 offset:5120
	ds_read_b128 v[58:61], v238 offset:6144
	ds_read_b128 v[62:65], v238 offset:7168
	s_add_u32 s26, s6, 0x180
	s_addc_u32 s27, s7, 0
	s_add_u32 s76, s62, 0x40080
	s_addc_u32 s77, s63, 0
	s_add_u32 m0, s28, 0xc000
	s_nop 0
	global_load_lds_dwordx4 v232, s[76:77]
	s_nop 0
	s_add_u32 m0, s28, 0xe000
	s_nop 0
	global_load_lds_dwordx4 v234, s[76:77]
	s_waitcnt vmcnt(8)
	s_waitcnt lgkmcnt(0)
	s_barrier
	v_mfma_f32_16x16x32_f16 v[86:89], v[10:13], v[50:53], 0
	s_setprio 1
	v_mfma_f32_16x16x32_f16 v[90:93], v[14:17], v[54:57], v[86:89]
	v_mfma_f32_16x16x32_f16 v[86:89], v[2:5], v[58:61], 0
	v_mfma_f32_16x16x32_f16 v[94:97], v[6:9], v[62:65], v[86:89]
	v_mfma_f32_16x16x32_f16 v[66:69], v[2:5], v[34:37], 0
	v_mfma_f32_16x16x32_f16 v[66:69], v[6:9], v[38:41], v[66:69]
	v_mfma_f32_16x16x32_f16 v[70:73], v[10:13], v[34:37], 0
	v_mfma_f32_16x16x32_f16 v[70:73], v[14:17], v[38:41], v[70:73]
	v_mfma_f32_16x16x32_f16 v[74:77], v[2:5], v[42:45], 0
	v_mfma_f32_16x16x32_f16 v[74:77], v[6:9], v[46:49], v[74:77]
	v_mfma_f32_16x16x32_f16 v[78:81], v[10:13], v[42:45], 0
	v_mfma_f32_16x16x32_f16 v[78:81], v[14:17], v[46:49], v[78:81]
	v_mfma_f32_16x16x32_f16 v[82:85], v[2:5], v[50:53], 0
	v_mfma_f32_16x16x32_f16 v[82:85], v[6:9], v[54:57], v[82:85]
	v_mfma_f32_16x16x32_f16 v[86:89], v[10:13], v[58:61], 0
	v_mfma_f32_16x16x32_f16 v[106:109], v[14:17], v[62:65], v[86:89]
	v_mfma_f32_16x16x32_f16 v[86:89], v[18:21], v[34:37], 0
	v_mfma_f32_16x16x32_f16 v[110:113], v[22:25], v[38:41], v[86:89]
	v_mfma_f32_16x16x32_f16 v[34:37], v[26:29], v[34:37], 0
	v_mfma_f32_16x16x32_f16 v[34:37], v[30:33], v[38:41], v[34:37]
	v_mfma_f32_16x16x32_f16 v[38:41], v[18:21], v[42:45], 0
	v_mfma_f32_16x16x32_f16 v[38:41], v[22:25], v[46:49], v[38:41]
	v_mfma_f32_16x16x32_f16 v[42:45], v[26:29], v[42:45], 0
	v_mfma_f32_16x16x32_f16 v[42:45], v[30:33], v[46:49], v[42:45]
	v_mfma_f32_16x16x32_f16 v[46:49], v[18:21], v[50:53], 0
	v_mfma_f32_16x16x32_f16 v[46:49], v[22:25], v[54:57], v[46:49]
	v_mfma_f32_16x16x32_f16 v[50:53], v[26:29], v[50:53], 0
	v_mfma_f32_16x16x32_f16 v[54:57], v[30:33], v[54:57], v[50:53]
	v_mfma_f32_16x16x32_f16 v[50:53], v[18:21], v[58:61], 0
	v_mfma_f32_16x16x32_f16 v[130:133], v[22:25], v[62:65], v[50:53]
	v_mfma_f32_16x16x32_f16 v[50:53], v[26:29], v[58:61], 0
	v_mfma_f32_16x16x32_f16 v[62:65], v[30:33], v[62:65], v[50:53]
	s_barrier
	s_setprio 0
	s_nop 4
	ds_read_b128 v[50:53], v238 offset:16384
	ds_read_b128 v[58:61], v238 offset:17408
	ds_read_b128 v[86:89], v238 offset:18432
	ds_read_b128 v[98:101], v238 offset:19456
	ds_read_b128 v[102:105], v238 offset:20480
	ds_read_b128 v[114:117], v238 offset:21504
	ds_read_b128 v[118:121], v238 offset:22528
	ds_read_b128 v[122:125], v238 offset:23552
	s_add_u32 m0, s28, 0x10000
	s_nop 0
	global_load_lds_dwordx4 v233, s[64:65]
	s_nop 0
	s_add_u32 m0, s28, 0x12000
	s_nop 0
	global_load_lds_dwordx4 v235, s[64:65]
	s_add_u32 s64, s6, 0x40100
	s_addc_u32 s65, s7, 0
	s_add_u32 m0, s28, 0x14000
	s_nop 0
	global_load_lds_dwordx4 v233, s[64:65]
	s_nop 0
	s_add_u32 m0, s28, 0x16000
	s_nop 0
	global_load_lds_dwordx4 v235, s[64:65]
	s_nop 0
	s_add_u32 m0, s28, 0
	s_nop 0
	global_load_lds_dwordx4 v232, s[8:9]
	s_nop 0
	s_add_u32 m0, s28, 0x2000
	s_nop 0
	global_load_lds_dwordx4 v234, s[8:9]
	s_waitcnt vmcnt(8)
	s_waitcnt lgkmcnt(0)
	s_barrier
	v_mfma_f32_16x16x32_f16 v[126:129], v[2:5], v[50:53], 0
	s_setprio 1
	v_mfma_f32_16x16x32_f16 v[134:137], v[6:9], v[58:61], v[126:129]
	v_mfma_f32_16x16x32_f16 v[126:129], v[10:13], v[50:53], 0
	v_mfma_f32_16x16x32_f16 v[138:141], v[14:17], v[58:61], v[126:129]
	v_mfma_f32_16x16x32_f16 v[126:129], v[2:5], v[86:89], 0
	v_mfma_f32_16x16x32_f16 v[142:145], v[6:9], v[98:101], v[126:129]
	v_mfma_f32_16x16x32_f16 v[126:129], v[10:13], v[86:89], 0
	v_mfma_f32_16x16x32_f16 v[146:149], v[14:17], v[98:101], v[126:129]
	v_mfma_f32_16x16x32_f16 v[126:129], v[2:5], v[102:105], 0
	v_mfma_f32_16x16x32_f16 v[150:153], v[6:9], v[114:117], v[126:129]
	v_mfma_f32_16x16x32_f16 v[2:5], v[2:5], v[118:121], 0
	v_mfma_f32_16x16x32_f16 v[2:5], v[6:9], v[122:125], v[2:5]
	v_mfma_f32_16x16x32_f16 v[6:9], v[10:13], v[118:121], 0
	v_mfma_f32_16x16x32_f16 v[126:129], v[10:13], v[102:105], 0
	v_mfma_f32_16x16x32_f16 v[154:157], v[14:17], v[114:117], v[126:129]
	v_mfma_f32_16x16x32_f16 v[10:13], v[14:17], v[122:125], v[6:9]
	v_mfma_f32_16x16x32_f16 v[6:9], v[18:21], v[50:53], 0
	v_mfma_f32_16x16x32_f16 v[158:161], v[22:25], v[58:61], v[6:9]
	v_mfma_f32_16x16x32_f16 v[6:9], v[26:29], v[50:53], 0
	v_mfma_f32_16x16x32_f16 v[162:165], v[30:33], v[58:61], v[6:9]
	v_mfma_f32_16x16x32_f16 v[6:9], v[18:21], v[86:89], 0
	v_mfma_f32_16x16x32_f16 v[166:169], v[22:25], v[98:101], v[6:9]
	v_mfma_f32_16x16x32_f16 v[6:9], v[26:29], v[86:89], 0
	v_mfma_f32_16x16x32_f16 v[170:173], v[30:33], v[98:101], v[6:9]
	v_mfma_f32_16x16x32_f16 v[6:9], v[18:21], v[102:105], 0
	v_mfma_f32_16x16x32_f16 v[174:177], v[22:25], v[114:117], v[6:9]
	v_mfma_f32_16x16x32_f16 v[6:9], v[26:29], v[102:105], 0
	v_mfma_f32_16x16x32_f16 v[178:181], v[30:33], v[114:117], v[6:9]
	v_mfma_f32_16x16x32_f16 v[6:9], v[18:21], v[118:121], 0
	v_mfma_f32_16x16x32_f16 v[22:25], v[22:25], v[122:125], v[6:9]
	v_mfma_f32_16x16x32_f16 v[6:9], v[26:29], v[118:121], 0
	v_mfma_f32_16x16x32_f16 v[182:185], v[30:33], v[122:125], v[6:9]
	s_barrier
; #define PG8_STAGE(bufoff, gbase, voff) do { if constexpr (ABL & 1) break; glds16s<(bufoff)>((voff)[0], (const void*)(gbase), ldsbw); glds16s<(bufoff) + 8192>((voff)[1], (const void*)(gbase), ldsbw); } while (0)
; #define PG8_LDA(dst, b, h) do { if constexpr (ABL & 4) break; _Pragma("unroll") for (int m = 0; m < 4; ++m) _Pragma("unroll") for (int k = 0; k < 2; ++k) dst[m][k] = *(const LAS f16x8*)(lds + PG8_SA(b, h) + aoff + m * 2048 + k * 1024); } while (0)
; #define PG8_LDB(dst, b, h) do { if constexpr (ABL & 4) break; _Pragma("unroll") for (int n = 0; n < 2; ++n) _Pragma("unroll") for (int k = 0; k < 2; ++k) dst[n][k] = *(const LAS f16x8*)(lds + PG8_SB(b, h) + boff + n * 2048 + k * 1024); } while (0)
; #define PG8_MMA(ai, bj, At, Bt) do { if constexpr (ABL & 2) break; __builtin_amdgcn_s_setprio(1); _Pragma("unroll") for (int m = 0; m < 4; ++m) _Pragma("unroll") for (int n = 0; n < 2; ++n) _Pragma("unroll") for (int k = 0; k < 2; ++k) \
;         acc[ai][bj][m][n] = __builtin_amdgcn_mfma_f32_16x16x32_f16(Bt[n][k], At[m][k], acc[ai][bj][m][n], 0, 0, 0); __builtin_amdgcn_s_setprio(0); } while (0)
; #define PG8_WAIT_V(n) asm volatile("s_waitcnt vmcnt(" #n ")" ::: "memory")
; #define PG8_WAIT_L(n) asm volatile("s_waitcnt lgkmcnt(" #n ")" ::: "memory")
; #define PG8_BAR __builtin_amdgcn_s_barrier()
; #define PG8_SCHED __builtin_amdgcn_sched_barrier(0)
;     ...
;             PG8_LDB(B0, 1, 0); PG8_LDB(B1, 1, 1); PG8_SCHED; PG8_LDA(At, 1, 0); if (!fin) PG8_STAGE(PG8_SA(0, 1), a2 + hstep, voffA);
;             if (!fin) PG8_WAIT_V(8); else PG8_WAIT_V(0); PG8_WAIT_L(0); PG8_BAR; PG8_MMA(0, 0, At, B0); PG8_MMA(0, 1, At, B1); PG8_BAR; PG8_SCHED;
;             PG8_LDA(At, 1, 1); if (!fin) { PG8_STAGE(PG8_SB(1, 0), b3, voffB); PG8_STAGE(PG8_SB(1, 1), b3 + hstep, voffB); PG8_STAGE(PG8_SA(1, 0), a3, voffA); }
;             if (!fin) PG8_WAIT_V(8); PG8_WAIT_L(0); PG8_BAR; PG8_MMA(1, 0, At, B0); PG8_MMA(1, 1, At, B1); PG8_BAR; PG8_SCHED;
	s_setprio 0
	s_nop 4
	ds_read_b128 v[6:9], v239
	ds_read_b128 v[26:29], v239 offset:1024
	ds_read_b128 v[186:189], v239 offset:2048
	ds_read_b128 v[190:193], v239 offset:3072
	ds_read_b128 v[206:209], v240
	ds_read_b128 v[210:213], v240 offset:1024
	ds_read_b128 v[214:217], v240 offset:2048
	ds_read_b128 v[218:221], v240 offset:3072
	ds_read_b128 v[14:17], v238 offset:32768
	ds_read_b128 v[18:21], v238 offset:33792
	ds_read_b128 v[30:33], v238 offset:34816
	ds_read_b128 v[222:225], v238 offset:35840
	ds_read_b128 v[226:229], v238 offset:36864
	ds_read_b128 v[242:245], v238 offset:37888
	ds_read_b128 v[246:249], v238 offset:38912
	ds_read_b128 v[250:253], v238 offset:39936
	s_add_u32 s62, s62, 0x40100
	s_addc_u32 s63, s63, 0
	s_add_u32 m0, s28, 0x4000
	s_nop 0
	global_load_lds_dwordx4 v232, s[62:63]
	s_nop 0
	s_add_u32 m0, s28, 0x6000
	s_nop 0
	global_load_lds_dwordx4 v234, s[62:63]
	s_waitcnt vmcnt(8)
	s_waitcnt lgkmcnt(0)
	s_barrier
	v_mfma_f32_16x16x32_f16 v[50:53], v[6:9], v[14:17], v[66:69]
	s_setprio 1
	v_mfma_f32_16x16x32_f16 v[118:121], v[26:29], v[18:21], v[50:53]
	v_mfma_f32_16x16x32_f16 v[50:53], v[186:189], v[14:17], v[70:73]
	v_mfma_f32_16x16x32_f16 v[114:117], v[190:193], v[18:21], v[50:53]
	v_mfma_f32_16x16x32_f16 v[50:53], v[6:9], v[30:33], v[74:77]
	v_mfma_f32_16x16x32_f16 v[102:105], v[26:29], v[222:225], v[50:53]
	v_mfma_f32_16x16x32_f16 v[50:53], v[186:189], v[30:33], v[78:81]
	v_mfma_f32_16x16x32_f16 v[98:101], v[190:193], v[222:225], v[50:53]
	v_mfma_f32_16x16x32_f16 v[50:53], v[6:9], v[226:229], v[82:85]
	v_mfma_f32_16x16x32_f16 v[86:89], v[26:29], v[242:245], v[50:53]
	v_mfma_f32_16x16x32_f16 v[50:53], v[186:189], v[226:229], v[90:93]
	v_mfma_f32_16x16x32_f16 v[78:81], v[190:193], v[242:245], v[50:53]
	v_mfma_f32_16x16x32_f16 v[50:53], v[6:9], v[246:249], v[94:97]
	v_mfma_f32_16x16x32_f16 v[58:61], v[26:29], v[250:253], v[50:53]
	v_mfma_f32_16x16x32_f16 v[50:53], v[186:189], v[246:249], v[106:109]
	v_mfma_f32_16x16x32_f16 v[50:53], v[190:193], v[250:253], v[50:53]
	v_mfma_f32_16x16x32_f16 v[66:69], v[206:209], v[14:17], v[110:113]
	v_mfma_f32_16x16x32_f16 v[126:129], v[210:213], v[18:21], v[66:69]
	v_mfma_f32_16x16x32_f16 v[14:17], v[214:217], v[14:17], v[34:37]
	v_mfma_f32_16x16x32_f16 v[122:125], v[218:221], v[18:21], v[14:17]
	v_mfma_f32_16x16x32_f16 v[14:17], v[206:209], v[30:33], v[38:41]
	v_mfma_f32_16x16x32_f16 v[110:113], v[210:213], v[222:225], v[14:17]
	v_mfma_f32_16x16x32_f16 v[14:17], v[214:217], v[30:33], v[42:45]
	v_mfma_f32_16x16x32_f16 v[106:109], v[218:221], v[222:225], v[14:17]
	v_mfma_f32_16x16x32_f16 v[14:17], v[206:209], v[226:229], v[46:49]
	v_mfma_f32_16x16x32_f16 v[94:97], v[210:213], v[242:245], v[14:17]
	v_mfma_f32_16x16x32_f16 v[14:17], v[214:217], v[226:229], v[54:57]
	v_mfma_f32_16x16x32_f16 v[90:93], v[218:221], v[242:245], v[14:17]
	v_mfma_f32_16x16x32_f16 v[14:17], v[206:209], v[246:249], v[130:133]
	v_mfma_f32_16x16x32_f16 v[74:77], v[210:213], v[250:253], v[14:17]
	v_mfma_f32_16x16x32_f16 v[14:17], v[214:217], v[246:249], v[62:65]
	v_mfma_f32_16x16x32_f16 v[66:69], v[218:221], v[250:253], v[14:17]
	s_barrier
	s_setprio 0
	ds_read_b128 v[38:41], v238 offset:49152
	ds_read_b128 v[42:45], v238 offset:50176
	ds_read_b128 v[130:133], v238 offset:51200
	ds_read_b128 v[222:225], v238 offset:52224
	ds_read_b128 v[226:229], v238 offset:53248
	ds_read_b128 v[242:245], v238 offset:54272
	ds_read_b128 v[246:249], v238 offset:55296
	ds_read_b128 v[250:253], v238 offset:56320
	s_add_u32 m0, s28, 0x18000
	s_nop 0
	global_load_lds_dwordx4 v233, s[26:27]
	s_nop 0
	s_add_u32 m0, s28, 0x1a000
	s_nop 0
	global_load_lds_dwordx4 v235, s[26:27]
	s_add_u32 s26, s6, 0x40180
	s_addc_u32 s27, s7, 0
	s_add_u32 m0, s28, 0x1c000
	s_nop 0
	global_load_lds_dwordx4 v233, s[26:27]
	s_nop 0
	s_add_u32 m0, s28, 0x1e000
	s_nop 0
	global_load_lds_dwordx4 v235, s[26:27]
	s_nop 0
	s_add_u32 m0, s28, 0x8000
	s_nop 0
	global_load_lds_dwordx4 v232, s[24:25]
	s_nop 0
	s_add_u32 m0, s28, 0xa000
	s_nop 0
	global_load_lds_dwordx4 v234, s[24:25]
	s_waitcnt vmcnt(8)
	s_waitcnt lgkmcnt(0)
	s_barrier
	v_mfma_f32_16x16x32_f16 v[14:17], v[6:9], v[38:41], v[134:137]
	s_setprio 1
	v_mfma_f32_16x16x32_f16 v[54:57], v[26:29], v[42:45], v[14:17]
	v_mfma_f32_16x16x32_f16 v[14:17], v[186:189], v[38:41], v[138:141]
	v_mfma_f32_16x16x32_f16 v[46:49], v[190:193], v[42:45], v[14:17]
	v_mfma_f32_16x16x32_f16 v[14:17], v[6:9], v[130:133], v[142:145]
	v_mfma_f32_16x16x32_f16 v[34:37], v[26:29], v[222:225], v[14:17]
	v_mfma_f32_16x16x32_f16 v[14:17], v[186:189], v[130:133], v[146:149]
	v_mfma_f32_16x16x32_f16 v[30:33], v[190:193], v[222:225], v[14:17]
	v_mfma_f32_16x16x32_f16 v[14:17], v[6:9], v[226:229], v[150:153]
	v_mfma_f32_16x16x32_f16 v[18:21], v[26:29], v[242:245], v[14:17]
	v_mfma_f32_16x16x32_f16 v[2:5], v[6:9], v[246:249], v[2:5]
	v_mfma_f32_16x16x32_f16 v[6:9], v[26:29], v[250:253], v[2:5]
	v_mfma_f32_16x16x32_f16 v[14:17], v[186:189], v[226:229], v[154:157]
	v_mfma_f32_16x16x32_f16 v[14:17], v[190:193], v[242:245], v[14:17]
	v_mfma_f32_16x16x32_f16 v[2:5], v[186:189], v[246:249], v[10:13]
	v_mfma_f32_16x16x32_f16 v[2:5], v[190:193], v[250:253], v[2:5]
	v_mfma_f32_16x16x32_f16 v[10:13], v[206:209], v[38:41], v[158:161]
	v_mfma_f32_16x16x32_f16 v[82:85], v[210:213], v[42:45], v[10:13]
	v_mfma_f32_16x16x32_f16 v[10:13], v[214:217], v[38:41], v[162:165]
	v_mfma_f32_16x16x32_f16 v[70:73], v[218:221], v[42:45], v[10:13]
	v_mfma_f32_16x16x32_f16 v[10:13], v[206:209], v[130:133], v[166:169]
	v_mfma_f32_16x16x32_f16 v[62:65], v[210:213], v[222:225], v[10:13]
	v_mfma_f32_16x16x32_f16 v[10:13], v[214:217], v[130:133], v[170:173]
	v_mfma_f32_16x16x32_f16 v[42:45], v[218:221], v[222:225], v[10:13]
	v_mfma_f32_16x16x32_f16 v[10:13], v[206:209], v[226:229], v[174:177]
	v_mfma_f32_16x16x32_f16 v[38:41], v[210:213], v[242:245], v[10:13]
	v_mfma_f32_16x16x32_f16 v[10:13], v[214:217], v[226:229], v[178:181]
	v_mfma_f32_16x16x32_f16 v[26:29], v[218:221], v[242:245], v[10:13]
	v_mfma_f32_16x16x32_f16 v[10:13], v[206:209], v[246:249], v[22:25]
	v_mfma_f32_16x16x32_f16 v[22:25], v[210:213], v[250:253], v[10:13]
	v_mfma_f32_16x16x32_f16 v[10:13], v[214:217], v[246:249], v[182:185]
	v_mfma_f32_16x16x32_f16 v[10:13], v[218:221], v[250:253], v[10:13]
	s_barrier
	s_setprio 0
	s_add_u32 s53, s6, 0x200
	s_addc_u32 s61, s7, 0
	s_mov_b32 s64, 0
	s_branch .LBB0_231

;     __device__ __forceinline__ bool next(int i, Unit& u) const { if (i >= count) return false; const int L = first + i; u.pm = L / nN; u.pn = L % nN; return true; }
; #define PG8_STAGE(bufoff, gbase, voff) do { if constexpr (ABL & 1) break; glds16s<(bufoff)>((voff)[0], (const void*)(gbase), ldsbw); glds16s<(bufoff) + 8192>((voff)[1], (const void*)(gbase), ldsbw); } while (0)
; #define PG8_LDA(dst, b, h) do { if constexpr (ABL & 4) break; _Pragma("unroll") for (int m = 0; m < 4; ++m) _Pragma("unroll") for (int k = 0; k < 2; ++k) dst[m][k] = *(const LAS f16x8*)(lds + PG8_SA(b, h) + aoff + m * 2048 + k * 1024); } while (0)
; #define PG8_LDB(dst, b, h) do { if constexpr (ABL & 4) break; _Pragma("unroll") for (int n = 0; n < 2; ++n) _Pragma("unroll") for (int k = 0; k < 2; ++k) dst[n][k] = *(const LAS f16x8*)(lds + PG8_SB(b, h) + boff + n * 2048 + k * 1024); } while (0)
; #define PG8_MMAF(ai, bj, At, Bt) do { if (t == 0) PG8_MMA0(ai, bj, At, Bt); else PG8_MMA(ai, bj, At, Bt); } while (0)
; #define PG8_WAIT_V(n) asm volatile("s_waitcnt vmcnt(" #n ")" ::: "memory")
; #define PG8_BAR __builtin_amdgcn_s_barrier()
;     ...
;         const bool has_next = S.next(ui + 1, nxt);
;         const char* nA = has_next ? (const char*)g.A + (size_t)nxt.pm * tstep : cA; const char* nB = has_next ? (const char*)g.Bt + (size_t)nxt.pn * tstep : cB;
;         for (int t = 0; t < nt; t += 2) {
;             const bool last = (t == nt - 2);
;             const char* a1 = cA + (size_t)(t + 1) * kstep;
;             const char* a2 = last ? nA : cA + (size_t)(t + 2) * kstep; const char* b2 = last ? nB : cB + (size_t)(t + 2) * kstep;
;             const char* a3 = a2 + kstep; const char* b3 = b2 + kstep;
;             if (last && has_next) S.a_ready(nxt);
;             if constexpr (SP2) {
;             PG8_LDB(B0, 0, 0); PG8_LDB(B1, 0, 1); PG8_SCHED; PG8_LDA(At, 0, 0); PG8_STAGE(PG8_SA(1, 1), a1 + hstep, voffA);
;             PG8_WAIT_V(8); PG8_WAIT_L(0); PG8_BAR; PG8_MMAF(0, 0, At, B0); PG8_MMAF(0, 1, At, B1); PG8_BAR; PG8_SCHED;
;             const bool fin = last && !has_next;
;             PG8_LDA(At, 0, 1); if (!fin) { PG8_STAGE(PG8_SB(0, 0), b2, voffB); PG8_STAGE(PG8_SB(0, 1), b2 + hstep, voffB); PG8_STAGE(PG8_SA(0, 0), a2, voffA); }
;             if (!fin) PG8_WAIT_V(8); else PG8_WAIT_V(2); PG8_WAIT_L(0); PG8_BAR; PG8_MMAF(1, 0, At, B0); PG8_MMAF(1, 1, At, B1); PG8_BAR; PG8_SCHED;
.LBB0_748:
	s_ashr_i32 s47, s46, 31
	s_lshl_b64 s[8:9], s[46:47], 19
	s_add_u32 s48, s12, s8
	s_addc_u32 s49, s13, s9
	s_and_b64 s[8:9], exec, s[4:5]
	s_waitcnt lgkmcnt(0)
	ds_read_b128 v[2:5], v222
	ds_read_b128 v[6:9], v222 offset:1024
	ds_read_b128 v[10:13], v222 offset:2048
	ds_read_b128 v[14:17], v222 offset:3072
	ds_read_b128 v[18:21], v223
	ds_read_b128 v[22:25], v223 offset:1024
	ds_read_b128 v[26:29], v223 offset:2048
	ds_read_b128 v[30:33], v223 offset:3072
	s_cselect_b32 s47, s31, s49
	s_cselect_b32 s55, s30, s48
	s_ashr_i32 s45, s44, 31
	s_lshl_b64 s[8:9], s[44:45], 19
	s_add_u32 s50, s90, s8
	s_addc_u32 s51, s91, s9
	s_and_b64 s[8:9], exec, s[4:5]
	s_cselect_b32 s45, s7, s51
	s_cselect_b32 s58, s6, s50
	s_add_u32 s56, s30, 0x100
	s_addc_u32 s57, s31, 0
	s_add_u32 s26, s6, 0x100
	s_addc_u32 s27, s7, 0
	s_add_u32 s8, s30, 0x180
	s_addc_u32 s9, s31, 0
	ds_read_b128 v[34:37], v224
	ds_read_b128 v[38:41], v224 offset:1024
	ds_read_b128 v[42:45], v224 offset:2048
	ds_read_b128 v[46:49], v224 offset:3072
	ds_read_b128 v[50:53], v224 offset:4096
	ds_read_b128 v[54:57], v224 offset:5120
	ds_read_b128 v[58:61], v224 offset:6144
	ds_read_b128 v[62:65], v224 offset:7168
	s_add_u32 s24, s6, 0x180
	s_addc_u32 s25, s7, 0
	s_add_u32 s60, s30, 0x40080
	s_addc_u32 s61, s31, 0
	s_add_u32 m0, s14, 0xc000
	s_nop 0
	global_load_lds_dwordx4 v1, s[60:61]
	s_nop 0
	s_add_u32 m0, s14, 0xe000
	s_nop 0
	global_load_lds_dwordx4 v213, s[60:61]
	s_waitcnt vmcnt(8)
	s_waitcnt lgkmcnt(0)
	s_barrier
	v_mfma_f32_16x16x32_f16 v[66:69], v[2:5], v[34:37], 0
	s_setprio 1
	v_mfma_f32_16x16x32_f16 v[66:69], v[6:9], v[38:41], v[66:69]
	v_mfma_f32_16x16x32_f16 v[70:73], v[10:13], v[34:37], 0
	v_mfma_f32_16x16x32_f16 v[70:73], v[14:17], v[38:41], v[70:73]
	v_mfma_f32_16x16x32_f16 v[78:81], v[10:13], v[42:45], 0
	v_mfma_f32_16x16x32_f16 v[78:81], v[14:17], v[46:49], v[78:81]
	v_mfma_f32_16x16x32_f16 v[82:85], v[2:5], v[50:53], 0
	v_mfma_f32_16x16x32_f16 v[82:85], v[6:9], v[54:57], v[82:85]
	v_mfma_f32_16x16x32_f16 v[90:93], v[2:5], v[58:61], 0
	v_mfma_f32_16x16x32_f16 v[90:93], v[6:9], v[62:65], v[90:93]
	v_mfma_f32_16x16x32_f16 v[94:97], v[10:13], v[58:61], 0
	v_mfma_f32_16x16x32_f16 v[94:97], v[14:17], v[62:65], v[94:97]
	v_mfma_f32_16x16x32_f16 v[74:77], v[2:5], v[42:45], 0
	v_mfma_f32_16x16x32_f16 v[74:77], v[6:9], v[46:49], v[74:77]
	v_mfma_f32_16x16x32_f16 v[86:89], v[10:13], v[50:53], 0
	v_mfma_f32_16x16x32_f16 v[86:89], v[14:17], v[54:57], v[86:89]
	v_mfma_f32_16x16x32_f16 v[98:101], v[18:21], v[34:37], 0
	v_mfma_f32_16x16x32_f16 v[98:101], v[22:25], v[38:41], v[98:101]
	v_mfma_f32_16x16x32_f16 v[34:37], v[26:29], v[34:37], 0
	v_mfma_f32_16x16x32_f16 v[34:37], v[30:33], v[38:41], v[34:37]
	v_mfma_f32_16x16x32_f16 v[38:41], v[18:21], v[42:45], 0
	v_mfma_f32_16x16x32_f16 v[38:41], v[22:25], v[46:49], v[38:41]
	v_mfma_f32_16x16x32_f16 v[42:45], v[26:29], v[42:45], 0
	v_mfma_f32_16x16x32_f16 v[42:45], v[30:33], v[46:49], v[42:45]
	v_mfma_f32_16x16x32_f16 v[46:49], v[18:21], v[50:53], 0
	v_mfma_f32_16x16x32_f16 v[46:49], v[22:25], v[54:57], v[46:49]
	v_mfma_f32_16x16x32_f16 v[50:53], v[26:29], v[50:53], 0
	v_mfma_f32_16x16x32_f16 v[50:53], v[30:33], v[54:57], v[50:53]
	v_mfma_f32_16x16x32_f16 v[54:57], v[18:21], v[58:61], 0
	v_mfma_f32_16x16x32_f16 v[54:57], v[22:25], v[62:65], v[54:57]
	v_mfma_f32_16x16x32_f16 v[58:61], v[26:29], v[58:61], 0
	v_mfma_f32_16x16x32_f16 v[58:61], v[30:33], v[62:65], v[58:61]
	s_barrier
	s_setprio 0
	ds_read_b128 v[62:65], v224 offset:16384
	ds_read_b128 v[102:105], v224 offset:17408
	ds_read_b128 v[106:109], v224 offset:18432
	ds_read_b128 v[110:113], v224 offset:19456
	ds_read_b128 v[114:117], v224 offset:20480
	ds_read_b128 v[118:121], v224 offset:21504
	ds_read_b128 v[122:125], v224 offset:22528
	ds_read_b128 v[126:129], v224 offset:23552
	s_add_u32 m0, s14, 0x10000
	s_nop 0
	global_load_lds_dwordx4 v209, s[26:27]
	s_nop 0
	s_add_u32 m0, s14, 0x12000
	s_nop 0
	global_load_lds_dwordx4 v219, s[26:27]
	s_add_u32 s26, s6, 0x40100
	s_addc_u32 s27, s7, 0
	s_add_u32 m0, s14, 0x14000
	s_nop 0
	global_load_lds_dwordx4 v209, s[26:27]
	s_nop 0
	s_add_u32 m0, s14, 0x16000
	s_nop 0
	global_load_lds_dwordx4 v219, s[26:27]
	s_nop 0
	s_add_u32 m0, s14, 0
	s_nop 0
	global_load_lds_dwordx4 v1, s[56:57]
	s_nop 0
	s_add_u32 m0, s14, 0x2000
	s_nop 0
	global_load_lds_dwordx4 v213, s[56:57]
	s_waitcnt vmcnt(8)
	s_waitcnt lgkmcnt(0)
	s_barrier
	v_mfma_f32_16x16x32_f16 v[130:133], v[2:5], v[62:65], 0
	s_setprio 1
	v_mfma_f32_16x16x32_f16 v[134:137], v[6:9], v[102:105], v[130:133]
	v_mfma_f32_16x16x32_f16 v[130:133], v[10:13], v[62:65], 0
	v_mfma_f32_16x16x32_f16 v[146:149], v[14:17], v[102:105], v[130:133]
	v_mfma_f32_16x16x32_f16 v[130:133], v[2:5], v[106:109], 0
	v_mfma_f32_16x16x32_f16 v[158:161], v[6:9], v[110:113], v[130:133]
	v_mfma_f32_16x16x32_f16 v[130:133], v[10:13], v[106:109], 0
	v_mfma_f32_16x16x32_f16 v[162:165], v[14:17], v[110:113], v[130:133]
	v_mfma_f32_16x16x32_f16 v[130:133], v[2:5], v[114:117], 0
	v_mfma_f32_16x16x32_f16 v[166:169], v[6:9], v[118:121], v[130:133]
	v_mfma_f32_16x16x32_f16 v[2:5], v[2:5], v[122:125], 0
	v_mfma_f32_16x16x32_f16 v[2:5], v[6:9], v[126:129], v[2:5]
	v_mfma_f32_16x16x32_f16 v[6:9], v[10:13], v[122:125], 0
	v_mfma_f32_16x16x32_f16 v[6:9], v[14:17], v[126:129], v[6:9]
	v_mfma_f32_16x16x32_f16 v[130:133], v[10:13], v[114:117], 0
	v_mfma_f32_16x16x32_f16 v[170:173], v[14:17], v[118:121], v[130:133]
	v_mfma_f32_16x16x32_f16 v[10:13], v[18:21], v[62:65], 0
	v_mfma_f32_16x16x32_f16 v[174:177], v[22:25], v[102:105], v[10:13]
	v_mfma_f32_16x16x32_f16 v[10:13], v[26:29], v[62:65], 0
	v_mfma_f32_16x16x32_f16 v[178:181], v[30:33], v[102:105], v[10:13]
	v_mfma_f32_16x16x32_f16 v[10:13], v[18:21], v[106:109], 0
	v_mfma_f32_16x16x32_f16 v[182:185], v[22:25], v[110:113], v[10:13]
	v_mfma_f32_16x16x32_f16 v[10:13], v[26:29], v[106:109], 0
	v_mfma_f32_16x16x32_f16 v[110:113], v[30:33], v[110:113], v[10:13]
	v_mfma_f32_16x16x32_f16 v[10:13], v[18:21], v[114:117], 0
	v_mfma_f32_16x16x32_f16 v[186:189], v[22:25], v[118:121], v[10:13]
	v_mfma_f32_16x16x32_f16 v[10:13], v[26:29], v[114:117], 0
	v_mfma_f32_16x16x32_f16 v[190:193], v[30:33], v[118:121], v[10:13]
	v_mfma_f32_16x16x32_f16 v[10:13], v[18:21], v[122:125], 0
	v_mfma_f32_16x16x32_f16 v[194:197], v[22:25], v[126:129], v[10:13]
	v_mfma_f32_16x16x32_f16 v[10:13], v[26:29], v[122:125], 0
	v_mfma_f32_16x16x32_f16 v[122:125], v[30:33], v[126:129], v[10:13]
	s_barrier
; #define PG8_STAGE(bufoff, gbase, voff) do { if constexpr (ABL & 1) break; glds16s<(bufoff)>((voff)[0], (const void*)(gbase), ldsbw); glds16s<(bufoff) + 8192>((voff)[1], (const void*)(gbase), ldsbw); } while (0)
; #define PG8_LDA(dst, b, h) do { if constexpr (ABL & 4) break; _Pragma("unroll") for (int m = 0; m < 4; ++m) _Pragma("unroll") for (int k = 0; k < 2; ++k) dst[m][k] = *(const LAS f16x8*)(lds + PG8_SA(b, h) + aoff + m * 2048 + k * 1024); } while (0)
; #define PG8_LDB(dst, b, h) do { if constexpr (ABL & 4) break; _Pragma("unroll") for (int n = 0; n < 2; ++n) _Pragma("unroll") for (int k = 0; k < 2; ++k) dst[n][k] = *(const LAS f16x8*)(lds + PG8_SB(b, h) + boff + n * 2048 + k * 1024); } while (0)
; #define PG8_MMA(ai, bj, At, Bt) do { if constexpr (ABL & 2) break; __builtin_amdgcn_s_setprio(1); _Pragma("unroll") for (int m = 0; m < 4; ++m) _Pragma("unroll") for (int n = 0; n < 2; ++n) _Pragma("unroll") for (int k = 0; k < 2; ++k) \
;         acc[ai][bj][m][n] = __builtin_amdgcn_mfma_f32_16x16x32_f16(Bt[n][k], At[m][k], acc[ai][bj][m][n], 0, 0, 0); __builtin_amdgcn_s_setprio(0); } while (0)
; #define PG8_WAIT_V(n) asm volatile("s_waitcnt vmcnt(" #n ")" ::: "memory")
; #define PG8_WAIT_L(n) asm volatile("s_waitcnt lgkmcnt(" #n ")" ::: "memory")
; #define PG8_BAR __builtin_amdgcn_s_barrier()
; #define PG8_SCHED __builtin_amdgcn_sched_barrier(0)
;     ...
;             PG8_LDB(B0, 1, 0); PG8_LDB(B1, 1, 1); PG8_SCHED; PG8_LDA(At, 1, 0); if (!fin) PG8_STAGE(PG8_SA(0, 1), a2 + hstep, voffA);
;             if (!fin) PG8_WAIT_V(8); else PG8_WAIT_V(0); PG8_WAIT_L(0); PG8_BAR; PG8_MMA(0, 0, At, B0); PG8_MMA(0, 1, At, B1); PG8_BAR; PG8_SCHED;
;             PG8_LDA(At, 1, 1); if (!fin) { PG8_STAGE(PG8_SB(1, 0), b3, voffB); PG8_STAGE(PG8_SB(1, 1), b3 + hstep, voffB); PG8_STAGE(PG8_SA(1, 0), a3, voffA); }
;             if (!fin) PG8_WAIT_V(8); PG8_WAIT_L(0); PG8_BAR; PG8_MMA(1, 0, At, B0); PG8_MMA(1, 1, At, B1); PG8_BAR; PG8_SCHED;
	s_setprio 0
	s_nop 4
	ds_read_b128 v[10:13], v225
	ds_read_b128 v[14:17], v225 offset:1024
	ds_read_b128 v[18:21], v225 offset:2048
	ds_read_b128 v[22:25], v225 offset:3072
	ds_read_b128 v[198:201], v226
	ds_read_b128 v[214:217], v226 offset:1024
	ds_read_b128 v[228:231], v226 offset:2048
	ds_read_b128 v[232:235], v226 offset:3072
	ds_read_b128 v[26:29], v224 offset:32768
	ds_read_b128 v[30:33], v224 offset:33792
	ds_read_b128 v[62:65], v224 offset:34816
	ds_read_b128 v[114:117], v224 offset:35840
	ds_read_b128 v[236:239], v224 offset:36864
	ds_read_b128 v[240:243], v224 offset:37888
	ds_read_b128 v[244:247], v224 offset:38912
	ds_read_b128 v[248:251], v224 offset:39936
	s_add_u32 s26, s30, 0x40100
	s_addc_u32 s27, s31, 0
	s_add_u32 m0, s14, 0x4000
	s_nop 0
	global_load_lds_dwordx4 v1, s[26:27]
	s_nop 0
	s_add_u32 m0, s14, 0x6000
	s_nop 0
	global_load_lds_dwordx4 v213, s[26:27]
	s_waitcnt vmcnt(8)
	s_waitcnt lgkmcnt(0)
	s_barrier
	v_mfma_f32_16x16x32_f16 v[66:69], v[10:13], v[26:29], v[66:69]
	s_setprio 1
	v_mfma_f32_16x16x32_f16 v[154:157], v[14:17], v[30:33], v[66:69]
	v_mfma_f32_16x16x32_f16 v[66:69], v[18:21], v[26:29], v[70:73]
	v_mfma_f32_16x16x32_f16 v[150:153], v[22:25], v[30:33], v[66:69]
	v_mfma_f32_16x16x32_f16 v[66:69], v[10:13], v[62:65], v[74:77]
	v_mfma_f32_16x16x32_f16 v[130:133], v[14:17], v[114:117], v[66:69]
	v_mfma_f32_16x16x32_f16 v[66:69], v[18:21], v[62:65], v[78:81]
	v_mfma_f32_16x16x32_f16 v[126:129], v[22:25], v[114:117], v[66:69]
	v_mfma_f32_16x16x32_f16 v[66:69], v[10:13], v[236:239], v[82:85]
	v_mfma_f32_16x16x32_f16 v[106:109], v[14:17], v[240:243], v[66:69]
	v_mfma_f32_16x16x32_f16 v[66:69], v[18:21], v[236:239], v[86:89]
	v_mfma_f32_16x16x32_f16 v[102:105], v[22:25], v[240:243], v[66:69]
	v_mfma_f32_16x16x32_f16 v[66:69], v[10:13], v[244:247], v[90:93]
	v_mfma_f32_16x16x32_f16 v[82:85], v[14:17], v[248:251], v[66:69]
	v_mfma_f32_16x16x32_f16 v[66:69], v[18:21], v[244:247], v[94:97]
	v_mfma_f32_16x16x32_f16 v[78:81], v[22:25], v[248:251], v[66:69]
	v_mfma_f32_16x16x32_f16 v[66:69], v[198:201], v[26:29], v[98:101]
	v_mfma_f32_16x16x32_f16 v[142:145], v[214:217], v[30:33], v[66:69]
	v_mfma_f32_16x16x32_f16 v[26:29], v[228:231], v[26:29], v[34:37]
	v_mfma_f32_16x16x32_f16 v[138:141], v[232:235], v[30:33], v[26:29]
	v_mfma_f32_16x16x32_f16 v[26:29], v[198:201], v[62:65], v[38:41]
	v_mfma_f32_16x16x32_f16 v[118:121], v[214:217], v[114:117], v[26:29]
	v_mfma_f32_16x16x32_f16 v[26:29], v[228:231], v[62:65], v[42:45]
	v_mfma_f32_16x16x32_f16 v[114:117], v[232:235], v[114:117], v[26:29]
	v_mfma_f32_16x16x32_f16 v[26:29], v[198:201], v[236:239], v[46:49]
	v_mfma_f32_16x16x32_f16 v[94:97], v[214:217], v[240:243], v[26:29]
	v_mfma_f32_16x16x32_f16 v[26:29], v[228:231], v[236:239], v[50:53]
	v_mfma_f32_16x16x32_f16 v[90:93], v[232:235], v[240:243], v[26:29]
	v_mfma_f32_16x16x32_f16 v[26:29], v[198:201], v[244:247], v[54:57]
	v_mfma_f32_16x16x32_f16 v[70:73], v[214:217], v[248:251], v[26:29]
	v_mfma_f32_16x16x32_f16 v[26:29], v[228:231], v[244:247], v[58:61]
	v_mfma_f32_16x16x32_f16 v[66:69], v[232:235], v[248:251], v[26:29]
	s_barrier
	s_setprio 0
	ds_read_b128 v[34:37], v224 offset:49152
	ds_read_b128 v[38:41], v224 offset:50176
	ds_read_b128 v[74:77], v224 offset:51200
	ds_read_b128 v[86:89], v224 offset:52224
	ds_read_b128 v[98:101], v224 offset:53248
	ds_read_b128 v[236:239], v224 offset:54272
	ds_read_b128 v[240:243], v224 offset:55296
	ds_read_b128 v[244:247], v224 offset:56320
	s_add_u32 m0, s14, 0x18000
	s_nop 0
	global_load_lds_dwordx4 v209, s[24:25]
	s_nop 0
	s_add_u32 m0, s14, 0x1a000
	s_nop 0
	global_load_lds_dwordx4 v219, s[24:25]
	s_add_u32 s24, s6, 0x40180
	s_addc_u32 s25, s7, 0
	s_add_u32 m0, s14, 0x1c000
	s_nop 0
	global_load_lds_dwordx4 v209, s[24:25]
	s_nop 0
	s_add_u32 m0, s14, 0x1e000
	s_nop 0
	global_load_lds_dwordx4 v219, s[24:25]
	s_nop 0
	s_add_u32 m0, s14, 0x8000
	s_nop 0
	global_load_lds_dwordx4 v1, s[8:9]
	s_nop 0
	s_add_u32 m0, s14, 0xa000
	s_nop 0
	global_load_lds_dwordx4 v213, s[8:9]
	s_waitcnt vmcnt(8)
	s_waitcnt lgkmcnt(0)
	s_barrier
	v_mfma_f32_16x16x32_f16 v[26:29], v[10:13], v[34:37], v[134:137]
	s_setprio 1
	v_mfma_f32_16x16x32_f16 v[62:65], v[14:17], v[38:41], v[26:29]
	v_mfma_f32_16x16x32_f16 v[26:29], v[18:21], v[34:37], v[146:149]
	v_mfma_f32_16x16x32_f16 v[58:61], v[22:25], v[38:41], v[26:29]
	v_mfma_f32_16x16x32_f16 v[26:29], v[10:13], v[74:77], v[158:161]
	v_mfma_f32_16x16x32_f16 v[46:49], v[14:17], v[86:89], v[26:29]
	v_mfma_f32_16x16x32_f16 v[26:29], v[18:21], v[74:77], v[162:165]
	v_mfma_f32_16x16x32_f16 v[42:45], v[22:25], v[86:89], v[26:29]
	v_mfma_f32_16x16x32_f16 v[26:29], v[10:13], v[98:101], v[166:169]
	v_mfma_f32_16x16x32_f16 v[30:33], v[14:17], v[236:239], v[26:29]
	v_mfma_f32_16x16x32_f16 v[2:5], v[10:13], v[240:243], v[2:5]
	v_mfma_f32_16x16x32_f16 v[14:17], v[14:17], v[244:247], v[2:5]
	v_mfma_f32_16x16x32_f16 v[26:29], v[18:21], v[98:101], v[170:173]
	v_mfma_f32_16x16x32_f16 v[26:29], v[22:25], v[236:239], v[26:29]
	v_mfma_f32_16x16x32_f16 v[2:5], v[18:21], v[240:243], v[6:9]
	v_mfma_f32_16x16x32_f16 v[10:13], v[22:25], v[244:247], v[2:5]
	v_mfma_f32_16x16x32_f16 v[2:5], v[198:201], v[34:37], v[174:177]
	v_mfma_f32_16x16x32_f16 v[54:57], v[214:217], v[38:41], v[2:5]
	v_mfma_f32_16x16x32_f16 v[2:5], v[228:231], v[34:37], v[178:181]
	v_mfma_f32_16x16x32_f16 v[50:53], v[232:235], v[38:41], v[2:5]
	v_mfma_f32_16x16x32_f16 v[2:5], v[198:201], v[74:77], v[182:185]
	v_mfma_f32_16x16x32_f16 v[38:41], v[214:217], v[86:89], v[2:5]
	v_mfma_f32_16x16x32_f16 v[2:5], v[228:231], v[74:77], v[110:113]
	v_mfma_f32_16x16x32_f16 v[34:37], v[232:235], v[86:89], v[2:5]
	v_mfma_f32_16x16x32_f16 v[2:5], v[198:201], v[98:101], v[186:189]
	v_mfma_f32_16x16x32_f16 v[22:25], v[214:217], v[236:239], v[2:5]
	v_mfma_f32_16x16x32_f16 v[2:5], v[228:231], v[98:101], v[190:193]
	v_mfma_f32_16x16x32_f16 v[18:21], v[232:235], v[236:239], v[2:5]
	v_mfma_f32_16x16x32_f16 v[2:5], v[198:201], v[240:243], v[194:197]
	v_mfma_f32_16x16x32_f16 v[6:9], v[214:217], v[244:247], v[2:5]
	v_mfma_f32_16x16x32_f16 v[2:5], v[228:231], v[240:243], v[122:125]
	v_mfma_f32_16x16x32_f16 v[2:5], v[232:235], v[244:247], v[2:5]
	s_barrier
	s_setprio 0
	s_add_u32 s30, s6, 0x200
	s_addc_u32 s31, s7, 0
	s_mov_b32 s59, 0
	s_branch .LBB0_750

; #define PG8_STAGE(bufoff, gbase, voff) do { if constexpr (ABL & 1) break; glds16s<(bufoff)>((voff)[0], (const void*)(gbase), ldsbw); glds16s<(bufoff) + 8192>((voff)[1], (const void*)(gbase), ldsbw); } while (0)
; #define PG8_LDA(dst, b, h) do { if constexpr (ABL & 4) break; _Pragma("unroll") for (int m = 0; m < 4; ++m) _Pragma("unroll") for (int k = 0; k < 2; ++k) dst[m][k] = *(const LAS f16x8*)(lds + PG8_SA(b, h) + aoff + m * 2048 + k * 1024); } while (0)
; #define PG8_LDB(dst, b, h) do { if constexpr (ABL & 4) break; _Pragma("unroll") for (int n = 0; n < 2; ++n) _Pragma("unroll") for (int k = 0; k < 2; ++k) dst[n][k] = *(const LAS f16x8*)(lds + PG8_SB(b, h) + boff + n * 2048 + k * 1024); } while (0)
; #define PG8_MMAF(ai, bj, At, Bt) do { if (t == 0) PG8_MMA0(ai, bj, At, Bt); else PG8_MMA(ai, bj, At, Bt); } while (0)
; #define PG8_WAIT_V(n) asm volatile("s_waitcnt vmcnt(" #n ")" ::: "memory")
; #define PG8_WAIT_L(n) asm volatile("s_waitcnt lgkmcnt(" #n ")" ::: "memory")
; #define PG8_BAR __builtin_amdgcn_s_barrier()
; #define PG8_SCHED __builtin_amdgcn_sched_barrier(0)
;     ...
;         for (int t = 0; t < nt; t += 2) {
;             const bool last = (t == nt - 2);
;             const char* a1 = cA + (size_t)(t + 1) * kstep;
;             const char* a2 = last ? nA : cA + (size_t)(t + 2) * kstep; const char* b2 = last ? nB : cB + (size_t)(t + 2) * kstep;
;             const char* a3 = a2 + kstep; const char* b3 = b2 + kstep;
;             if (last && has_next) S.a_ready(nxt);
;             if constexpr (SP2) {
;             PG8_LDB(B0, 0, 0); PG8_LDB(B1, 0, 1); PG8_SCHED; PG8_LDA(At, 0, 0); PG8_STAGE(PG8_SA(1, 1), a1 + hstep, voffA);
;             PG8_WAIT_V(8); PG8_WAIT_L(0); PG8_BAR; PG8_MMAF(0, 0, At, B0); PG8_MMAF(0, 1, At, B1); PG8_BAR; PG8_SCHED;
;             const bool fin = last && !has_next;
;             PG8_LDA(At, 0, 1); if (!fin) { PG8_STAGE(PG8_SB(0, 0), b2, voffB); PG8_STAGE(PG8_SB(0, 1), b2 + hstep, voffB); PG8_STAGE(PG8_SA(0, 0), a2, voffA); }
.LBB0_750:
	ds_read_b128 v[146:149], v222
	ds_read_b128 v[158:161], v222 offset:1024
	ds_read_b128 v[162:165], v222 offset:2048
	ds_read_b128 v[166:169], v222 offset:3072
	ds_read_b128 v[74:77], v223
	ds_read_b128 v[86:89], v223 offset:1024
	ds_read_b128 v[98:101], v223 offset:2048
	ds_read_b128 v[110:113], v223 offset:3072
	s_mov_b64 s[6:7], s[56:57]
	s_add_u32 s56, s6, 0x100
	s_addc_u32 s57, s7, 0
	s_cmp_eq_u32 s59, 12
	s_cselect_b64 s[26:27], -1, 0
	s_and_b64 s[8:9], s[26:27], exec
	s_cselect_b32 s25, s47, s57
	s_cselect_b32 s24, s55, s56
	s_cselect_b32 s9, s45, s31
	s_cselect_b32 s8, s58, s30
	ds_read_b128 v[170:173], v224
	ds_read_b128 v[174:177], v224 offset:1024
	ds_read_b128 v[178:181], v224 offset:2048
	ds_read_b128 v[182:185], v224 offset:3072
	ds_read_b128 v[186:189], v224 offset:4096
	ds_read_b128 v[190:193], v224 offset:5120
	ds_read_b128 v[194:197], v224 offset:6144
	ds_read_b128 v[198:201], v224 offset:7168
	s_add_u32 s6, s6, 0x40080
	s_addc_u32 s7, s7, 0
	s_add_u32 m0, s14, 0xc000
	s_nop 0
	global_load_lds_dwordx4 v1, s[6:7]
	s_nop 0
	s_add_u32 m0, s14, 0xe000
	s_nop 0
	global_load_lds_dwordx4 v213, s[6:7]
	s_waitcnt vmcnt(8)
	s_waitcnt lgkmcnt(0)
	s_barrier
	v_mfma_f32_16x16x32_f16 v[122:125], v[146:149], v[170:173], v[154:157]
	s_setprio 1
	v_mfma_f32_16x16x32_f16 v[122:125], v[158:161], v[174:177], v[122:125]
	v_mfma_f32_16x16x32_f16 v[134:137], v[162:165], v[170:173], v[150:153]
	v_mfma_f32_16x16x32_f16 v[134:137], v[166:169], v[174:177], v[134:137]
	v_mfma_f32_16x16x32_f16 v[130:133], v[146:149], v[178:181], v[130:133]
	v_mfma_f32_16x16x32_f16 v[130:133], v[158:161], v[182:185], v[130:133]
	v_mfma_f32_16x16x32_f16 v[126:129], v[162:165], v[178:181], v[126:129]
	v_mfma_f32_16x16x32_f16 v[126:129], v[166:169], v[182:185], v[126:129]
	v_mfma_f32_16x16x32_f16 v[106:109], v[146:149], v[186:189], v[106:109]
	v_mfma_f32_16x16x32_f16 v[106:109], v[158:161], v[190:193], v[106:109]
	v_mfma_f32_16x16x32_f16 v[102:105], v[162:165], v[186:189], v[102:105]
	v_mfma_f32_16x16x32_f16 v[102:105], v[166:169], v[190:193], v[102:105]
	v_mfma_f32_16x16x32_f16 v[82:85], v[146:149], v[194:197], v[82:85]
	v_mfma_f32_16x16x32_f16 v[82:85], v[158:161], v[198:201], v[82:85]
	v_mfma_f32_16x16x32_f16 v[78:81], v[162:165], v[194:197], v[78:81]
	v_mfma_f32_16x16x32_f16 v[78:81], v[166:169], v[198:201], v[78:81]
	v_mfma_f32_16x16x32_f16 v[142:145], v[74:77], v[170:173], v[142:145]
	v_mfma_f32_16x16x32_f16 v[142:145], v[86:89], v[174:177], v[142:145]
	v_mfma_f32_16x16x32_f16 v[138:141], v[98:101], v[170:173], v[138:141]
	v_mfma_f32_16x16x32_f16 v[138:141], v[110:113], v[174:177], v[138:141]
	v_mfma_f32_16x16x32_f16 v[118:121], v[74:77], v[178:181], v[118:121]
	v_mfma_f32_16x16x32_f16 v[118:121], v[86:89], v[182:185], v[118:121]
	v_mfma_f32_16x16x32_f16 v[114:117], v[98:101], v[178:181], v[114:117]
	v_mfma_f32_16x16x32_f16 v[114:117], v[110:113], v[182:185], v[114:117]
	v_mfma_f32_16x16x32_f16 v[94:97], v[74:77], v[186:189], v[94:97]
	v_mfma_f32_16x16x32_f16 v[94:97], v[86:89], v[190:193], v[94:97]
	v_mfma_f32_16x16x32_f16 v[90:93], v[98:101], v[186:189], v[90:93]
	v_mfma_f32_16x16x32_f16 v[90:93], v[110:113], v[190:193], v[90:93]
	v_mfma_f32_16x16x32_f16 v[70:73], v[74:77], v[194:197], v[70:73]
	v_mfma_f32_16x16x32_f16 v[70:73], v[86:89], v[198:201], v[70:73]
	v_mfma_f32_16x16x32_f16 v[66:69], v[98:101], v[194:197], v[66:69]
	v_mfma_f32_16x16x32_f16 v[66:69], v[110:113], v[198:201], v[66:69]
	s_barrier
	s_setprio 0
	ds_read_b128 v[186:189], v224 offset:16384
	ds_read_b128 v[190:193], v224 offset:17408
	ds_read_b128 v[178:181], v224 offset:18432
	ds_read_b128 v[182:185], v224 offset:19456
	ds_read_b128 v[170:173], v224 offset:20480
	ds_read_b128 v[174:177], v224 offset:21504
	ds_read_b128 v[150:153], v224 offset:22528
	ds_read_b128 v[154:157], v224 offset:23552
	s_and_b64 s[6:7], s[4:5], s[26:27]
	s_mov_b64 s[26:27], -1
	s_and_b64 vcc, exec, s[6:7]
	s_cbranch_vccnz .LBB0_752
	s_add_u32 m0, s14, 0x10000
	s_nop 0
	global_load_lds_dwordx4 v209, s[8:9]
	s_nop 0
	s_add_u32 m0, s14, 0x12000
	s_nop 0
	global_load_lds_dwordx4 v219, s[8:9]
	s_add_u32 s26, s8, 0x40000
	s_addc_u32 s27, s9, 0
	s_add_u32 m0, s14, 0x14000
	s_nop 0
	global_load_lds_dwordx4 v209, s[26:27]
	s_nop 0
	s_add_u32 m0, s14, 0x16000
	s_nop 0
	global_load_lds_dwordx4 v219, s[26:27]
	s_mov_b64 s[26:27], 0
	s_add_u32 m0, s14, 0
	s_nop 0
	global_load_lds_dwordx4 v1, s[24:25]
	s_nop 0
	s_add_u32 m0, s14, 0x2000
	s_nop 0
	global_load_lds_dwordx4 v213, s[24:25]
	s_waitcnt vmcnt(8)

; #define PG8_STAGE(bufoff, gbase, voff) do { if constexpr (ABL & 1) break; glds16s<(bufoff)>((voff)[0], (const void*)(gbase), ldsbw); glds16s<(bufoff) + 8192>((voff)[1], (const void*)(gbase), ldsbw); } while (0)
; #define PG8_LDA(dst, b, h) do { if constexpr (ABL & 4) break; _Pragma("unroll") for (int m = 0; m < 4; ++m) _Pragma("unroll") for (int k = 0; k < 2; ++k) dst[m][k] = *(const LAS f16x8*)(lds + PG8_SA(b, h) + aoff + m * 2048 + k * 1024); } while (0)
; #define PG8_MMA(ai, bj, At, Bt) do { if constexpr (ABL & 2) break; __builtin_amdgcn_s_setprio(1); _Pragma("unroll") for (int m = 0; m < 4; ++m) _Pragma("unroll") for (int n = 0; n < 2; ++n) _Pragma("unroll") for (int k = 0; k < 2; ++k) \
;         acc[ai][bj][m][n] = __builtin_amdgcn_mfma_f32_16x16x32_f16(Bt[n][k], At[m][k], acc[ai][bj][m][n], 0, 0, 0); __builtin_amdgcn_s_setprio(0); } while (0)
; #define PG8_WAIT_V(n) asm volatile("s_waitcnt vmcnt(" #n ")" ::: "memory")
; #define PG8_WAIT_L(n) asm volatile("s_waitcnt lgkmcnt(" #n ")" ::: "memory")
; #define PG8_BAR __builtin_amdgcn_s_barrier()
; #define PG8_SCHED __builtin_amdgcn_sched_barrier(0)
;     ...
;             if (!fin) PG8_WAIT_V(8); else PG8_WAIT_V(0); PG8_WAIT_L(0); PG8_BAR; PG8_MMA(0, 0, At, B0); PG8_MMA(0, 1, At, B1); PG8_BAR; PG8_SCHED;
;             PG8_LDA(At, 1, 1); if (!fin) { PG8_STAGE(PG8_SB(1, 0), b3, voffB); PG8_STAGE(PG8_SB(1, 1), b3 + hstep, voffB); PG8_STAGE(PG8_SA(1, 0), a3, voffA); }
;             if (!fin) PG8_WAIT_V(8); PG8_WAIT_L(0); PG8_BAR; PG8_MMA(1, 0, At, B0); PG8_MMA(1, 1, At, B1); PG8_BAR; PG8_SCHED;
.LBB0_758:
	s_waitcnt lgkmcnt(0)
	s_barrier
	v_mfma_f32_16x16x32_f16 v[122:125], v[162:165], v[194:197], v[122:125]
	s_setprio 1
	v_mfma_f32_16x16x32_f16 v[154:157], v[166:169], v[198:201], v[122:125]
	v_mfma_f32_16x16x32_f16 v[122:125], v[146:149], v[194:197], v[134:137]
	v_mfma_f32_16x16x32_f16 v[150:153], v[158:161], v[198:201], v[122:125]
	v_mfma_f32_16x16x32_f16 v[122:125], v[162:165], v[186:189], v[130:133]
	v_mfma_f32_16x16x32_f16 v[130:133], v[166:169], v[190:193], v[122:125]
	v_mfma_f32_16x16x32_f16 v[122:125], v[146:149], v[186:189], v[126:129]
	v_mfma_f32_16x16x32_f16 v[126:129], v[158:161], v[190:193], v[122:125]
	v_mfma_f32_16x16x32_f16 v[106:109], v[162:165], v[178:181], v[106:109]
	v_mfma_f32_16x16x32_f16 v[106:109], v[166:169], v[182:185], v[106:109]
	v_mfma_f32_16x16x32_f16 v[102:105], v[146:149], v[178:181], v[102:105]
	v_mfma_f32_16x16x32_f16 v[102:105], v[158:161], v[182:185], v[102:105]
	v_mfma_f32_16x16x32_f16 v[82:85], v[162:165], v[170:173], v[82:85]
	v_mfma_f32_16x16x32_f16 v[82:85], v[166:169], v[174:177], v[82:85]
	v_mfma_f32_16x16x32_f16 v[78:81], v[146:149], v[170:173], v[78:81]
	v_mfma_f32_16x16x32_f16 v[78:81], v[158:161], v[174:177], v[78:81]
	v_mfma_f32_16x16x32_f16 v[122:125], v[98:101], v[194:197], v[142:145]
	v_mfma_f32_16x16x32_f16 v[142:145], v[110:113], v[198:201], v[122:125]
	v_mfma_f32_16x16x32_f16 v[122:125], v[74:77], v[194:197], v[138:141]
	v_mfma_f32_16x16x32_f16 v[138:141], v[86:89], v[198:201], v[122:125]
	v_mfma_f32_16x16x32_f16 v[118:121], v[98:101], v[186:189], v[118:121]
	v_mfma_f32_16x16x32_f16 v[118:121], v[110:113], v[190:193], v[118:121]
	v_mfma_f32_16x16x32_f16 v[114:117], v[74:77], v[186:189], v[114:117]
	v_mfma_f32_16x16x32_f16 v[114:117], v[86:89], v[190:193], v[114:117]
	v_mfma_f32_16x16x32_f16 v[94:97], v[98:101], v[178:181], v[94:97]
	v_mfma_f32_16x16x32_f16 v[94:97], v[110:113], v[182:185], v[94:97]
	v_mfma_f32_16x16x32_f16 v[90:93], v[74:77], v[178:181], v[90:93]
	v_mfma_f32_16x16x32_f16 v[90:93], v[86:89], v[182:185], v[90:93]
	v_mfma_f32_16x16x32_f16 v[70:73], v[98:101], v[170:173], v[70:73]
	v_mfma_f32_16x16x32_f16 v[70:73], v[110:113], v[174:177], v[70:73]
	v_mfma_f32_16x16x32_f16 v[66:69], v[74:77], v[170:173], v[66:69]
	v_mfma_f32_16x16x32_f16 v[66:69], v[86:89], v[174:177], v[66:69]
	s_barrier
	s_setprio 0
	ds_read_b128 v[186:189], v224 offset:49152
	ds_read_b128 v[190:193], v224 offset:50176
	ds_read_b128 v[178:181], v224 offset:51200
	ds_read_b128 v[182:185], v224 offset:52224
	ds_read_b128 v[170:173], v224 offset:53248
	ds_read_b128 v[174:177], v224 offset:54272
	ds_read_b128 v[122:125], v224 offset:55296
	ds_read_b128 v[134:137], v224 offset:56320
	s_and_b64 vcc, exec, s[6:7]
	s_cbranch_vccnz .LBB0_749
	s_add_u32 s6, s24, 0x80
	s_addc_u32 s7, s25, 0
	s_add_u32 s24, s8, 0x80
	s_addc_u32 s25, s9, 0
	s_add_u32 m0, s14, 0x18000
	s_nop 0
	global_load_lds_dwordx4 v209, s[24:25]
	s_nop 0
	s_add_u32 m0, s14, 0x1a000
	s_nop 0
	global_load_lds_dwordx4 v219, s[24:25]
	s_add_u32 s8, s8, 0x40080
	s_addc_u32 s9, s9, 0
	s_add_u32 m0, s14, 0x1c000
	s_nop 0
	global_load_lds_dwordx4 v209, s[8:9]
	s_nop 0
	s_add_u32 m0, s14, 0x1e000
	s_nop 0
	global_load_lds_dwordx4 v219, s[8:9]
	s_nop 0
	s_add_u32 m0, s14, 0x8000
	s_nop 0
	global_load_lds_dwordx4 v1, s[6:7]
	s_nop 0
	s_add_u32 m0, s14, 0xa000
	s_nop 0
	global_load_lds_dwordx4 v213, s[6:7]
	s_waitcnt vmcnt(8)
	s_branch .LBB0_749

;     __device__ __forceinline__ bool next(int i, Unit& u) const { if (i >= count) return false; const int L = first + i; u.pm = L / nN; u.pn = L % nN; return true; }
; #define PG8_STAGE(bufoff, gbase, voff) do { if constexpr (ABL & 1) break; glds16s<(bufoff)>((voff)[0], (const void*)(gbase), ldsbw); glds16s<(bufoff) + 8192>((voff)[1], (const void*)(gbase), ldsbw); } while (0)
; #define PG8_LDA(dst, b, h) do { if constexpr (ABL & 4) break; _Pragma("unroll") for (int m = 0; m < 4; ++m) _Pragma("unroll") for (int k = 0; k < 2; ++k) dst[m][k] = *(const LAS f16x8*)(lds + PG8_SA(b, h) + aoff + m * 2048 + k * 1024); } while (0)
; #define PG8_LDB(dst, b, h) do { if constexpr (ABL & 4) break; _Pragma("unroll") for (int n = 0; n < 2; ++n) _Pragma("unroll") for (int k = 0; k < 2; ++k) dst[n][k] = *(const LAS f16x8*)(lds + PG8_SB(b, h) + boff + n * 2048 + k * 1024); } while (0)
; #define PG8_MMAF(ai, bj, At, Bt) do { if (t == 0) PG8_MMA0(ai, bj, At, Bt); else PG8_MMA(ai, bj, At, Bt); } while (0)
; #define PG8_WAIT_V(n) asm volatile("s_waitcnt vmcnt(" #n ")" ::: "memory")
; #define PG8_BAR __builtin_amdgcn_s_barrier()
;     ...
;         const bool has_next = S.next(ui + 1, nxt);
;         const char* nA = has_next ? (const char*)g.A + (size_t)nxt.pm * tstep : cA; const char* nB = has_next ? (const char*)g.Bt + (size_t)nxt.pn * tstep : cB;
;         for (int t = 0; t < nt; t += 2) {
;             const bool last = (t == nt - 2);
;             const char* a1 = cA + (size_t)(t + 1) * kstep;
;             const char* a2 = last ? nA : cA + (size_t)(t + 2) * kstep; const char* b2 = last ? nB : cB + (size_t)(t + 2) * kstep;
;             const char* a3 = a2 + kstep; const char* b3 = b2 + kstep;
;             if (last && has_next) S.a_ready(nxt);
;             if constexpr (SP2) {
;             PG8_LDB(B0, 0, 0); PG8_LDB(B1, 0, 1); PG8_SCHED; PG8_LDA(At, 0, 0); PG8_STAGE(PG8_SA(1, 1), a1 + hstep, voffA);
;             PG8_WAIT_V(8); PG8_WAIT_L(0); PG8_BAR; PG8_MMAF(0, 0, At, B0); PG8_MMAF(0, 1, At, B1); PG8_BAR; PG8_SCHED;
;             const bool fin = last && !has_next;
;             PG8_LDA(At, 0, 1); if (!fin) { PG8_STAGE(PG8_SB(0, 0), b2, voffB); PG8_STAGE(PG8_SB(0, 1), b2 + hstep, voffB); PG8_STAGE(PG8_SA(0, 0), a2, voffA); }
;             if (!fin) PG8_WAIT_V(8); else PG8_WAIT_V(2); PG8_WAIT_L(0); PG8_BAR; PG8_MMAF(1, 0, At, B0); PG8_MMAF(1, 1, At, B1); PG8_BAR; PG8_SCHED;
.LBB0_841:
	s_ashr_i32 s41, s40, 31
	s_lshl_b64 s[24:25], s[40:41], 19
	s_add_u32 s42, s74, s24
	s_addc_u32 s43, s75, s25
	s_and_b64 s[24:25], exec, s[4:5]
	ds_read_b128 v[2:5], v210
	ds_read_b128 v[6:9], v210 offset:1024
	ds_read_b128 v[10:13], v210 offset:2048
	ds_read_b128 v[14:17], v210 offset:3072
	ds_read_b128 v[18:21], v211
	ds_read_b128 v[22:25], v211 offset:1024
	ds_read_b128 v[26:29], v211 offset:2048
	ds_read_b128 v[30:33], v211 offset:3072
	s_cselect_b32 s41, s9, s43
	s_cselect_b32 s51, s8, s42
	s_ashr_i32 s39, s38, 31
	s_lshl_b64 s[24:25], s[38:39], 19
	s_add_u32 s44, s58, s24
	s_addc_u32 s45, s59, s25
	s_and_b64 s[24:25], exec, s[4:5]
	s_cselect_b32 s39, s7, s45
	s_cselect_b32 s52, s6, s44
	s_add_u32 s48, s8, 0x100
	s_addc_u32 s49, s9, 0
	s_add_u32 s54, s6, 0x100
	s_addc_u32 s55, s7, 0
	s_add_u32 s24, s8, 0x180
	s_addc_u32 s25, s9, 0
	ds_read_b128 v[34:37], v212
	ds_read_b128 v[38:41], v212 offset:1024
	ds_read_b128 v[42:45], v212 offset:2048
	ds_read_b128 v[46:49], v212 offset:3072
	ds_read_b128 v[50:53], v212 offset:4096
	ds_read_b128 v[54:57], v212 offset:5120
	ds_read_b128 v[58:61], v212 offset:6144
	ds_read_b128 v[62:65], v212 offset:7168
	s_add_u32 s26, s6, 0x180
	s_addc_u32 s27, s7, 0
	s_add_u32 s56, s8, 0x40080
	s_addc_u32 s57, s9, 0
	s_add_u32 m0, s14, 0xc000
	s_nop 0
	global_load_lds_dwordx4 v206, s[56:57]
	s_nop 0
	s_add_u32 m0, s14, 0xe000
	s_nop 0
	global_load_lds_dwordx4 v208, s[56:57]
	s_waitcnt vmcnt(8)
	s_waitcnt lgkmcnt(0)
	s_barrier
	v_mfma_f32_16x16x32_f16 v[90:93], v[2:5], v[58:61], 0
	s_setprio 1
	v_mfma_f32_16x16x32_f16 v[94:97], v[6:9], v[62:65], v[90:93]
	v_mfma_f32_16x16x32_f16 v[66:69], v[2:5], v[34:37], 0
	v_mfma_f32_16x16x32_f16 v[66:69], v[6:9], v[38:41], v[66:69]
	v_mfma_f32_16x16x32_f16 v[70:73], v[10:13], v[34:37], 0
	v_mfma_f32_16x16x32_f16 v[70:73], v[14:17], v[38:41], v[70:73]
	v_mfma_f32_16x16x32_f16 v[74:77], v[2:5], v[42:45], 0
	v_mfma_f32_16x16x32_f16 v[74:77], v[6:9], v[46:49], v[74:77]
	v_mfma_f32_16x16x32_f16 v[78:81], v[10:13], v[42:45], 0
	v_mfma_f32_16x16x32_f16 v[78:81], v[14:17], v[46:49], v[78:81]
	v_mfma_f32_16x16x32_f16 v[82:85], v[2:5], v[50:53], 0
	v_mfma_f32_16x16x32_f16 v[82:85], v[6:9], v[54:57], v[82:85]
	v_mfma_f32_16x16x32_f16 v[86:89], v[10:13], v[50:53], 0
	v_mfma_f32_16x16x32_f16 v[86:89], v[14:17], v[54:57], v[86:89]
	v_mfma_f32_16x16x32_f16 v[90:93], v[10:13], v[58:61], 0
	v_mfma_f32_16x16x32_f16 v[102:105], v[14:17], v[62:65], v[90:93]
	v_mfma_f32_16x16x32_f16 v[90:93], v[18:21], v[34:37], 0
	v_mfma_f32_16x16x32_f16 v[118:121], v[22:25], v[38:41], v[90:93]
	v_mfma_f32_16x16x32_f16 v[34:37], v[26:29], v[34:37], 0
	v_mfma_f32_16x16x32_f16 v[34:37], v[30:33], v[38:41], v[34:37]
	v_mfma_f32_16x16x32_f16 v[38:41], v[18:21], v[42:45], 0
	v_mfma_f32_16x16x32_f16 v[38:41], v[22:25], v[46:49], v[38:41]
	v_mfma_f32_16x16x32_f16 v[42:45], v[26:29], v[42:45], 0
	v_mfma_f32_16x16x32_f16 v[42:45], v[30:33], v[46:49], v[42:45]
	v_mfma_f32_16x16x32_f16 v[46:49], v[18:21], v[50:53], 0
	v_mfma_f32_16x16x32_f16 v[46:49], v[22:25], v[54:57], v[46:49]
	v_mfma_f32_16x16x32_f16 v[50:53], v[26:29], v[50:53], 0
	v_mfma_f32_16x16x32_f16 v[50:53], v[30:33], v[54:57], v[50:53]
	v_mfma_f32_16x16x32_f16 v[54:57], v[18:21], v[58:61], 0
	v_mfma_f32_16x16x32_f16 v[54:57], v[22:25], v[62:65], v[54:57]
	v_mfma_f32_16x16x32_f16 v[58:61], v[26:29], v[58:61], 0
	v_mfma_f32_16x16x32_f16 v[58:61], v[30:33], v[62:65], v[58:61]
	s_barrier
	s_setprio 0
	ds_read_b128 v[62:65], v212 offset:16384
	ds_read_b128 v[90:93], v212 offset:17408
	ds_read_b128 v[98:101], v212 offset:18432
	ds_read_b128 v[106:109], v212 offset:19456
	ds_read_b128 v[110:113], v212 offset:20480
	ds_read_b128 v[114:117], v212 offset:21504
	ds_read_b128 v[122:125], v212 offset:22528
	ds_read_b128 v[126:129], v212 offset:23552
	s_add_u32 m0, s14, 0x10000
	s_nop 0
	global_load_lds_dwordx4 v207, s[54:55]
	s_nop 0
	s_add_u32 m0, s14, 0x12000
	s_nop 0
	global_load_lds_dwordx4 v209, s[54:55]
	s_add_u32 s54, s6, 0x40100
	s_addc_u32 s55, s7, 0
	s_add_u32 m0, s14, 0x14000
	s_nop 0
	global_load_lds_dwordx4 v207, s[54:55]
	s_nop 0
	s_add_u32 m0, s14, 0x16000
	s_nop 0
	global_load_lds_dwordx4 v209, s[54:55]
	s_nop 0
	s_add_u32 m0, s14, 0
	s_nop 0
	global_load_lds_dwordx4 v206, s[48:49]
	s_nop 0
	s_add_u32 m0, s14, 0x2000
	s_nop 0
	global_load_lds_dwordx4 v208, s[48:49]
	s_waitcnt vmcnt(8)
	s_waitcnt lgkmcnt(0)
	s_barrier
	v_mfma_f32_16x16x32_f16 v[130:133], v[2:5], v[62:65], 0
	s_setprio 1
	v_mfma_f32_16x16x32_f16 v[130:133], v[6:9], v[90:93], v[130:133]
	v_mfma_f32_16x16x32_f16 v[138:141], v[2:5], v[98:101], 0
	v_mfma_f32_16x16x32_f16 v[138:141], v[6:9], v[106:109], v[138:141]
	v_mfma_f32_16x16x32_f16 v[146:149], v[2:5], v[110:113], 0
	v_mfma_f32_16x16x32_f16 v[146:149], v[6:9], v[114:117], v[146:149]
	v_mfma_f32_16x16x32_f16 v[2:5], v[2:5], v[122:125], 0
	v_mfma_f32_16x16x32_f16 v[2:5], v[6:9], v[126:129], v[2:5]
	v_mfma_f32_16x16x32_f16 v[6:9], v[10:13], v[122:125], 0
	v_mfma_f32_16x16x32_f16 v[6:9], v[14:17], v[126:129], v[6:9]
	v_mfma_f32_16x16x32_f16 v[134:137], v[10:13], v[62:65], 0
	v_mfma_f32_16x16x32_f16 v[134:137], v[14:17], v[90:93], v[134:137]
	v_mfma_f32_16x16x32_f16 v[142:145], v[10:13], v[98:101], 0
	v_mfma_f32_16x16x32_f16 v[142:145], v[14:17], v[106:109], v[142:145]
	v_mfma_f32_16x16x32_f16 v[150:153], v[10:13], v[110:113], 0
	v_mfma_f32_16x16x32_f16 v[150:153], v[14:17], v[114:117], v[150:153]
	v_mfma_f32_16x16x32_f16 v[10:13], v[18:21], v[62:65], 0
	v_mfma_f32_16x16x32_f16 v[14:17], v[22:25], v[90:93], v[10:13]
	v_mfma_f32_16x16x32_f16 v[10:13], v[26:29], v[62:65], 0
	v_mfma_f32_16x16x32_f16 v[154:157], v[30:33], v[90:93], v[10:13]
	v_mfma_f32_16x16x32_f16 v[10:13], v[18:21], v[98:101], 0
	v_mfma_f32_16x16x32_f16 v[158:161], v[22:25], v[106:109], v[10:13]
	v_mfma_f32_16x16x32_f16 v[10:13], v[26:29], v[98:101], 0
	v_mfma_f32_16x16x32_f16 v[162:165], v[30:33], v[106:109], v[10:13]
	v_mfma_f32_16x16x32_f16 v[10:13], v[18:21], v[110:113], 0
	v_mfma_f32_16x16x32_f16 v[166:169], v[22:25], v[114:117], v[10:13]
	v_mfma_f32_16x16x32_f16 v[10:13], v[26:29], v[110:113], 0
	v_mfma_f32_16x16x32_f16 v[170:173], v[30:33], v[114:117], v[10:13]
	v_mfma_f32_16x16x32_f16 v[10:13], v[18:21], v[122:125], 0
	v_mfma_f32_16x16x32_f16 v[174:177], v[22:25], v[126:129], v[10:13]
	v_mfma_f32_16x16x32_f16 v[10:13], v[26:29], v[122:125], 0
	v_mfma_f32_16x16x32_f16 v[178:181], v[30:33], v[126:129], v[10:13]
	s_barrier
; #define PG8_STAGE(bufoff, gbase, voff) do { if constexpr (ABL & 1) break; glds16s<(bufoff)>((voff)[0], (const void*)(gbase), ldsbw); glds16s<(bufoff) + 8192>((voff)[1], (const void*)(gbase), ldsbw); } while (0)
; #define PG8_LDA(dst, b, h) do { if constexpr (ABL & 4) break; _Pragma("unroll") for (int m = 0; m < 4; ++m) _Pragma("unroll") for (int k = 0; k < 2; ++k) dst[m][k] = *(const LAS f16x8*)(lds + PG8_SA(b, h) + aoff + m * 2048 + k * 1024); } while (0)
; #define PG8_LDB(dst, b, h) do { if constexpr (ABL & 4) break; _Pragma("unroll") for (int n = 0; n < 2; ++n) _Pragma("unroll") for (int k = 0; k < 2; ++k) dst[n][k] = *(const LAS f16x8*)(lds + PG8_SB(b, h) + boff + n * 2048 + k * 1024); } while (0)
; #define PG8_MMA(ai, bj, At, Bt) do { if constexpr (ABL & 2) break; __builtin_amdgcn_s_setprio(1); _Pragma("unroll") for (int m = 0; m < 4; ++m) _Pragma("unroll") for (int n = 0; n < 2; ++n) _Pragma("unroll") for (int k = 0; k < 2; ++k) \
;         acc[ai][bj][m][n] = __builtin_amdgcn_mfma_f32_16x16x32_f16(Bt[n][k], At[m][k], acc[ai][bj][m][n], 0, 0, 0); __builtin_amdgcn_s_setprio(0); } while (0)
; #define PG8_WAIT_V(n) asm volatile("s_waitcnt vmcnt(" #n ")" ::: "memory")
; #define PG8_WAIT_L(n) asm volatile("s_waitcnt lgkmcnt(" #n ")" ::: "memory")
; #define PG8_BAR __builtin_amdgcn_s_barrier()
; #define PG8_SCHED __builtin_amdgcn_sched_barrier(0)
;     ...
;             PG8_LDB(B0, 1, 0); PG8_LDB(B1, 1, 1); PG8_SCHED; PG8_LDA(At, 1, 0); if (!fin) PG8_STAGE(PG8_SA(0, 1), a2 + hstep, voffA);
;             if (!fin) PG8_WAIT_V(8); else PG8_WAIT_V(0); PG8_WAIT_L(0); PG8_BAR; PG8_MMA(0, 0, At, B0); PG8_MMA(0, 1, At, B1); PG8_BAR; PG8_SCHED;
;             PG8_LDA(At, 1, 1); if (!fin) { PG8_STAGE(PG8_SB(1, 0), b3, voffB); PG8_STAGE(PG8_SB(1, 1), b3 + hstep, voffB); PG8_STAGE(PG8_SA(1, 0), a3, voffA); }
;             if (!fin) PG8_WAIT_V(8); PG8_WAIT_L(0); PG8_BAR; PG8_MMA(1, 0, At, B0); PG8_MMA(1, 1, At, B1); PG8_BAR; PG8_SCHED;
	s_setprio 0
	s_nop 4
	ds_read_b128 v[10:13], v213
	ds_read_b128 v[22:25], v213 offset:1024
	ds_read_b128 v[30:33], v213 offset:2048
	ds_read_b128 v[182:185], v213 offset:3072
	ds_read_b128 v[186:189], v214
	ds_read_b128 v[190:193], v214 offset:1024
	ds_read_b128 v[216:219], v214 offset:2048
	ds_read_b128 v[220:223], v214 offset:3072
	ds_read_b128 v[18:21], v212 offset:32768
	ds_read_b128 v[26:29], v212 offset:33792
	ds_read_b128 v[224:227], v212 offset:34816
	ds_read_b128 v[228:231], v212 offset:35840
	ds_read_b128 v[232:235], v212 offset:36864
	ds_read_b128 v[236:239], v212 offset:37888
	ds_read_b128 v[240:243], v212 offset:38912
	ds_read_b128 v[244:247], v212 offset:39936
	s_add_u32 s8, s8, 0x40100
	s_addc_u32 s9, s9, 0
	s_add_u32 m0, s14, 0x4000
	s_nop 0
	global_load_lds_dwordx4 v206, s[8:9]
	s_nop 0
	s_add_u32 m0, s14, 0x6000
	s_nop 0
	global_load_lds_dwordx4 v208, s[8:9]
	s_waitcnt vmcnt(8)
	s_waitcnt lgkmcnt(0)
	s_barrier
	v_mfma_f32_16x16x32_f16 v[62:65], v[10:13], v[18:21], v[66:69]
	s_setprio 1
	v_mfma_f32_16x16x32_f16 v[114:117], v[22:25], v[26:29], v[62:65]
	v_mfma_f32_16x16x32_f16 v[62:65], v[30:33], v[18:21], v[70:73]
	v_mfma_f32_16x16x32_f16 v[110:113], v[182:185], v[26:29], v[62:65]
	v_mfma_f32_16x16x32_f16 v[62:65], v[10:13], v[224:227], v[74:77]
	v_mfma_f32_16x16x32_f16 v[106:109], v[22:25], v[228:231], v[62:65]
	v_mfma_f32_16x16x32_f16 v[62:65], v[30:33], v[224:227], v[78:81]
	v_mfma_f32_16x16x32_f16 v[98:101], v[182:185], v[228:231], v[62:65]
	v_mfma_f32_16x16x32_f16 v[62:65], v[10:13], v[232:235], v[82:85]
	v_mfma_f32_16x16x32_f16 v[90:93], v[22:25], v[236:239], v[62:65]
	v_mfma_f32_16x16x32_f16 v[62:65], v[30:33], v[232:235], v[86:89]
	v_mfma_f32_16x16x32_f16 v[82:85], v[182:185], v[236:239], v[62:65]
	v_mfma_f32_16x16x32_f16 v[62:65], v[10:13], v[240:243], v[94:97]
	v_mfma_f32_16x16x32_f16 v[74:77], v[22:25], v[244:247], v[62:65]
	v_mfma_f32_16x16x32_f16 v[62:65], v[30:33], v[240:243], v[102:105]
	v_mfma_f32_16x16x32_f16 v[62:65], v[182:185], v[244:247], v[62:65]
	v_mfma_f32_16x16x32_f16 v[66:69], v[186:189], v[18:21], v[118:121]
	v_mfma_f32_16x16x32_f16 v[126:129], v[190:193], v[26:29], v[66:69]
	v_mfma_f32_16x16x32_f16 v[18:21], v[216:219], v[18:21], v[34:37]
	v_mfma_f32_16x16x32_f16 v[122:125], v[220:223], v[26:29], v[18:21]
	v_mfma_f32_16x16x32_f16 v[18:21], v[186:189], v[224:227], v[38:41]
	v_mfma_f32_16x16x32_f16 v[118:121], v[190:193], v[228:231], v[18:21]
	v_mfma_f32_16x16x32_f16 v[18:21], v[216:219], v[224:227], v[42:45]
	v_mfma_f32_16x16x32_f16 v[102:105], v[220:223], v[228:231], v[18:21]
	v_mfma_f32_16x16x32_f16 v[18:21], v[186:189], v[232:235], v[46:49]
	v_mfma_f32_16x16x32_f16 v[94:97], v[190:193], v[236:239], v[18:21]
	v_mfma_f32_16x16x32_f16 v[18:21], v[216:219], v[232:235], v[50:53]
	v_mfma_f32_16x16x32_f16 v[86:89], v[220:223], v[236:239], v[18:21]
	v_mfma_f32_16x16x32_f16 v[18:21], v[186:189], v[240:243], v[54:57]
	v_mfma_f32_16x16x32_f16 v[78:81], v[190:193], v[244:247], v[18:21]
	v_mfma_f32_16x16x32_f16 v[18:21], v[216:219], v[240:243], v[58:61]
	v_mfma_f32_16x16x32_f16 v[70:73], v[220:223], v[244:247], v[18:21]
	s_barrier
	s_setprio 0
	ds_read_b128 v[38:41], v212 offset:49152
	ds_read_b128 v[46:49], v212 offset:50176
	ds_read_b128 v[224:227], v212 offset:51200
	ds_read_b128 v[228:231], v212 offset:52224
	ds_read_b128 v[232:235], v212 offset:53248
	ds_read_b128 v[236:239], v212 offset:54272
	ds_read_b128 v[240:243], v212 offset:55296
	ds_read_b128 v[244:247], v212 offset:56320
	s_add_u32 m0, s14, 0x18000
	s_nop 0
	global_load_lds_dwordx4 v207, s[26:27]
	s_nop 0
	s_add_u32 m0, s14, 0x1a000
	s_nop 0
	global_load_lds_dwordx4 v209, s[26:27]
	s_add_u32 s8, s6, 0x40180
	s_addc_u32 s9, s7, 0
	s_add_u32 m0, s14, 0x1c000
	s_nop 0
	global_load_lds_dwordx4 v207, s[8:9]
	s_nop 0
	s_add_u32 m0, s14, 0x1e000
	s_nop 0
	global_load_lds_dwordx4 v209, s[8:9]
	s_nop 0
	s_add_u32 m0, s14, 0x8000
	s_nop 0
	global_load_lds_dwordx4 v206, s[24:25]
	s_nop 0
	s_add_u32 m0, s14, 0xa000
	s_nop 0
	global_load_lds_dwordx4 v208, s[24:25]
	s_waitcnt vmcnt(8)
	s_waitcnt lgkmcnt(0)
	s_barrier
	v_mfma_f32_16x16x32_f16 v[18:21], v[10:13], v[38:41], v[130:133]
	s_setprio 1
	v_mfma_f32_16x16x32_f16 v[58:61], v[22:25], v[46:49], v[18:21]
	v_mfma_f32_16x16x32_f16 v[18:21], v[30:33], v[38:41], v[134:137]
	v_mfma_f32_16x16x32_f16 v[50:53], v[182:185], v[46:49], v[18:21]
	v_mfma_f32_16x16x32_f16 v[18:21], v[10:13], v[224:227], v[138:141]
	v_mfma_f32_16x16x32_f16 v[42:45], v[22:25], v[228:231], v[18:21]
	v_mfma_f32_16x16x32_f16 v[18:21], v[30:33], v[224:227], v[142:145]
	v_mfma_f32_16x16x32_f16 v[34:37], v[182:185], v[228:231], v[18:21]
	v_mfma_f32_16x16x32_f16 v[18:21], v[10:13], v[232:235], v[146:149]
	v_mfma_f32_16x16x32_f16 v[26:29], v[22:25], v[236:239], v[18:21]
	v_mfma_f32_16x16x32_f16 v[2:5], v[10:13], v[240:243], v[2:5]
	v_mfma_f32_16x16x32_f16 v[10:13], v[22:25], v[244:247], v[2:5]
	v_mfma_f32_16x16x32_f16 v[18:21], v[30:33], v[232:235], v[150:153]
	v_mfma_f32_16x16x32_f16 v[18:21], v[182:185], v[236:239], v[18:21]
	v_mfma_f32_16x16x32_f16 v[2:5], v[30:33], v[240:243], v[6:9]
	v_mfma_f32_16x16x32_f16 v[2:5], v[182:185], v[244:247], v[2:5]
	v_mfma_f32_16x16x32_f16 v[6:9], v[186:189], v[38:41], v[14:17]
	v_mfma_f32_16x16x32_f16 v[66:69], v[190:193], v[46:49], v[6:9]
	v_mfma_f32_16x16x32_f16 v[6:9], v[216:219], v[38:41], v[154:157]
	v_mfma_f32_16x16x32_f16 v[54:57], v[220:223], v[46:49], v[6:9]
	v_mfma_f32_16x16x32_f16 v[6:9], v[186:189], v[224:227], v[158:161]
	v_mfma_f32_16x16x32_f16 v[46:49], v[190:193], v[228:231], v[6:9]
	v_mfma_f32_16x16x32_f16 v[6:9], v[216:219], v[224:227], v[162:165]
	v_mfma_f32_16x16x32_f16 v[38:41], v[220:223], v[228:231], v[6:9]
	v_mfma_f32_16x16x32_f16 v[6:9], v[186:189], v[232:235], v[166:169]
	v_mfma_f32_16x16x32_f16 v[30:33], v[190:193], v[236:239], v[6:9]
	v_mfma_f32_16x16x32_f16 v[6:9], v[216:219], v[232:235], v[170:173]
	v_mfma_f32_16x16x32_f16 v[22:25], v[220:223], v[236:239], v[6:9]
	v_mfma_f32_16x16x32_f16 v[6:9], v[186:189], v[240:243], v[174:177]
	v_mfma_f32_16x16x32_f16 v[14:17], v[190:193], v[244:247], v[6:9]
	v_mfma_f32_16x16x32_f16 v[6:9], v[216:219], v[240:243], v[178:181]
	v_mfma_f32_16x16x32_f16 v[6:9], v[220:223], v[244:247], v[6:9]
	s_barrier
	s_setprio 0
	s_add_u32 s53, s6, 0x200
	s_addc_u32 s54, s7, 0
	s_mov_b32 s55, 0
	s_branch .LBB0_843

;     __device__ __forceinline__ bool next(int i, Unit& u) const { if (i >= count) return false; const int L = first + i; u.pm = L / nN; u.pn = L % nN; return true; }
; #define PG8_STAGE(bufoff, gbase, voff) do { if constexpr (ABL & 1) break; glds16s<(bufoff)>((voff)[0], (const void*)(gbase), ldsbw); glds16s<(bufoff) + 8192>((voff)[1], (const void*)(gbase), ldsbw); } while (0)
; #define PG8_LDA(dst, b, h) do { if constexpr (ABL & 4) break; _Pragma("unroll") for (int m = 0; m < 4; ++m) _Pragma("unroll") for (int k = 0; k < 2; ++k) dst[m][k] = *(const LAS f16x8*)(lds + PG8_SA(b, h) + aoff + m * 2048 + k * 1024); } while (0)
; #define PG8_LDB(dst, b, h) do { if constexpr (ABL & 4) break; _Pragma("unroll") for (int n = 0; n < 2; ++n) _Pragma("unroll") for (int k = 0; k < 2; ++k) dst[n][k] = *(const LAS f16x8*)(lds + PG8_SB(b, h) + boff + n * 2048 + k * 1024); } while (0)
; #define PG8_MMAF(ai, bj, At, Bt) do { if (t == 0) PG8_MMA0(ai, bj, At, Bt); else PG8_MMA(ai, bj, At, Bt); } while (0)
; #define PG8_WAIT_V(n) asm volatile("s_waitcnt vmcnt(" #n ")" ::: "memory")
; #define PG8_BAR __builtin_amdgcn_s_barrier()
;     ...
;         const bool has_next = S.next(ui + 1, nxt);
;         const char* nA = has_next ? (const char*)g.A + (size_t)nxt.pm * tstep : cA; const char* nB = has_next ? (const char*)g.Bt + (size_t)nxt.pn * tstep : cB;
;         for (int t = 0; t < nt; t += 2) {
;             const bool last = (t == nt - 2);
;             const char* a1 = cA + (size_t)(t + 1) * kstep;
;             const char* a2 = last ? nA : cA + (size_t)(t + 2) * kstep; const char* b2 = last ? nB : cB + (size_t)(t + 2) * kstep;
;             const char* a3 = a2 + kstep; const char* b3 = b2 + kstep;
;             if (last && has_next) S.a_ready(nxt);
;             if constexpr (SP2) {
;             PG8_LDB(B0, 0, 0); PG8_LDB(B1, 0, 1); PG8_SCHED; PG8_LDA(At, 0, 0); PG8_STAGE(PG8_SA(1, 1), a1 + hstep, voffA);
;             PG8_WAIT_V(8); PG8_WAIT_L(0); PG8_BAR; PG8_MMAF(0, 0, At, B0); PG8_MMAF(0, 1, At, B1); PG8_BAR; PG8_SCHED;
;             const bool fin = last && !has_next;
;             PG8_LDA(At, 0, 1); if (!fin) { PG8_STAGE(PG8_SB(0, 0), b2, voffB); PG8_STAGE(PG8_SB(0, 1), b2 + hstep, voffB); PG8_STAGE(PG8_SA(0, 0), a2, voffA); }
;             if (!fin) PG8_WAIT_V(8); else PG8_WAIT_V(2); PG8_WAIT_L(0); PG8_BAR; PG8_MMAF(1, 0, At, B0); PG8_MMAF(1, 1, At, B1); PG8_BAR; PG8_SCHED;
.LBB0_878:
	s_ashr_i32 s45, s44, 31
	s_lshl_b64 s[8:9], s[44:45], 17
	s_add_u32 s48, s86, s8
	ds_read_b128 v[2:5], v1
	ds_read_b128 v[6:9], v1 offset:1024
	ds_read_b128 v[10:13], v1 offset:2048
	ds_read_b128 v[14:17], v1 offset:3072
	ds_read_b128 v[18:21], v234
	ds_read_b128 v[22:25], v234 offset:1024
	ds_read_b128 v[26:29], v234 offset:2048
	ds_read_b128 v[30:33], v234 offset:3072
	s_addc_u32 s49, s87, s9
	s_ashr_i32 s43, s42, 31
	s_lshl_b64 s[8:9], s[42:43], 17
	s_add_u32 s50, s70, s8
	s_addc_u32 s51, s71, s9
	s_add_u32 s26, s52, 0x100
	s_addc_u32 s27, s53, 0
	s_add_u32 s60, s54, 0x100
	s_addc_u32 s61, s55, 0
	s_add_u32 s8, s52, 0x180
	s_addc_u32 s9, s53, 0
	ds_read_b128 v[34:37], v235
	ds_read_b128 v[38:41], v235 offset:1024
	ds_read_b128 v[42:45], v235 offset:2048
	ds_read_b128 v[46:49], v235 offset:3072
	ds_read_b128 v[50:53], v235 offset:4096
	ds_read_b128 v[54:57], v235 offset:5120
	ds_read_b128 v[58:61], v235 offset:6144
	ds_read_b128 v[62:65], v235 offset:7168
	s_add_u32 s24, s54, 0x180
	s_addc_u32 s25, s55, 0
	s_add_u32 s62, s52, 0x10080
	s_addc_u32 s63, s53, 0
	s_add_u32 m0, s14, 0xc000
	s_nop 0
	global_load_lds_dwordx4 v230, s[62:63]
	s_nop 0
	s_add_u32 m0, s14, 0xe000
	s_nop 0
	global_load_lds_dwordx4 v232, s[62:63]
	s_waitcnt vmcnt(8)
	s_waitcnt lgkmcnt(0)
	s_barrier
	v_mfma_f32_16x16x32_f16 v[66:69], v[2:5], v[34:37], 0
	s_setprio 1
	v_mfma_f32_16x16x32_f16 v[66:69], v[6:9], v[38:41], v[66:69]
	v_mfma_f32_16x16x32_f16 v[70:73], v[10:13], v[34:37], 0
	v_mfma_f32_16x16x32_f16 v[70:73], v[14:17], v[38:41], v[70:73]
	v_mfma_f32_16x16x32_f16 v[82:85], v[2:5], v[50:53], 0
	v_mfma_f32_16x16x32_f16 v[82:85], v[6:9], v[54:57], v[82:85]
	v_mfma_f32_16x16x32_f16 v[86:89], v[10:13], v[50:53], 0
	v_mfma_f32_16x16x32_f16 v[86:89], v[14:17], v[54:57], v[86:89]
	v_mfma_f32_16x16x32_f16 v[90:93], v[2:5], v[58:61], 0
	v_mfma_f32_16x16x32_f16 v[90:93], v[6:9], v[62:65], v[90:93]
	v_mfma_f32_16x16x32_f16 v[94:97], v[10:13], v[58:61], 0
	v_mfma_f32_16x16x32_f16 v[94:97], v[14:17], v[62:65], v[94:97]
	v_mfma_f32_16x16x32_f16 v[74:77], v[2:5], v[42:45], 0
	v_mfma_f32_16x16x32_f16 v[74:77], v[6:9], v[46:49], v[74:77]
	v_mfma_f32_16x16x32_f16 v[78:81], v[10:13], v[42:45], 0
	v_mfma_f32_16x16x32_f16 v[78:81], v[14:17], v[46:49], v[78:81]
	v_mfma_f32_16x16x32_f16 v[98:101], v[18:21], v[34:37], 0
	v_mfma_f32_16x16x32_f16 v[98:101], v[22:25], v[38:41], v[98:101]
	v_mfma_f32_16x16x32_f16 v[34:37], v[26:29], v[34:37], 0
	v_mfma_f32_16x16x32_f16 v[34:37], v[30:33], v[38:41], v[34:37]
	v_mfma_f32_16x16x32_f16 v[38:41], v[18:21], v[42:45], 0
	v_mfma_f32_16x16x32_f16 v[38:41], v[22:25], v[46:49], v[38:41]
	v_mfma_f32_16x16x32_f16 v[42:45], v[26:29], v[42:45], 0
	v_mfma_f32_16x16x32_f16 v[42:45], v[30:33], v[46:49], v[42:45]
	v_mfma_f32_16x16x32_f16 v[46:49], v[18:21], v[50:53], 0
	v_mfma_f32_16x16x32_f16 v[46:49], v[22:25], v[54:57], v[46:49]
	v_mfma_f32_16x16x32_f16 v[50:53], v[26:29], v[50:53], 0
	v_mfma_f32_16x16x32_f16 v[50:53], v[30:33], v[54:57], v[50:53]
	v_mfma_f32_16x16x32_f16 v[54:57], v[18:21], v[58:61], 0
	v_mfma_f32_16x16x32_f16 v[54:57], v[22:25], v[62:65], v[54:57]
	v_mfma_f32_16x16x32_f16 v[58:61], v[26:29], v[58:61], 0
	v_mfma_f32_16x16x32_f16 v[58:61], v[30:33], v[62:65], v[58:61]
	s_barrier
	s_setprio 0
	ds_read_b128 v[62:65], v235 offset:16384
	ds_read_b128 v[102:105], v235 offset:17408
	ds_read_b128 v[106:109], v235 offset:18432
	ds_read_b128 v[110:113], v235 offset:19456
	ds_read_b128 v[114:117], v235 offset:20480
	ds_read_b128 v[118:121], v235 offset:21504
	ds_read_b128 v[122:125], v235 offset:22528
	ds_read_b128 v[126:129], v235 offset:23552
	s_add_u32 m0, s14, 0x10000
	s_nop 0
	global_load_lds_dwordx4 v231, s[60:61]
	s_nop 0
	s_add_u32 m0, s14, 0x12000
	s_nop 0
	global_load_lds_dwordx4 v233, s[60:61]
	s_add_u32 s60, s54, 0x10100
	s_addc_u32 s61, s55, 0
	s_add_u32 m0, s14, 0x14000
	s_nop 0
	global_load_lds_dwordx4 v231, s[60:61]
	s_nop 0
	s_add_u32 m0, s14, 0x16000
	s_nop 0
	global_load_lds_dwordx4 v233, s[60:61]
	s_nop 0
	s_add_u32 m0, s14, 0
	s_nop 0
	global_load_lds_dwordx4 v230, s[26:27]
	s_nop 0
	s_add_u32 m0, s14, 0x2000
	s_nop 0
	global_load_lds_dwordx4 v232, s[26:27]
	s_waitcnt vmcnt(8)
	s_waitcnt lgkmcnt(0)
	s_barrier
	v_mfma_f32_16x16x32_f16 v[130:133], v[2:5], v[62:65], 0
	s_setprio 1
	v_mfma_f32_16x16x32_f16 v[130:133], v[6:9], v[102:105], v[130:133]
	v_mfma_f32_16x16x32_f16 v[138:141], v[2:5], v[106:109], 0
	v_mfma_f32_16x16x32_f16 v[138:141], v[6:9], v[110:113], v[138:141]
	v_mfma_f32_16x16x32_f16 v[146:149], v[2:5], v[114:117], 0
	v_mfma_f32_16x16x32_f16 v[146:149], v[6:9], v[118:121], v[146:149]
	v_mfma_f32_16x16x32_f16 v[2:5], v[2:5], v[122:125], 0
	v_mfma_f32_16x16x32_f16 v[2:5], v[6:9], v[126:129], v[2:5]
	v_mfma_f32_16x16x32_f16 v[134:137], v[10:13], v[62:65], 0
	v_mfma_f32_16x16x32_f16 v[134:137], v[14:17], v[102:105], v[134:137]
	v_mfma_f32_16x16x32_f16 v[142:145], v[10:13], v[106:109], 0
	v_mfma_f32_16x16x32_f16 v[142:145], v[14:17], v[110:113], v[142:145]
	v_mfma_f32_16x16x32_f16 v[150:153], v[10:13], v[114:117], 0
	v_mfma_f32_16x16x32_f16 v[150:153], v[14:17], v[118:121], v[150:153]
	v_mfma_f32_16x16x32_f16 v[6:9], v[10:13], v[122:125], 0
	v_mfma_f32_16x16x32_f16 v[6:9], v[14:17], v[126:129], v[6:9]
	v_mfma_f32_16x16x32_f16 v[10:13], v[18:21], v[62:65], 0
	v_mfma_f32_16x16x32_f16 v[10:13], v[22:25], v[102:105], v[10:13]
	v_mfma_f32_16x16x32_f16 v[14:17], v[26:29], v[62:65], 0
	v_mfma_f32_16x16x32_f16 v[14:17], v[30:33], v[102:105], v[14:17]
	v_mfma_f32_16x16x32_f16 v[102:105], v[26:29], v[106:109], 0
	v_mfma_f32_16x16x32_f16 v[154:157], v[30:33], v[110:113], v[102:105]
	v_mfma_f32_16x16x32_f16 v[62:65], v[18:21], v[106:109], 0
	v_mfma_f32_16x16x32_f16 v[62:65], v[22:25], v[110:113], v[62:65]
	v_mfma_f32_16x16x32_f16 v[102:105], v[18:21], v[114:117], 0
	v_mfma_f32_16x16x32_f16 v[158:161], v[22:25], v[118:121], v[102:105]
	v_mfma_f32_16x16x32_f16 v[18:21], v[18:21], v[122:125], 0
	v_mfma_f32_16x16x32_f16 v[18:21], v[22:25], v[126:129], v[18:21]
	v_mfma_f32_16x16x32_f16 v[102:105], v[26:29], v[114:117], 0
	v_mfma_f32_16x16x32_f16 v[162:165], v[30:33], v[118:121], v[102:105]
	v_mfma_f32_16x16x32_f16 v[22:25], v[26:29], v[122:125], 0
	v_mfma_f32_16x16x32_f16 v[22:25], v[30:33], v[126:129], v[22:25]
	s_barrier
; #define PG8_STAGE(bufoff, gbase, voff) do { if constexpr (ABL & 1) break; glds16s<(bufoff)>((voff)[0], (const void*)(gbase), ldsbw); glds16s<(bufoff) + 8192>((voff)[1], (const void*)(gbase), ldsbw); } while (0)
; #define PG8_LDA(dst, b, h) do { if constexpr (ABL & 4) break; _Pragma("unroll") for (int m = 0; m < 4; ++m) _Pragma("unroll") for (int k = 0; k < 2; ++k) dst[m][k] = *(const LAS f16x8*)(lds + PG8_SA(b, h) + aoff + m * 2048 + k * 1024); } while (0)
; #define PG8_LDB(dst, b, h) do { if constexpr (ABL & 4) break; _Pragma("unroll") for (int n = 0; n < 2; ++n) _Pragma("unroll") for (int k = 0; k < 2; ++k) dst[n][k] = *(const LAS f16x8*)(lds + PG8_SB(b, h) + boff + n * 2048 + k * 1024); } while (0)
; #define PG8_MMA(ai, bj, At, Bt) do { if constexpr (ABL & 2) break; __builtin_amdgcn_s_setprio(1); _Pragma("unroll") for (int m = 0; m < 4; ++m) _Pragma("unroll") for (int n = 0; n < 2; ++n) _Pragma("unroll") for (int k = 0; k < 2; ++k) \
;         acc[ai][bj][m][n] = __builtin_amdgcn_mfma_f32_16x16x32_f16(Bt[n][k], At[m][k], acc[ai][bj][m][n], 0, 0, 0); __builtin_amdgcn_s_setprio(0); } while (0)
; #define PG8_WAIT_V(n) asm volatile("s_waitcnt vmcnt(" #n ")" ::: "memory")
; #define PG8_WAIT_L(n) asm volatile("s_waitcnt lgkmcnt(" #n ")" ::: "memory")
; #define PG8_BAR __builtin_amdgcn_s_barrier()
; #define PG8_SCHED __builtin_amdgcn_sched_barrier(0)
;     ...
;             PG8_LDB(B0, 1, 0); PG8_LDB(B1, 1, 1); PG8_SCHED; PG8_LDA(At, 1, 0); if (!fin) PG8_STAGE(PG8_SA(0, 1), a2 + hstep, voffA);
;             if (!fin) PG8_WAIT_V(8); else PG8_WAIT_V(0); PG8_WAIT_L(0); PG8_BAR; PG8_MMA(0, 0, At, B0); PG8_MMA(0, 1, At, B1); PG8_BAR; PG8_SCHED;
;             PG8_LDA(At, 1, 1); if (!fin) { PG8_STAGE(PG8_SB(1, 0), b3, voffB); PG8_STAGE(PG8_SB(1, 1), b3 + hstep, voffB); PG8_STAGE(PG8_SA(1, 0), a3, voffA); }
;             if (!fin) PG8_WAIT_V(8); PG8_WAIT_L(0); PG8_BAR; PG8_MMA(1, 0, At, B0); PG8_MMA(1, 1, At, B1); PG8_BAR; PG8_SCHED;
	s_setprio 0
	ds_read_b128 v[26:29], v236
	ds_read_b128 v[30:33], v236 offset:1024
	ds_read_b128 v[102:105], v236 offset:2048
	ds_read_b128 v[106:109], v236 offset:3072
	ds_read_b128 v[166:169], v237
	ds_read_b128 v[170:173], v237 offset:1024
	ds_read_b128 v[174:177], v237 offset:2048
	ds_read_b128 v[178:181], v237 offset:3072
	ds_read_b128 v[110:113], v235 offset:32768
	ds_read_b128 v[114:117], v235 offset:33792
	ds_read_b128 v[118:121], v235 offset:34816
	ds_read_b128 v[122:125], v235 offset:35840
	ds_read_b128 v[126:129], v235 offset:36864
	ds_read_b128 v[182:185], v235 offset:37888
	ds_read_b128 v[186:189], v235 offset:38912
	ds_read_b128 v[190:193], v235 offset:39936
	s_add_u32 s26, s52, 0x10100
	s_addc_u32 s27, s53, 0
	s_add_u32 m0, s14, 0x4000
	s_nop 0
	global_load_lds_dwordx4 v230, s[26:27]
	s_nop 0
	s_add_u32 m0, s14, 0x6000
	s_nop 0
	global_load_lds_dwordx4 v232, s[26:27]
	s_waitcnt vmcnt(8)
	s_waitcnt lgkmcnt(0)
	s_barrier
	v_mfma_f32_16x16x32_f16 v[82:85], v[26:29], v[126:129], v[82:85]
	s_setprio 1
	v_mfma_f32_16x16x32_f16 v[194:197], v[30:33], v[182:185], v[82:85]
	v_mfma_f32_16x16x32_f16 v[82:85], v[102:105], v[126:129], v[86:89]
	v_mfma_f32_16x16x32_f16 v[198:201], v[106:109], v[182:185], v[82:85]
	v_mfma_f32_16x16x32_f16 v[66:69], v[26:29], v[110:113], v[66:69]
	v_mfma_f32_16x16x32_f16 v[66:69], v[30:33], v[114:117], v[66:69]
	v_mfma_f32_16x16x32_f16 v[70:73], v[102:105], v[110:113], v[70:73]
	v_mfma_f32_16x16x32_f16 v[70:73], v[106:109], v[114:117], v[70:73]
	v_mfma_f32_16x16x32_f16 v[82:85], v[26:29], v[186:189], v[90:93]
	v_mfma_f32_16x16x32_f16 v[202:205], v[30:33], v[190:193], v[82:85]
	v_mfma_f32_16x16x32_f16 v[74:77], v[26:29], v[118:121], v[74:77]
	v_mfma_f32_16x16x32_f16 v[74:77], v[30:33], v[122:125], v[74:77]
	v_mfma_f32_16x16x32_f16 v[78:81], v[102:105], v[118:121], v[78:81]
	v_mfma_f32_16x16x32_f16 v[78:81], v[106:109], v[122:125], v[78:81]
	v_mfma_f32_16x16x32_f16 v[82:85], v[102:105], v[186:189], v[94:97]
	v_mfma_f32_16x16x32_f16 v[206:209], v[106:109], v[190:193], v[82:85]
	v_mfma_f32_16x16x32_f16 v[34:37], v[174:177], v[110:113], v[34:37]
	v_mfma_f32_16x16x32_f16 v[214:217], v[178:181], v[114:117], v[34:37]
	v_mfma_f32_16x16x32_f16 v[34:37], v[166:169], v[118:121], v[38:41]
	v_mfma_f32_16x16x32_f16 v[218:221], v[170:173], v[122:125], v[34:37]
	v_mfma_f32_16x16x32_f16 v[34:37], v[174:177], v[118:121], v[42:45]
	v_mfma_f32_16x16x32_f16 v[222:225], v[178:181], v[122:125], v[34:37]
	v_mfma_f32_16x16x32_f16 v[34:37], v[166:169], v[126:129], v[46:49]
	v_mfma_f32_16x16x32_f16 v[238:241], v[170:173], v[182:185], v[34:37]
	v_mfma_f32_16x16x32_f16 v[34:37], v[174:177], v[126:129], v[50:53]
	v_mfma_f32_16x16x32_f16 v[182:185], v[178:181], v[182:185], v[34:37]
	v_mfma_f32_16x16x32_f16 v[34:37], v[166:169], v[186:189], v[54:57]
	v_mfma_f32_16x16x32_f16 v[242:245], v[170:173], v[190:193], v[34:37]
	v_mfma_f32_16x16x32_f16 v[34:37], v[174:177], v[186:189], v[58:61]
	v_mfma_f32_16x16x32_f16 v[186:189], v[178:181], v[190:193], v[34:37]
	v_mfma_f32_16x16x32_f16 v[82:85], v[166:169], v[110:113], v[98:101]
	v_mfma_f32_16x16x32_f16 v[210:213], v[170:173], v[114:117], v[82:85]
	s_barrier
	s_setprio 0
	ds_read_b128 v[42:45], v235 offset:49152
	ds_read_b128 v[46:49], v235 offset:50176
	ds_read_b128 v[50:53], v235 offset:51200
	ds_read_b128 v[54:57], v235 offset:52224
	ds_read_b128 v[58:61], v235 offset:53248
	ds_read_b128 v[126:129], v235 offset:54272
	ds_read_b128 v[190:193], v235 offset:55296
	ds_read_b128 v[246:249], v235 offset:56320
	s_add_u32 m0, s14, 0x18000
	s_nop 0
	global_load_lds_dwordx4 v231, s[24:25]
	s_nop 0
	s_add_u32 m0, s14, 0x1a000
	s_nop 0
	global_load_lds_dwordx4 v233, s[24:25]
	s_add_u32 s24, s54, 0x10180
	s_addc_u32 s25, s55, 0
	s_add_u32 m0, s14, 0x1c000
	s_nop 0
	global_load_lds_dwordx4 v231, s[24:25]
	s_nop 0
	s_add_u32 m0, s14, 0x1e000
	s_nop 0
	global_load_lds_dwordx4 v233, s[24:25]
	s_nop 0
	s_add_u32 m0, s14, 0x8000
	s_nop 0
	global_load_lds_dwordx4 v230, s[8:9]
	s_nop 0
	s_add_u32 m0, s14, 0xa000
	s_nop 0
	global_load_lds_dwordx4 v232, s[8:9]
	s_waitcnt vmcnt(8)
	s_waitcnt lgkmcnt(0)
	s_barrier
; #define PG8_STAGE(bufoff, gbase, voff) do { if constexpr (ABL & 1) break; glds16s<(bufoff)>((voff)[0], (const void*)(gbase), ldsbw); glds16s<(bufoff) + 8192>((voff)[1], (const void*)(gbase), ldsbw); } while (0)
; #define PG8_LDA(dst, b, h) do { if constexpr (ABL & 4) break; _Pragma("unroll") for (int m = 0; m < 4; ++m) _Pragma("unroll") for (int k = 0; k < 2; ++k) dst[m][k] = *(const LAS f16x8*)(lds + PG8_SA(b, h) + aoff + m * 2048 + k * 1024); } while (0)
; #define PG8_LDB(dst, b, h) do { if constexpr (ABL & 4) break; _Pragma("unroll") for (int n = 0; n < 2; ++n) _Pragma("unroll") for (int k = 0; k < 2; ++k) dst[n][k] = *(const LAS f16x8*)(lds + PG8_SB(b, h) + boff + n * 2048 + k * 1024); } while (0)
; #define PG8_MMA(ai, bj, At, Bt) do { if constexpr (ABL & 2) break; __builtin_amdgcn_s_setprio(1); _Pragma("unroll") for (int m = 0; m < 4; ++m) _Pragma("unroll") for (int n = 0; n < 2; ++n) _Pragma("unroll") for (int k = 0; k < 2; ++k) \
;         acc[ai][bj][m][n] = __builtin_amdgcn_mfma_f32_16x16x32_f16(Bt[n][k], At[m][k], acc[ai][bj][m][n], 0, 0, 0); __builtin_amdgcn_s_setprio(0); } while (0)
; #define PG8_WAIT_V(n) asm volatile("s_waitcnt vmcnt(" #n ")" ::: "memory")
;     ...
;             PG8_LDB(B0, 0, 0); PG8_LDB(B1, 0, 1); PG8_SCHED; PG8_LDA(At, 0, 0); PG8_STAGE(PG8_SA(1, 1), a1 + hstep, voffA);
;             PG8_WAIT_V(8); PG8_WAIT_L(0); PG8_BAR; PG8_MMAF(0, 0, At, B0); PG8_MMAF(0, 1, At, B1); PG8_BAR; PG8_SCHED;
;             const bool fin = last && !has_next;
;             PG8_LDA(At, 0, 1); if (!fin) { PG8_STAGE(PG8_SB(0, 0), b2, voffB); PG8_STAGE(PG8_SB(0, 1), b2 + hstep, voffB); PG8_STAGE(PG8_SA(0, 0), a2, voffA); }
;             if (!fin) PG8_WAIT_V(8); else PG8_WAIT_V(2); PG8_WAIT_L(0); PG8_BAR; PG8_MMAF(1, 0, At, B0); PG8_MMAF(1, 1, At, B1); PG8_BAR; PG8_SCHED;
;             PG8_LDB(B0, 1, 0); PG8_LDB(B1, 1, 1); PG8_SCHED; PG8_LDA(At, 1, 0); if (!fin) PG8_STAGE(PG8_SA(0, 1), a2 + hstep, voffA);
;             if (!fin) PG8_WAIT_V(8); else PG8_WAIT_V(0); PG8_WAIT_L(0); PG8_BAR; PG8_MMA(0, 0, At, B0); PG8_MMA(0, 1, At, B1); PG8_BAR; PG8_SCHED;
;             PG8_LDA(At, 1, 1); if (!fin) { PG8_STAGE(PG8_SB(1, 0), b3, voffB); PG8_STAGE(PG8_SB(1, 1), b3 + hstep, voffB); PG8_STAGE(PG8_SA(1, 0), a3, voffA); }
;             if (!fin) PG8_WAIT_V(8); PG8_WAIT_L(0); PG8_BAR; PG8_MMA(1, 0, At, B0); PG8_MMA(1, 1, At, B1); PG8_BAR; PG8_SCHED;
	v_mfma_f32_16x16x32_f16 v[2:5], v[26:29], v[190:193], v[2:5]
	s_setprio 1
	v_mfma_f32_16x16x32_f16 v[98:101], v[30:33], v[246:249], v[2:5]
	v_mfma_f32_16x16x32_f16 v[34:37], v[26:29], v[42:45], v[130:133]
	v_mfma_f32_16x16x32_f16 v[34:37], v[30:33], v[46:49], v[34:37]
	v_mfma_f32_16x16x32_f16 v[38:41], v[102:105], v[42:45], v[134:137]
	v_mfma_f32_16x16x32_f16 v[38:41], v[106:109], v[46:49], v[38:41]
	v_mfma_f32_16x16x32_f16 v[82:85], v[26:29], v[50:53], v[138:141]
	v_mfma_f32_16x16x32_f16 v[82:85], v[30:33], v[54:57], v[82:85]
	v_mfma_f32_16x16x32_f16 v[86:89], v[102:105], v[50:53], v[142:145]
	v_mfma_f32_16x16x32_f16 v[86:89], v[106:109], v[54:57], v[86:89]
	v_mfma_f32_16x16x32_f16 v[90:93], v[26:29], v[58:61], v[146:149]
	v_mfma_f32_16x16x32_f16 v[90:93], v[30:33], v[126:129], v[90:93]
	v_mfma_f32_16x16x32_f16 v[94:97], v[102:105], v[58:61], v[150:153]
	v_mfma_f32_16x16x32_f16 v[94:97], v[106:109], v[126:129], v[94:97]
	v_mfma_f32_16x16x32_f16 v[2:5], v[102:105], v[190:193], v[6:9]
	v_mfma_f32_16x16x32_f16 v[102:105], v[106:109], v[246:249], v[2:5]
	v_mfma_f32_16x16x32_f16 v[2:5], v[166:169], v[42:45], v[10:13]
	v_mfma_f32_16x16x32_f16 v[106:109], v[170:173], v[46:49], v[2:5]
	v_mfma_f32_16x16x32_f16 v[2:5], v[174:177], v[42:45], v[14:17]
	v_mfma_f32_16x16x32_f16 v[110:113], v[178:181], v[46:49], v[2:5]
	v_mfma_f32_16x16x32_f16 v[2:5], v[166:169], v[50:53], v[62:65]
	v_mfma_f32_16x16x32_f16 v[114:117], v[170:173], v[54:57], v[2:5]
	v_mfma_f32_16x16x32_f16 v[2:5], v[174:177], v[50:53], v[154:157]
	v_mfma_f32_16x16x32_f16 v[118:121], v[178:181], v[54:57], v[2:5]
	v_mfma_f32_16x16x32_f16 v[2:5], v[166:169], v[58:61], v[158:161]
	v_mfma_f32_16x16x32_f16 v[122:125], v[170:173], v[126:129], v[2:5]
	v_mfma_f32_16x16x32_f16 v[2:5], v[174:177], v[58:61], v[162:165]
	v_mfma_f32_16x16x32_f16 v[126:129], v[178:181], v[126:129], v[2:5]
	v_mfma_f32_16x16x32_f16 v[2:5], v[166:169], v[190:193], v[18:21]
	v_mfma_f32_16x16x32_f16 v[130:133], v[170:173], v[246:249], v[2:5]
	v_mfma_f32_16x16x32_f16 v[2:5], v[174:177], v[190:193], v[22:25]
	v_mfma_f32_16x16x32_f16 v[134:137], v[178:181], v[246:249], v[2:5]
	s_barrier
	s_setprio 0
	ds_read_b128 v[154:157], v1
	ds_read_b128 v[158:161], v1 offset:1024
	ds_read_b128 v[162:165], v1 offset:2048
	ds_read_b128 v[166:169], v1 offset:3072
	ds_read_b128 v[138:141], v234
	ds_read_b128 v[142:145], v234 offset:1024
	ds_read_b128 v[146:149], v234 offset:2048
	ds_read_b128 v[150:153], v234 offset:3072
	ds_read_b128 v[46:49], v235
	ds_read_b128 v[50:53], v235 offset:1024
	ds_read_b128 v[54:57], v235 offset:2048
	ds_read_b128 v[58:61], v235 offset:3072
	ds_read_b128 v[62:65], v235 offset:4096
	ds_read_b128 v[170:173], v235 offset:5120
	ds_read_b128 v[174:177], v235 offset:6144
	ds_read_b128 v[178:181], v235 offset:7168
	s_add_u32 s8, s52, 0x10180
	s_addc_u32 s9, s53, 0
	s_add_u32 m0, s14, 0xc000
	s_nop 0
	global_load_lds_dwordx4 v230, s[8:9]
	s_nop 0
	s_add_u32 m0, s14, 0xe000
	s_nop 0
	global_load_lds_dwordx4 v232, s[8:9]
	s_waitcnt vmcnt(8)
	s_waitcnt lgkmcnt(0)
	s_barrier
	v_mfma_f32_16x16x32_f16 v[2:5], v[154:157], v[46:49], v[66:69]
	s_setprio 1
	v_mfma_f32_16x16x32_f16 v[2:5], v[158:161], v[50:53], v[2:5]
	v_mfma_f32_16x16x32_f16 v[6:9], v[162:165], v[46:49], v[70:73]
	v_mfma_f32_16x16x32_f16 v[6:9], v[166:169], v[50:53], v[6:9]
	v_mfma_f32_16x16x32_f16 v[10:13], v[154:157], v[54:57], v[74:77]
	v_mfma_f32_16x16x32_f16 v[10:13], v[158:161], v[58:61], v[10:13]
	v_mfma_f32_16x16x32_f16 v[14:17], v[162:165], v[54:57], v[78:81]
	v_mfma_f32_16x16x32_f16 v[14:17], v[166:169], v[58:61], v[14:17]
	v_mfma_f32_16x16x32_f16 v[18:21], v[154:157], v[62:65], v[194:197]
	v_mfma_f32_16x16x32_f16 v[18:21], v[158:161], v[170:173], v[18:21]
	v_mfma_f32_16x16x32_f16 v[22:25], v[162:165], v[62:65], v[198:201]
	v_mfma_f32_16x16x32_f16 v[22:25], v[166:169], v[170:173], v[22:25]
	v_mfma_f32_16x16x32_f16 v[26:29], v[154:157], v[174:177], v[202:205]
	v_mfma_f32_16x16x32_f16 v[26:29], v[158:161], v[178:181], v[26:29]
	v_mfma_f32_16x16x32_f16 v[30:33], v[162:165], v[174:177], v[206:209]
	v_mfma_f32_16x16x32_f16 v[30:33], v[166:169], v[178:181], v[30:33]
	v_mfma_f32_16x16x32_f16 v[42:45], v[138:141], v[46:49], v[210:213]
	v_mfma_f32_16x16x32_f16 v[42:45], v[142:145], v[50:53], v[42:45]
	v_mfma_f32_16x16x32_f16 v[46:49], v[146:149], v[46:49], v[214:217]
	v_mfma_f32_16x16x32_f16 v[46:49], v[150:153], v[50:53], v[46:49]
	v_mfma_f32_16x16x32_f16 v[50:53], v[138:141], v[54:57], v[218:221]
	v_mfma_f32_16x16x32_f16 v[50:53], v[142:145], v[58:61], v[50:53]
	v_mfma_f32_16x16x32_f16 v[54:57], v[146:149], v[54:57], v[222:225]
	v_mfma_f32_16x16x32_f16 v[54:57], v[150:153], v[58:61], v[54:57]
	v_mfma_f32_16x16x32_f16 v[58:61], v[138:141], v[62:65], v[238:241]
	v_mfma_f32_16x16x32_f16 v[58:61], v[142:145], v[170:173], v[58:61]
	v_mfma_f32_16x16x32_f16 v[62:65], v[146:149], v[62:65], v[182:185]
	v_mfma_f32_16x16x32_f16 v[62:65], v[150:153], v[170:173], v[62:65]
	v_mfma_f32_16x16x32_f16 v[66:69], v[138:141], v[174:177], v[242:245]
	v_mfma_f32_16x16x32_f16 v[66:69], v[142:145], v[178:181], v[66:69]
	v_mfma_f32_16x16x32_f16 v[70:73], v[146:149], v[174:177], v[186:189]
	v_mfma_f32_16x16x32_f16 v[70:73], v[150:153], v[178:181], v[70:73]
	s_barrier
	s_setprio 0
	ds_read_b128 v[194:197], v235 offset:16384
	ds_read_b128 v[198:201], v235 offset:17408
	ds_read_b128 v[186:189], v235 offset:18432
	ds_read_b128 v[190:193], v235 offset:19456
	ds_read_b128 v[178:181], v235 offset:20480
	ds_read_b128 v[182:185], v235 offset:21504
	ds_read_b128 v[170:173], v235 offset:22528
	ds_read_b128 v[174:177], v235 offset:23552
	s_mov_b64 s[8:9], -1
	s_and_b64 vcc, exec, s[4:5]
	s_cbranch_vccz .LBB0_880
	s_waitcnt vmcnt(2)
	s_mov_b64 s[8:9], 0

; #define PG8_STAGE(bufoff, gbase, voff) do { if constexpr (ABL & 1) break; glds16s<(bufoff)>((voff)[0], (const void*)(gbase), ldsbw); glds16s<(bufoff) + 8192>((voff)[1], (const void*)(gbase), ldsbw); } while (0)
; #define PG8_LDA(dst, b, h) do { if constexpr (ABL & 4) break; _Pragma("unroll") for (int m = 0; m < 4; ++m) _Pragma("unroll") for (int k = 0; k < 2; ++k) dst[m][k] = *(const LAS f16x8*)(lds + PG8_SA(b, h) + aoff + m * 2048 + k * 1024); } while (0)
; #define PG8_LDB(dst, b, h) do { if constexpr (ABL & 4) break; _Pragma("unroll") for (int n = 0; n < 2; ++n) _Pragma("unroll") for (int k = 0; k < 2; ++k) dst[n][k] = *(const LAS f16x8*)(lds + PG8_SB(b, h) + boff + n * 2048 + k * 1024); } while (0)
; #define PG8_MMAF(ai, bj, At, Bt) do { if (t == 0) PG8_MMA0(ai, bj, At, Bt); else PG8_MMA(ai, bj, At, Bt); } while (0)
; #define PG8_WAIT_V(n) asm volatile("s_waitcnt vmcnt(" #n ")" ::: "memory")
; #define PG8_WAIT_L(n) asm volatile("s_waitcnt lgkmcnt(" #n ")" ::: "memory")
; #define PG8_BAR __builtin_amdgcn_s_barrier()
; #define PG8_SCHED __builtin_amdgcn_sched_barrier(0)
;     ...
;             if (!fin) PG8_WAIT_V(8); else PG8_WAIT_V(2); PG8_WAIT_L(0); PG8_BAR; PG8_MMAF(1, 0, At, B0); PG8_MMAF(1, 1, At, B1); PG8_BAR; PG8_SCHED;
;             PG8_LDB(B0, 1, 0); PG8_LDB(B1, 1, 1); PG8_SCHED; PG8_LDA(At, 1, 0); if (!fin) PG8_STAGE(PG8_SA(0, 1), a2 + hstep, voffA);
.LBB0_882:
	s_waitcnt lgkmcnt(0)
	s_barrier
	v_mfma_f32_16x16x32_f16 v[34:37], v[154:157], v[194:197], v[34:37]
	s_setprio 1
	v_mfma_f32_16x16x32_f16 v[74:77], v[158:161], v[198:201], v[34:37]
	v_mfma_f32_16x16x32_f16 v[34:37], v[162:165], v[194:197], v[38:41]
	v_mfma_f32_16x16x32_f16 v[78:81], v[166:169], v[198:201], v[34:37]
	v_mfma_f32_16x16x32_f16 v[34:37], v[154:157], v[186:189], v[82:85]
	v_mfma_f32_16x16x32_f16 v[82:85], v[158:161], v[190:193], v[34:37]
	v_mfma_f32_16x16x32_f16 v[34:37], v[162:165], v[186:189], v[86:89]
	v_mfma_f32_16x16x32_f16 v[86:89], v[166:169], v[190:193], v[34:37]
	v_mfma_f32_16x16x32_f16 v[34:37], v[154:157], v[178:181], v[90:93]
	v_mfma_f32_16x16x32_f16 v[90:93], v[158:161], v[182:185], v[34:37]
	v_mfma_f32_16x16x32_f16 v[34:37], v[162:165], v[178:181], v[94:97]
	v_mfma_f32_16x16x32_f16 v[94:97], v[166:169], v[182:185], v[34:37]
	v_mfma_f32_16x16x32_f16 v[34:37], v[154:157], v[170:173], v[98:101]
	v_mfma_f32_16x16x32_f16 v[98:101], v[158:161], v[174:177], v[34:37]
	v_mfma_f32_16x16x32_f16 v[34:37], v[162:165], v[170:173], v[102:105]
	v_mfma_f32_16x16x32_f16 v[102:105], v[166:169], v[174:177], v[34:37]
	v_mfma_f32_16x16x32_f16 v[34:37], v[138:141], v[194:197], v[106:109]
	v_mfma_f32_16x16x32_f16 v[106:109], v[142:145], v[198:201], v[34:37]
	v_mfma_f32_16x16x32_f16 v[34:37], v[146:149], v[194:197], v[110:113]
	v_mfma_f32_16x16x32_f16 v[110:113], v[150:153], v[198:201], v[34:37]
	v_mfma_f32_16x16x32_f16 v[34:37], v[138:141], v[186:189], v[114:117]
	v_mfma_f32_16x16x32_f16 v[114:117], v[142:145], v[190:193], v[34:37]
	v_mfma_f32_16x16x32_f16 v[34:37], v[146:149], v[186:189], v[118:121]
	v_mfma_f32_16x16x32_f16 v[118:121], v[150:153], v[190:193], v[34:37]
	v_mfma_f32_16x16x32_f16 v[34:37], v[138:141], v[178:181], v[122:125]
	v_mfma_f32_16x16x32_f16 v[122:125], v[142:145], v[182:185], v[34:37]
	v_mfma_f32_16x16x32_f16 v[34:37], v[146:149], v[178:181], v[126:129]
	v_mfma_f32_16x16x32_f16 v[126:129], v[150:153], v[182:185], v[34:37]
	v_mfma_f32_16x16x32_f16 v[34:37], v[138:141], v[170:173], v[130:133]
	v_mfma_f32_16x16x32_f16 v[130:133], v[142:145], v[174:177], v[34:37]
	v_mfma_f32_16x16x32_f16 v[34:37], v[146:149], v[170:173], v[134:137]
	v_mfma_f32_16x16x32_f16 v[134:137], v[150:153], v[174:177], v[34:37]
	s_barrier
	s_setprio 0
	ds_read_b128 v[170:173], v236
	ds_read_b128 v[174:177], v236 offset:1024
	ds_read_b128 v[178:181], v236 offset:2048
	ds_read_b128 v[182:185], v236 offset:3072
	ds_read_b128 v[146:149], v237
	ds_read_b128 v[150:153], v237 offset:1024
	ds_read_b128 v[154:157], v237 offset:2048
	ds_read_b128 v[158:161], v237 offset:3072
	ds_read_b128 v[162:165], v235 offset:32768
	ds_read_b128 v[206:209], v235 offset:33792
	ds_read_b128 v[166:169], v235 offset:34816
	ds_read_b128 v[218:221], v235 offset:35840
	ds_read_b128 v[210:213], v235 offset:36864
	ds_read_b128 v[214:217], v235 offset:37888
	ds_read_b128 v[194:197], v235 offset:38912
	ds_read_b128 v[198:201], v235 offset:39936
	s_mov_b64 s[8:9], -1
	s_and_b64 vcc, exec, s[4:5]
	s_cbranch_vccz .LBB0_884
	s_waitcnt vmcnt(0)
	s_mov_b64 s[8:9], 0

; #define PG8_STAGE(bufoff, gbase, voff) do { if constexpr (ABL & 1) break; glds16s<(bufoff)>((voff)[0], (const void*)(gbase), ldsbw); glds16s<(bufoff) + 8192>((voff)[1], (const void*)(gbase), ldsbw); } while (0)
; #define PG8_LDA(dst, b, h) do { if constexpr (ABL & 4) break; _Pragma("unroll") for (int m = 0; m < 4; ++m) _Pragma("unroll") for (int k = 0; k < 2; ++k) dst[m][k] = *(const LAS f16x8*)(lds + PG8_SA(b, h) + aoff + m * 2048 + k * 1024); } while (0)
; #define PG8_MMA(ai, bj, At, Bt) do { if constexpr (ABL & 2) break; __builtin_amdgcn_s_setprio(1); _Pragma("unroll") for (int m = 0; m < 4; ++m) _Pragma("unroll") for (int n = 0; n < 2; ++n) _Pragma("unroll") for (int k = 0; k < 2; ++k) \
;         acc[ai][bj][m][n] = __builtin_amdgcn_mfma_f32_16x16x32_f16(Bt[n][k], At[m][k], acc[ai][bj][m][n], 0, 0, 0); __builtin_amdgcn_s_setprio(0); } while (0)
; #define PG8_WAIT_V(n) asm volatile("s_waitcnt vmcnt(" #n ")" ::: "memory")
; #define PG8_WAIT_L(n) asm volatile("s_waitcnt lgkmcnt(" #n ")" ::: "memory")
; #define PG8_BAR __builtin_amdgcn_s_barrier()
; #define PG8_SCHED __builtin_amdgcn_sched_barrier(0)
;     ...
;             if (!fin) PG8_WAIT_V(8); else PG8_WAIT_V(0); PG8_WAIT_L(0); PG8_BAR; PG8_MMA(0, 0, At, B0); PG8_MMA(0, 1, At, B1); PG8_BAR; PG8_SCHED;
;             PG8_LDA(At, 1, 1); if (!fin) { PG8_STAGE(PG8_SB(1, 0), b3, voffB); PG8_STAGE(PG8_SB(1, 1), b3 + hstep, voffB); PG8_STAGE(PG8_SA(1, 0), a3, voffA); }
;             if (!fin) PG8_WAIT_V(8); PG8_WAIT_L(0); PG8_BAR; PG8_MMA(1, 0, At, B0); PG8_MMA(1, 1, At, B1); PG8_BAR; PG8_SCHED;
;     ...
;         if constexpr (ALIGN_EPI) { if (wr == 0) PG8_BAR; }
.LBB0_886:
	s_waitcnt lgkmcnt(0)
	s_barrier
	v_mfma_f32_16x16x32_f16 v[2:5], v[170:173], v[162:165], v[2:5]
	s_setprio 1
	v_mfma_f32_16x16x32_f16 v[186:189], v[174:177], v[206:209], v[2:5]
	v_mfma_f32_16x16x32_f16 v[2:5], v[178:181], v[162:165], v[6:9]
	v_mfma_f32_16x16x32_f16 v[190:193], v[182:185], v[206:209], v[2:5]
	v_mfma_f32_16x16x32_f16 v[2:5], v[170:173], v[166:169], v[10:13]
	v_mfma_f32_16x16x32_f16 v[138:141], v[174:177], v[218:221], v[2:5]
	v_mfma_f32_16x16x32_f16 v[2:5], v[178:181], v[166:169], v[14:17]
	v_mfma_f32_16x16x32_f16 v[142:145], v[182:185], v[218:221], v[2:5]
	v_mfma_f32_16x16x32_f16 v[2:5], v[170:173], v[210:213], v[18:21]
	v_mfma_f32_16x16x32_f16 v[34:37], v[174:177], v[214:217], v[2:5]
	v_mfma_f32_16x16x32_f16 v[2:5], v[178:181], v[210:213], v[22:25]
	v_mfma_f32_16x16x32_f16 v[38:41], v[182:185], v[214:217], v[2:5]
	v_mfma_f32_16x16x32_f16 v[2:5], v[170:173], v[194:197], v[26:29]
	v_mfma_f32_16x16x32_f16 v[2:5], v[174:177], v[198:201], v[2:5]
	v_mfma_f32_16x16x32_f16 v[6:9], v[178:181], v[194:197], v[30:33]
	v_mfma_f32_16x16x32_f16 v[6:9], v[182:185], v[198:201], v[6:9]
	v_mfma_f32_16x16x32_f16 v[10:13], v[146:149], v[162:165], v[42:45]
	v_mfma_f32_16x16x32_f16 v[202:205], v[150:153], v[206:209], v[10:13]
	v_mfma_f32_16x16x32_f16 v[10:13], v[154:157], v[162:165], v[46:49]
	v_mfma_f32_16x16x32_f16 v[206:209], v[158:161], v[206:209], v[10:13]
	v_mfma_f32_16x16x32_f16 v[10:13], v[146:149], v[166:169], v[50:53]
	v_mfma_f32_16x16x32_f16 v[162:165], v[150:153], v[218:221], v[10:13]
	v_mfma_f32_16x16x32_f16 v[10:13], v[154:157], v[166:169], v[54:57]
	v_mfma_f32_16x16x32_f16 v[166:169], v[158:161], v[218:221], v[10:13]
	v_mfma_f32_16x16x32_f16 v[10:13], v[146:149], v[210:213], v[58:61]
	v_mfma_f32_16x16x32_f16 v[50:53], v[150:153], v[214:217], v[10:13]
	v_mfma_f32_16x16x32_f16 v[10:13], v[154:157], v[210:213], v[62:65]
	v_mfma_f32_16x16x32_f16 v[54:57], v[158:161], v[214:217], v[10:13]
	v_mfma_f32_16x16x32_f16 v[10:13], v[146:149], v[194:197], v[66:69]
	v_mfma_f32_16x16x32_f16 v[18:21], v[150:153], v[198:201], v[10:13]
	v_mfma_f32_16x16x32_f16 v[10:13], v[154:157], v[194:197], v[70:73]
	v_mfma_f32_16x16x32_f16 v[22:25], v[158:161], v[198:201], v[10:13]
	s_barrier
	s_setprio 0
	ds_read_b128 v[218:221], v235 offset:49152
	ds_read_b128 v[222:225], v235 offset:50176
	ds_read_b128 v[58:61], v235 offset:51200
	ds_read_b128 v[214:217], v235 offset:52224
	ds_read_b128 v[26:29], v235 offset:53248
	ds_read_b128 v[62:65], v235 offset:54272
	ds_read_b128 v[30:33], v235 offset:55296
	ds_read_b128 v[210:213], v235 offset:56320
	v_cndmask_b32_e64 v10, 0, 1, s[2:3]
	v_cmp_ne_u32_e64 s[4:5], 1, v10
	s_andn2_b64 vcc, exec, s[2:3]
	s_cbranch_vccnz .LBB0_888
	s_and_b64 s[2:3], s[2:3], exec
	s_cselect_b32 s2, s48, s52
	s_cselect_b32 s3, s49, s53
	s_cselect_b32 s9, s51, s55
	s_cselect_b32 s8, s50, s54
	s_add_u32 s2, s2, 0x80
	s_addc_u32 s3, s3, 0
	s_add_u32 s8, s8, 0x80
	s_addc_u32 s9, s9, 0
	s_add_u32 m0, s14, 0x18000
	s_nop 0
	global_load_lds_dwordx4 v231, s[8:9]
	s_nop 0
	s_add_u32 m0, s14, 0x1a000
	s_nop 0
	global_load_lds_dwordx4 v233, s[8:9]
	s_add_u32 s8, s50, 0x10080
	s_addc_u32 s9, s51, 0
	s_add_u32 m0, s14, 0x1c000
	s_nop 0
	global_load_lds_dwordx4 v231, s[8:9]
	s_nop 0
	s_add_u32 m0, s14, 0x1e000
	s_nop 0
	global_load_lds_dwordx4 v233, s[8:9]
	s_nop 0
	s_add_u32 m0, s14, 0x8000
	s_nop 0
	global_load_lds_dwordx4 v230, s[2:3]
	s_nop 0
	s_add_u32 m0, s14, 0xa000
	s_nop 0
	global_load_lds_dwordx4 v232, s[2:3]
	s_waitcnt vmcnt(8)
.LBB0_888:
	s_waitcnt lgkmcnt(0)
	s_barrier
	v_mfma_f32_16x16x32_f16 v[10:13], v[170:173], v[218:221], v[74:77]
	s_setprio 1
	v_mfma_f32_16x16x32_f16 v[194:197], v[174:177], v[222:225], v[10:13]
	v_mfma_f32_16x16x32_f16 v[10:13], v[178:181], v[218:221], v[78:81]
	v_mfma_f32_16x16x32_f16 v[198:201], v[182:185], v[222:225], v[10:13]
	v_mfma_f32_16x16x32_f16 v[10:13], v[170:173], v[58:61], v[82:85]
	v_mfma_f32_16x16x32_f16 v[66:69], v[174:177], v[214:217], v[10:13]
	v_mfma_f32_16x16x32_f16 v[10:13], v[178:181], v[58:61], v[86:89]
	v_mfma_f32_16x16x32_f16 v[70:73], v[182:185], v[214:217], v[10:13]
	v_mfma_f32_16x16x32_f16 v[10:13], v[170:173], v[26:29], v[90:93]
	v_mfma_f32_16x16x32_f16 v[42:45], v[174:177], v[62:65], v[10:13]
	v_mfma_f32_16x16x32_f16 v[10:13], v[178:181], v[26:29], v[94:97]
	v_mfma_f32_16x16x32_f16 v[46:49], v[182:185], v[62:65], v[10:13]
	v_mfma_f32_16x16x32_f16 v[10:13], v[170:173], v[30:33], v[98:101]
	v_mfma_f32_16x16x32_f16 v[10:13], v[174:177], v[210:213], v[10:13]
	v_mfma_f32_16x16x32_f16 v[14:17], v[178:181], v[30:33], v[102:105]
	v_mfma_f32_16x16x32_f16 v[14:17], v[182:185], v[210:213], v[14:17]
	v_mfma_f32_16x16x32_f16 v[74:77], v[146:149], v[218:221], v[106:109]
	v_mfma_f32_16x16x32_f16 v[82:85], v[150:153], v[222:225], v[74:77]
	v_mfma_f32_16x16x32_f16 v[74:77], v[154:157], v[218:221], v[110:113]
	v_mfma_f32_16x16x32_f16 v[86:89], v[158:161], v[222:225], v[74:77]
	v_mfma_f32_16x16x32_f16 v[74:77], v[146:149], v[58:61], v[114:117]
	v_mfma_f32_16x16x32_f16 v[74:77], v[150:153], v[214:217], v[74:77]
	v_mfma_f32_16x16x32_f16 v[58:61], v[154:157], v[58:61], v[118:121]
	v_mfma_f32_16x16x32_f16 v[78:81], v[158:161], v[214:217], v[58:61]
	v_mfma_f32_16x16x32_f16 v[58:61], v[146:149], v[26:29], v[122:125]
	v_mfma_f32_16x16x32_f16 v[58:61], v[150:153], v[62:65], v[58:61]
	v_mfma_f32_16x16x32_f16 v[26:29], v[154:157], v[26:29], v[126:129]
	v_mfma_f32_16x16x32_f16 v[62:65], v[158:161], v[62:65], v[26:29]
	v_mfma_f32_16x16x32_f16 v[26:29], v[146:149], v[30:33], v[130:133]
	v_mfma_f32_16x16x32_f16 v[26:29], v[150:153], v[210:213], v[26:29]
	v_mfma_f32_16x16x32_f16 v[30:33], v[154:157], v[30:33], v[134:137]
	v_mfma_f32_16x16x32_f16 v[30:33], v[158:161], v[210:213], v[30:33]
	s_barrier
	s_setprio 0
	s_andn2_b64 vcc, exec, s[6:7]
	s_cbranch_vccnz .LBB0_890
	s_barrier

; #define PG8_STAGE(bufoff, gbase, voff) do { if constexpr (ABL & 1) break; glds16s<(bufoff)>((voff)[0], (const void*)(gbase), ldsbw); glds16s<(bufoff) + 8192>((voff)[1], (const void*)(gbase), ldsbw); } while (0)
; #define PG8_LDA(dst, b, h) do { if constexpr (ABL & 4) break; _Pragma("unroll") for (int m = 0; m < 4; ++m) _Pragma("unroll") for (int k = 0; k < 2; ++k) dst[m][k] = *(const LAS f16x8*)(lds + PG8_SA(b, h) + aoff + m * 2048 + k * 1024); } while (0)
; #define PG8_LDB(dst, b, h) do { if constexpr (ABL & 4) break; _Pragma("unroll") for (int n = 0; n < 2; ++n) _Pragma("unroll") for (int k = 0; k < 2; ++k) dst[n][k] = *(const LAS f16x8*)(lds + PG8_SB(b, h) + boff + n * 2048 + k * 1024); } while (0)
; #define PG8_MMAF(ai, bj, At, Bt) do { if (t == 0) PG8_MMA0(ai, bj, At, Bt); else PG8_MMA(ai, bj, At, Bt); } while (0)
; #define PG8_WAIT_V(n) asm volatile("s_waitcnt vmcnt(" #n ")" ::: "memory")
; #define PG8_WAIT_L(n) asm volatile("s_waitcnt lgkmcnt(" #n ")" ::: "memory")
; #define PG8_BAR __builtin_amdgcn_s_barrier()
; #define PG8_SCHED __builtin_amdgcn_sched_barrier(0)
;     ...
;             PG8_LDB(B0, 0, 0); PG8_LDB(B1, 0, 1); PG8_SCHED; PG8_LDA(At, 0, 0); PG8_STAGE(PG8_SA(1, 1), a1 + hstep, voffA);
;             PG8_WAIT_V(8); PG8_WAIT_L(0); PG8_BAR; PG8_MMAF(0, 0, At, B0); PG8_MMAF(0, 1, At, B1); PG8_BAR; PG8_SCHED;
;             const bool fin = last && !has_next;
;             PG8_LDA(At, 0, 1); if (!fin) { PG8_STAGE(PG8_SB(0, 0), b2, voffB); PG8_STAGE(PG8_SB(0, 1), b2 + hstep, voffB); PG8_STAGE(PG8_SA(0, 0), a2, voffA); }
;             if (!fin) PG8_WAIT_V(8); else PG8_WAIT_V(2); PG8_WAIT_L(0); PG8_BAR; PG8_MMAF(1, 0, At, B0); PG8_MMAF(1, 1, At, B1); PG8_BAR; PG8_SCHED;
.LBB0_987:
	s_waitcnt lgkmcnt(0)
	ds_read_b128 v[2:5], v213
	ds_read_b128 v[6:9], v213 offset:1024
	ds_read_b128 v[10:13], v213 offset:2048
	ds_read_b128 v[14:17], v213 offset:3072
	ds_read_b128 v[18:21], v214
	ds_read_b128 v[22:25], v214 offset:1024
	ds_read_b128 v[26:29], v214 offset:2048
	ds_read_b128 v[30:33], v214 offset:3072
	s_add_u32 s50, s54, 0x100
	s_addc_u32 s51, s55, 0
	s_add_u32 s24, s52, 0x100
	s_addc_u32 s25, s53, 0
	s_add_u32 s6, s54, 0x180
	s_addc_u32 s7, s55, 0
	ds_read_b128 v[34:37], v215
	ds_read_b128 v[38:41], v215 offset:1024
	ds_read_b128 v[42:45], v215 offset:2048
	ds_read_b128 v[46:49], v215 offset:3072
	ds_read_b128 v[50:53], v215 offset:4096
	ds_read_b128 v[54:57], v215 offset:5120
	ds_read_b128 v[58:61], v215 offset:6144
	ds_read_b128 v[62:65], v215 offset:7168
	s_add_u32 s8, s52, 0x180
	s_addc_u32 s9, s53, 0
	s_add_u32 s26, s54, 0xb0080
	s_addc_u32 s27, s55, 0
	s_add_u32 m0, s28, 0xc000
	s_nop 0
	global_load_lds_dwordx4 v1, s[26:27]
	s_nop 0
	s_add_u32 m0, s28, 0xe000
	s_nop 0
	global_load_lds_dwordx4 v211, s[26:27]
	s_waitcnt vmcnt(8)
	s_waitcnt lgkmcnt(0)
	s_barrier
	v_mfma_f32_16x16x32_f16 v[70:73], v[10:13], v[34:37], 0
	s_setprio 1
	v_mfma_f32_16x16x32_f16 v[70:73], v[14:17], v[38:41], v[70:73]
	v_mfma_f32_16x16x32_f16 v[74:77], v[2:5], v[42:45], 0
	v_mfma_f32_16x16x32_f16 v[74:77], v[6:9], v[46:49], v[74:77]
	v_mfma_f32_16x16x32_f16 v[82:85], v[2:5], v[50:53], 0
	v_mfma_f32_16x16x32_f16 v[82:85], v[6:9], v[54:57], v[82:85]
	v_mfma_f32_16x16x32_f16 v[86:89], v[10:13], v[50:53], 0
	v_mfma_f32_16x16x32_f16 v[86:89], v[14:17], v[54:57], v[86:89]
	v_mfma_f32_16x16x32_f16 v[94:97], v[10:13], v[58:61], 0
	v_mfma_f32_16x16x32_f16 v[94:97], v[14:17], v[62:65], v[94:97]
	v_mfma_f32_16x16x32_f16 v[66:69], v[2:5], v[34:37], 0
	v_mfma_f32_16x16x32_f16 v[66:69], v[6:9], v[38:41], v[66:69]
	v_mfma_f32_16x16x32_f16 v[78:81], v[10:13], v[42:45], 0
	v_mfma_f32_16x16x32_f16 v[78:81], v[14:17], v[46:49], v[78:81]
	v_mfma_f32_16x16x32_f16 v[90:93], v[2:5], v[58:61], 0
	v_mfma_f32_16x16x32_f16 v[90:93], v[6:9], v[62:65], v[90:93]
	v_mfma_f32_16x16x32_f16 v[98:101], v[18:21], v[34:37], 0
	v_mfma_f32_16x16x32_f16 v[98:101], v[22:25], v[38:41], v[98:101]
	v_mfma_f32_16x16x32_f16 v[34:37], v[26:29], v[34:37], 0
	v_mfma_f32_16x16x32_f16 v[34:37], v[30:33], v[38:41], v[34:37]
	v_mfma_f32_16x16x32_f16 v[38:41], v[18:21], v[42:45], 0
	v_mfma_f32_16x16x32_f16 v[38:41], v[22:25], v[46:49], v[38:41]
	v_mfma_f32_16x16x32_f16 v[42:45], v[26:29], v[42:45], 0
	v_mfma_f32_16x16x32_f16 v[42:45], v[30:33], v[46:49], v[42:45]
	v_mfma_f32_16x16x32_f16 v[46:49], v[18:21], v[50:53], 0
	v_mfma_f32_16x16x32_f16 v[46:49], v[22:25], v[54:57], v[46:49]
	v_mfma_f32_16x16x32_f16 v[50:53], v[26:29], v[50:53], 0
	v_mfma_f32_16x16x32_f16 v[50:53], v[30:33], v[54:57], v[50:53]
	v_mfma_f32_16x16x32_f16 v[54:57], v[18:21], v[58:61], 0
	v_mfma_f32_16x16x32_f16 v[54:57], v[22:25], v[62:65], v[54:57]
	v_mfma_f32_16x16x32_f16 v[58:61], v[26:29], v[58:61], 0
	v_mfma_f32_16x16x32_f16 v[58:61], v[30:33], v[62:65], v[58:61]
	s_barrier
	s_setprio 0
	ds_read_b128 v[62:65], v215 offset:16384
	ds_read_b128 v[102:105], v215 offset:17408
	ds_read_b128 v[106:109], v215 offset:18432
	ds_read_b128 v[110:113], v215 offset:19456
	ds_read_b128 v[114:117], v215 offset:20480
	ds_read_b128 v[118:121], v215 offset:21504
	ds_read_b128 v[122:125], v215 offset:22528
	ds_read_b128 v[126:129], v215 offset:23552
	s_add_u32 m0, s28, 0x10000
	s_nop 0
	global_load_lds_dwordx4 v210, s[24:25]
	s_nop 0
	s_add_u32 m0, s28, 0x12000
	s_nop 0
	global_load_lds_dwordx4 v212, s[24:25]
	s_add_u32 s24, s52, 0xb0100
	s_addc_u32 s25, s53, 0
	s_add_u32 m0, s28, 0x14000
	s_nop 0
	global_load_lds_dwordx4 v210, s[24:25]
	s_nop 0
	s_add_u32 m0, s28, 0x16000
	s_nop 0
	global_load_lds_dwordx4 v212, s[24:25]
	s_nop 0
	s_add_u32 m0, s28, 0
	s_nop 0
	global_load_lds_dwordx4 v1, s[50:51]
	s_nop 0
	s_add_u32 m0, s28, 0x2000
	s_nop 0
	global_load_lds_dwordx4 v211, s[50:51]
	s_waitcnt vmcnt(8)
	s_waitcnt lgkmcnt(0)
	s_barrier
	v_mfma_f32_16x16x32_f16 v[130:133], v[2:5], v[62:65], 0
	s_setprio 1
	v_mfma_f32_16x16x32_f16 v[138:141], v[6:9], v[102:105], v[130:133]
	v_mfma_f32_16x16x32_f16 v[130:133], v[10:13], v[62:65], 0
	v_mfma_f32_16x16x32_f16 v[158:161], v[14:17], v[102:105], v[130:133]
	v_mfma_f32_16x16x32_f16 v[130:133], v[2:5], v[106:109], 0
	v_mfma_f32_16x16x32_f16 v[162:165], v[6:9], v[110:113], v[130:133]
	v_mfma_f32_16x16x32_f16 v[130:133], v[10:13], v[106:109], 0
	v_mfma_f32_16x16x32_f16 v[166:169], v[14:17], v[110:113], v[130:133]
	v_mfma_f32_16x16x32_f16 v[130:133], v[2:5], v[114:117], 0
	v_mfma_f32_16x16x32_f16 v[170:173], v[6:9], v[118:121], v[130:133]
	v_mfma_f32_16x16x32_f16 v[2:5], v[2:5], v[122:125], 0
	v_mfma_f32_16x16x32_f16 v[2:5], v[6:9], v[126:129], v[2:5]
	v_mfma_f32_16x16x32_f16 v[6:9], v[10:13], v[122:125], 0
	v_mfma_f32_16x16x32_f16 v[6:9], v[14:17], v[126:129], v[6:9]
	v_mfma_f32_16x16x32_f16 v[130:133], v[10:13], v[114:117], 0
	v_mfma_f32_16x16x32_f16 v[174:177], v[14:17], v[118:121], v[130:133]
	v_mfma_f32_16x16x32_f16 v[10:13], v[18:21], v[62:65], 0
	v_mfma_f32_16x16x32_f16 v[178:181], v[22:25], v[102:105], v[10:13]
	v_mfma_f32_16x16x32_f16 v[10:13], v[26:29], v[62:65], 0
	v_mfma_f32_16x16x32_f16 v[102:105], v[30:33], v[102:105], v[10:13]
	v_mfma_f32_16x16x32_f16 v[10:13], v[18:21], v[106:109], 0
	v_mfma_f32_16x16x32_f16 v[182:185], v[22:25], v[110:113], v[10:13]
	v_mfma_f32_16x16x32_f16 v[10:13], v[26:29], v[106:109], 0
	v_mfma_f32_16x16x32_f16 v[186:189], v[30:33], v[110:113], v[10:13]
	v_mfma_f32_16x16x32_f16 v[10:13], v[18:21], v[114:117], 0
	v_mfma_f32_16x16x32_f16 v[190:193], v[22:25], v[118:121], v[10:13]
	v_mfma_f32_16x16x32_f16 v[10:13], v[26:29], v[114:117], 0
	v_mfma_f32_16x16x32_f16 v[114:117], v[30:33], v[118:121], v[10:13]
	v_mfma_f32_16x16x32_f16 v[10:13], v[18:21], v[122:125], 0
	v_mfma_f32_16x16x32_f16 v[194:197], v[22:25], v[126:129], v[10:13]
	v_mfma_f32_16x16x32_f16 v[10:13], v[26:29], v[122:125], 0
	v_mfma_f32_16x16x32_f16 v[126:129], v[30:33], v[126:129], v[10:13]
	s_barrier
; #define PG8_STAGE(bufoff, gbase, voff) do { if constexpr (ABL & 1) break; glds16s<(bufoff)>((voff)[0], (const void*)(gbase), ldsbw); glds16s<(bufoff) + 8192>((voff)[1], (const void*)(gbase), ldsbw); } while (0)
; #define PG8_LDA(dst, b, h) do { if constexpr (ABL & 4) break; _Pragma("unroll") for (int m = 0; m < 4; ++m) _Pragma("unroll") for (int k = 0; k < 2; ++k) dst[m][k] = *(const LAS f16x8*)(lds + PG8_SA(b, h) + aoff + m * 2048 + k * 1024); } while (0)
; #define PG8_LDB(dst, b, h) do { if constexpr (ABL & 4) break; _Pragma("unroll") for (int n = 0; n < 2; ++n) _Pragma("unroll") for (int k = 0; k < 2; ++k) dst[n][k] = *(const LAS f16x8*)(lds + PG8_SB(b, h) + boff + n * 2048 + k * 1024); } while (0)
; #define PG8_MMA(ai, bj, At, Bt) do { if constexpr (ABL & 2) break; __builtin_amdgcn_s_setprio(1); _Pragma("unroll") for (int m = 0; m < 4; ++m) _Pragma("unroll") for (int n = 0; n < 2; ++n) _Pragma("unroll") for (int k = 0; k < 2; ++k) \
;         acc[ai][bj][m][n] = __builtin_amdgcn_mfma_f32_16x16x32_f16(Bt[n][k], At[m][k], acc[ai][bj][m][n], 0, 0, 0); __builtin_amdgcn_s_setprio(0); } while (0)
; #define PG8_WAIT_V(n) asm volatile("s_waitcnt vmcnt(" #n ")" ::: "memory")
; #define PG8_WAIT_L(n) asm volatile("s_waitcnt lgkmcnt(" #n ")" ::: "memory")
; #define PG8_BAR __builtin_amdgcn_s_barrier()
; #define PG8_SCHED __builtin_amdgcn_sched_barrier(0)
;     ...
;             PG8_LDB(B0, 1, 0); PG8_LDB(B1, 1, 1); PG8_SCHED; PG8_LDA(At, 1, 0); if (!fin) PG8_STAGE(PG8_SA(0, 1), a2 + hstep, voffA);
;             if (!fin) PG8_WAIT_V(8); else PG8_WAIT_V(0); PG8_WAIT_L(0); PG8_BAR; PG8_MMA(0, 0, At, B0); PG8_MMA(0, 1, At, B1); PG8_BAR; PG8_SCHED;
;             PG8_LDA(At, 1, 1); if (!fin) { PG8_STAGE(PG8_SB(1, 0), b3, voffB); PG8_STAGE(PG8_SB(1, 1), b3 + hstep, voffB); PG8_STAGE(PG8_SA(1, 0), a3, voffA); }
;             if (!fin) PG8_WAIT_V(8); PG8_WAIT_L(0); PG8_BAR; PG8_MMA(1, 0, At, B0); PG8_MMA(1, 1, At, B1); PG8_BAR; PG8_SCHED;
	s_setprio 0
	s_nop 4
	ds_read_b128 v[10:13], v216
	ds_read_b128 v[14:17], v216 offset:1024
	ds_read_b128 v[18:21], v216 offset:2048
	ds_read_b128 v[22:25], v216 offset:3072
	ds_read_b128 v[198:201], v217
	ds_read_b128 v[202:205], v217 offset:1024
	ds_read_b128 v[220:223], v217 offset:2048
	ds_read_b128 v[224:227], v217 offset:3072
	ds_read_b128 v[26:29], v215 offset:32768
	ds_read_b128 v[30:33], v215 offset:33792
	ds_read_b128 v[62:65], v215 offset:34816
	ds_read_b128 v[118:121], v215 offset:35840
	ds_read_b128 v[228:231], v215 offset:36864
	ds_read_b128 v[232:235], v215 offset:37888
	ds_read_b128 v[236:239], v215 offset:38912
	ds_read_b128 v[240:243], v215 offset:39936
	s_add_u32 s24, s54, 0xb0100
	s_addc_u32 s25, s55, 0
	s_add_u32 m0, s28, 0x4000
	s_nop 0
	global_load_lds_dwordx4 v1, s[24:25]
	s_nop 0
	s_add_u32 m0, s28, 0x6000
	s_nop 0
	global_load_lds_dwordx4 v211, s[24:25]
	s_waitcnt vmcnt(8)
	s_waitcnt lgkmcnt(0)
	s_barrier
	v_mfma_f32_16x16x32_f16 v[66:69], v[10:13], v[26:29], v[66:69]
	s_setprio 1
	v_mfma_f32_16x16x32_f16 v[154:157], v[14:17], v[30:33], v[66:69]
	v_mfma_f32_16x16x32_f16 v[66:69], v[18:21], v[26:29], v[70:73]
	v_mfma_f32_16x16x32_f16 v[150:153], v[22:25], v[30:33], v[66:69]
	v_mfma_f32_16x16x32_f16 v[66:69], v[10:13], v[62:65], v[74:77]
	v_mfma_f32_16x16x32_f16 v[134:137], v[14:17], v[118:121], v[66:69]
	v_mfma_f32_16x16x32_f16 v[66:69], v[18:21], v[62:65], v[78:81]
	v_mfma_f32_16x16x32_f16 v[130:133], v[22:25], v[118:121], v[66:69]
	v_mfma_f32_16x16x32_f16 v[66:69], v[10:13], v[228:231], v[82:85]
	v_mfma_f32_16x16x32_f16 v[110:113], v[14:17], v[232:235], v[66:69]
	v_mfma_f32_16x16x32_f16 v[66:69], v[18:21], v[228:231], v[86:89]
	v_mfma_f32_16x16x32_f16 v[106:109], v[22:25], v[232:235], v[66:69]
	v_mfma_f32_16x16x32_f16 v[66:69], v[10:13], v[236:239], v[90:93]
	v_mfma_f32_16x16x32_f16 v[86:89], v[14:17], v[240:243], v[66:69]
	v_mfma_f32_16x16x32_f16 v[66:69], v[18:21], v[236:239], v[94:97]
	v_mfma_f32_16x16x32_f16 v[82:85], v[22:25], v[240:243], v[66:69]
	v_mfma_f32_16x16x32_f16 v[66:69], v[198:201], v[26:29], v[98:101]
	v_mfma_f32_16x16x32_f16 v[146:149], v[202:205], v[30:33], v[66:69]
	v_mfma_f32_16x16x32_f16 v[26:29], v[220:223], v[26:29], v[34:37]
	v_mfma_f32_16x16x32_f16 v[142:145], v[224:227], v[30:33], v[26:29]
	v_mfma_f32_16x16x32_f16 v[26:29], v[198:201], v[62:65], v[38:41]
	v_mfma_f32_16x16x32_f16 v[122:125], v[202:205], v[118:121], v[26:29]
	v_mfma_f32_16x16x32_f16 v[26:29], v[220:223], v[62:65], v[42:45]
	v_mfma_f32_16x16x32_f16 v[118:121], v[224:227], v[118:121], v[26:29]
	v_mfma_f32_16x16x32_f16 v[26:29], v[198:201], v[228:231], v[46:49]
	v_mfma_f32_16x16x32_f16 v[98:101], v[202:205], v[232:235], v[26:29]
	v_mfma_f32_16x16x32_f16 v[26:29], v[220:223], v[228:231], v[50:53]
	v_mfma_f32_16x16x32_f16 v[94:97], v[224:227], v[232:235], v[26:29]
	v_mfma_f32_16x16x32_f16 v[26:29], v[198:201], v[236:239], v[54:57]
	v_mfma_f32_16x16x32_f16 v[74:77], v[202:205], v[240:243], v[26:29]
	v_mfma_f32_16x16x32_f16 v[26:29], v[220:223], v[236:239], v[58:61]
	v_mfma_f32_16x16x32_f16 v[70:73], v[224:227], v[240:243], v[26:29]
	s_barrier
	s_setprio 0
	ds_read_b128 v[34:37], v215 offset:49152
	ds_read_b128 v[38:41], v215 offset:50176
	ds_read_b128 v[66:69], v215 offset:51200
	ds_read_b128 v[78:81], v215 offset:52224
	ds_read_b128 v[90:93], v215 offset:53248
	ds_read_b128 v[228:231], v215 offset:54272
	ds_read_b128 v[232:235], v215 offset:55296
	ds_read_b128 v[236:239], v215 offset:56320
	s_add_u32 m0, s28, 0x18000
	s_nop 0
	global_load_lds_dwordx4 v210, s[8:9]
	s_nop 0
	s_add_u32 m0, s28, 0x1a000
	s_nop 0
	global_load_lds_dwordx4 v212, s[8:9]
	s_add_u32 s8, s52, 0xb0180
	s_addc_u32 s9, s53, 0
	s_add_u32 m0, s28, 0x1c000
	s_nop 0
	global_load_lds_dwordx4 v210, s[8:9]
	s_nop 0
	s_add_u32 m0, s28, 0x1e000
	s_nop 0
	global_load_lds_dwordx4 v212, s[8:9]
	s_nop 0
	s_add_u32 m0, s28, 0x8000
	s_nop 0
	global_load_lds_dwordx4 v1, s[6:7]
	s_nop 0
	s_add_u32 m0, s28, 0xa000
	s_nop 0
	global_load_lds_dwordx4 v211, s[6:7]
	s_waitcnt vmcnt(8)
	s_waitcnt lgkmcnt(0)
	s_barrier
	v_mfma_f32_16x16x32_f16 v[26:29], v[10:13], v[34:37], v[138:141]
	s_setprio 1
	v_mfma_f32_16x16x32_f16 v[62:65], v[14:17], v[38:41], v[26:29]
	v_mfma_f32_16x16x32_f16 v[26:29], v[18:21], v[34:37], v[158:161]
	v_mfma_f32_16x16x32_f16 v[58:61], v[22:25], v[38:41], v[26:29]
	v_mfma_f32_16x16x32_f16 v[26:29], v[10:13], v[66:69], v[162:165]
	v_mfma_f32_16x16x32_f16 v[46:49], v[14:17], v[78:81], v[26:29]
	v_mfma_f32_16x16x32_f16 v[26:29], v[18:21], v[66:69], v[166:169]
	v_mfma_f32_16x16x32_f16 v[42:45], v[22:25], v[78:81], v[26:29]
	v_mfma_f32_16x16x32_f16 v[26:29], v[10:13], v[90:93], v[170:173]
	v_mfma_f32_16x16x32_f16 v[30:33], v[14:17], v[228:231], v[26:29]
	v_mfma_f32_16x16x32_f16 v[2:5], v[10:13], v[232:235], v[2:5]
	v_mfma_f32_16x16x32_f16 v[14:17], v[14:17], v[236:239], v[2:5]
	v_mfma_f32_16x16x32_f16 v[26:29], v[18:21], v[90:93], v[174:177]
	v_mfma_f32_16x16x32_f16 v[26:29], v[22:25], v[228:231], v[26:29]
	v_mfma_f32_16x16x32_f16 v[2:5], v[18:21], v[232:235], v[6:9]
	v_mfma_f32_16x16x32_f16 v[10:13], v[22:25], v[236:239], v[2:5]
	v_mfma_f32_16x16x32_f16 v[2:5], v[198:201], v[34:37], v[178:181]
	v_mfma_f32_16x16x32_f16 v[54:57], v[202:205], v[38:41], v[2:5]
	v_mfma_f32_16x16x32_f16 v[2:5], v[220:223], v[34:37], v[102:105]
	v_mfma_f32_16x16x32_f16 v[50:53], v[224:227], v[38:41], v[2:5]
	v_mfma_f32_16x16x32_f16 v[2:5], v[198:201], v[66:69], v[182:185]
	v_mfma_f32_16x16x32_f16 v[38:41], v[202:205], v[78:81], v[2:5]
	v_mfma_f32_16x16x32_f16 v[2:5], v[220:223], v[66:69], v[186:189]
	v_mfma_f32_16x16x32_f16 v[34:37], v[224:227], v[78:81], v[2:5]
	v_mfma_f32_16x16x32_f16 v[2:5], v[198:201], v[90:93], v[190:193]
	v_mfma_f32_16x16x32_f16 v[22:25], v[202:205], v[228:231], v[2:5]
	v_mfma_f32_16x16x32_f16 v[2:5], v[220:223], v[90:93], v[114:117]
	v_mfma_f32_16x16x32_f16 v[18:21], v[224:227], v[228:231], v[2:5]
	v_mfma_f32_16x16x32_f16 v[2:5], v[198:201], v[232:235], v[194:197]
	v_mfma_f32_16x16x32_f16 v[6:9], v[202:205], v[236:239], v[2:5]
	v_mfma_f32_16x16x32_f16 v[2:5], v[220:223], v[232:235], v[126:129]
	v_mfma_f32_16x16x32_f16 v[2:5], v[224:227], v[236:239], v[2:5]
	s_barrier
	s_setprio 0
	s_add_u32 s52, s52, 0x200
	s_addc_u32 s53, s53, 0
	s_mov_b32 s54, 0
	s_branch .LBB0_989

; #define PG8_STAGE(bufoff, gbase, voff) do { if constexpr (ABL & 1) break; glds16s<(bufoff)>((voff)[0], (const void*)(gbase), ldsbw); glds16s<(bufoff) + 8192>((voff)[1], (const void*)(gbase), ldsbw); } while (0)
; #define PG8_LDA(dst, b, h) do { if constexpr (ABL & 4) break; _Pragma("unroll") for (int m = 0; m < 4; ++m) _Pragma("unroll") for (int k = 0; k < 2; ++k) dst[m][k] = *(const LAS f16x8*)(lds + PG8_SA(b, h) + aoff + m * 2048 + k * 1024); } while (0)
; #define PG8_LDB(dst, b, h) do { if constexpr (ABL & 4) break; _Pragma("unroll") for (int n = 0; n < 2; ++n) _Pragma("unroll") for (int k = 0; k < 2; ++k) dst[n][k] = *(const LAS f16x8*)(lds + PG8_SB(b, h) + boff + n * 2048 + k * 1024); } while (0)
; #define PG8_MMAF(ai, bj, At, Bt) do { if (t == 0) PG8_MMA0(ai, bj, At, Bt); else PG8_MMA(ai, bj, At, Bt); } while (0)
; #define PG8_WAIT_V(n) asm volatile("s_waitcnt vmcnt(" #n ")" ::: "memory")
; #define PG8_WAIT_L(n) asm volatile("s_waitcnt lgkmcnt(" #n ")" ::: "memory")
; #define PG8_BAR __builtin_amdgcn_s_barrier()
; #define PG8_SCHED __builtin_amdgcn_sched_barrier(0)
;     ...
;         for (int t = 0; t < nt; t += 2) {
;             const bool last = (t == nt - 2);
;             const char* a1 = cA + (size_t)(t + 1) * kstep;
;             const char* a2 = last ? nA : cA + (size_t)(t + 2) * kstep; const char* b2 = last ? nB : cB + (size_t)(t + 2) * kstep;
;             const char* a3 = a2 + kstep; const char* b3 = b2 + kstep;
;             if (last && has_next) S.a_ready(nxt);
;             if constexpr (SP2) {
;             PG8_LDB(B0, 0, 0); PG8_LDB(B1, 0, 1); PG8_SCHED; PG8_LDA(At, 0, 0); PG8_STAGE(PG8_SA(1, 1), a1 + hstep, voffA);
;             PG8_WAIT_V(8); PG8_WAIT_L(0); PG8_BAR; PG8_MMAF(0, 0, At, B0); PG8_MMAF(0, 1, At, B1); PG8_BAR; PG8_SCHED;
;             const bool fin = last && !has_next;
;             PG8_LDA(At, 0, 1); if (!fin) { PG8_STAGE(PG8_SB(0, 0), b2, voffB); PG8_STAGE(PG8_SB(0, 1), b2 + hstep, voffB); PG8_STAGE(PG8_SA(0, 0), a2, voffA); }
;             if (!fin) PG8_WAIT_V(8); else PG8_WAIT_V(2); PG8_WAIT_L(0); PG8_BAR; PG8_MMAF(1, 0, At, B0); PG8_MMAF(1, 1, At, B1); PG8_BAR; PG8_SCHED;
.LBB0_989:
	ds_read_b128 v[158:161], v213
	ds_read_b128 v[162:165], v213 offset:1024
	ds_read_b128 v[166:169], v213 offset:2048
	ds_read_b128 v[170:173], v213 offset:3072
	ds_read_b128 v[66:69], v214
	ds_read_b128 v[78:81], v214 offset:1024
	ds_read_b128 v[90:93], v214 offset:2048
	ds_read_b128 v[102:105], v214 offset:3072
	s_mov_b64 s[6:7], s[50:51]
	s_add_u32 s50, s6, 0x100
	s_addc_u32 s51, s7, 0
	s_cmp_eq_u32 s54, 40
	s_cselect_b64 s[26:27], -1, 0
	s_and_b64 s[8:9], s[26:27], exec
	s_cselect_b32 s25, s47, s51
	s_cselect_b32 s24, s46, s50
	s_cselect_b32 s9, s49, s53
	s_cselect_b32 s8, s48, s52
	ds_read_b128 v[174:177], v215
	ds_read_b128 v[178:181], v215 offset:1024
	ds_read_b128 v[182:185], v215 offset:2048
	ds_read_b128 v[186:189], v215 offset:3072
	ds_read_b128 v[190:193], v215 offset:4096
	ds_read_b128 v[194:197], v215 offset:5120
	ds_read_b128 v[198:201], v215 offset:6144
	ds_read_b128 v[202:205], v215 offset:7168
	s_add_u32 s6, s6, 0xb0080
	s_addc_u32 s7, s7, 0
	s_add_u32 m0, s28, 0xc000
	s_nop 0
	global_load_lds_dwordx4 v1, s[6:7]
	s_nop 0
	s_add_u32 m0, s28, 0xe000
	s_nop 0
	global_load_lds_dwordx4 v211, s[6:7]
	s_waitcnt vmcnt(8)
	s_waitcnt lgkmcnt(0)
	s_barrier
	v_mfma_f32_16x16x32_f16 v[114:117], v[158:161], v[174:177], v[154:157]
	s_setprio 1
	v_mfma_f32_16x16x32_f16 v[114:117], v[162:165], v[178:181], v[114:117]
	v_mfma_f32_16x16x32_f16 v[126:129], v[166:169], v[174:177], v[150:153]
	v_mfma_f32_16x16x32_f16 v[126:129], v[170:173], v[178:181], v[126:129]
	v_mfma_f32_16x16x32_f16 v[134:137], v[158:161], v[182:185], v[134:137]
	v_mfma_f32_16x16x32_f16 v[134:137], v[162:165], v[186:189], v[134:137]
	v_mfma_f32_16x16x32_f16 v[130:133], v[166:169], v[182:185], v[130:133]
	v_mfma_f32_16x16x32_f16 v[130:133], v[170:173], v[186:189], v[130:133]
	v_mfma_f32_16x16x32_f16 v[110:113], v[158:161], v[190:193], v[110:113]
	v_mfma_f32_16x16x32_f16 v[110:113], v[162:165], v[194:197], v[110:113]
	v_mfma_f32_16x16x32_f16 v[106:109], v[166:169], v[190:193], v[106:109]
	v_mfma_f32_16x16x32_f16 v[106:109], v[170:173], v[194:197], v[106:109]
	v_mfma_f32_16x16x32_f16 v[86:89], v[158:161], v[198:201], v[86:89]
	v_mfma_f32_16x16x32_f16 v[86:89], v[162:165], v[202:205], v[86:89]
	v_mfma_f32_16x16x32_f16 v[82:85], v[166:169], v[198:201], v[82:85]
	v_mfma_f32_16x16x32_f16 v[82:85], v[170:173], v[202:205], v[82:85]
	v_mfma_f32_16x16x32_f16 v[138:141], v[66:69], v[174:177], v[146:149]
	v_mfma_f32_16x16x32_f16 v[138:141], v[78:81], v[178:181], v[138:141]
	v_mfma_f32_16x16x32_f16 v[142:145], v[90:93], v[174:177], v[142:145]
	v_mfma_f32_16x16x32_f16 v[142:145], v[102:105], v[178:181], v[142:145]
	v_mfma_f32_16x16x32_f16 v[122:125], v[66:69], v[182:185], v[122:125]
	v_mfma_f32_16x16x32_f16 v[122:125], v[78:81], v[186:189], v[122:125]
	v_mfma_f32_16x16x32_f16 v[118:121], v[90:93], v[182:185], v[118:121]
	v_mfma_f32_16x16x32_f16 v[118:121], v[102:105], v[186:189], v[118:121]
	v_mfma_f32_16x16x32_f16 v[98:101], v[66:69], v[190:193], v[98:101]
	v_mfma_f32_16x16x32_f16 v[98:101], v[78:81], v[194:197], v[98:101]
	v_mfma_f32_16x16x32_f16 v[94:97], v[90:93], v[190:193], v[94:97]
	v_mfma_f32_16x16x32_f16 v[94:97], v[102:105], v[194:197], v[94:97]
	v_mfma_f32_16x16x32_f16 v[74:77], v[66:69], v[198:201], v[74:77]
	v_mfma_f32_16x16x32_f16 v[74:77], v[78:81], v[202:205], v[74:77]
	v_mfma_f32_16x16x32_f16 v[70:73], v[90:93], v[198:201], v[70:73]
	v_mfma_f32_16x16x32_f16 v[70:73], v[102:105], v[202:205], v[70:73]
	s_barrier
	s_setprio 0
	ds_read_b128 v[186:189], v215 offset:16384
	ds_read_b128 v[190:193], v215 offset:17408
	ds_read_b128 v[178:181], v215 offset:18432
	ds_read_b128 v[182:185], v215 offset:19456
	ds_read_b128 v[154:157], v215 offset:20480
	ds_read_b128 v[174:177], v215 offset:21504
	ds_read_b128 v[146:149], v215 offset:22528
	ds_read_b128 v[150:153], v215 offset:23552
	s_and_b64 s[6:7], s[4:5], s[26:27]
	s_mov_b64 s[26:27], -1
	s_and_b64 vcc, exec, s[6:7]
	s_cbranch_vccnz .LBB0_991
	s_add_u32 m0, s28, 0x10000
	s_nop 0
	global_load_lds_dwordx4 v210, s[8:9]
	s_nop 0
	s_add_u32 m0, s28, 0x12000
	s_nop 0
	global_load_lds_dwordx4 v212, s[8:9]
	s_add_u32 s26, s8, 0xb0000
	s_addc_u32 s27, s9, 0
	s_add_u32 m0, s28, 0x14000
	s_nop 0
	global_load_lds_dwordx4 v210, s[26:27]
	s_nop 0
	s_add_u32 m0, s28, 0x16000
	s_nop 0
	global_load_lds_dwordx4 v212, s[26:27]
	s_mov_b64 s[26:27], 0
	s_add_u32 m0, s28, 0
	s_nop 0
	global_load_lds_dwordx4 v1, s[24:25]
	s_nop 0
	s_add_u32 m0, s28, 0x2000
	s_nop 0
	global_load_lds_dwordx4 v211, s[24:25]
	s_waitcnt vmcnt(8)

; #define PG8_STAGE(bufoff, gbase, voff) do { if constexpr (ABL & 1) break; glds16s<(bufoff)>((voff)[0], (const void*)(gbase), ldsbw); glds16s<(bufoff) + 8192>((voff)[1], (const void*)(gbase), ldsbw); } while (0)
; #define PG8_LDA(dst, b, h) do { if constexpr (ABL & 4) break; _Pragma("unroll") for (int m = 0; m < 4; ++m) _Pragma("unroll") for (int k = 0; k < 2; ++k) dst[m][k] = *(const LAS f16x8*)(lds + PG8_SA(b, h) + aoff + m * 2048 + k * 1024); } while (0)
; #define PG8_MMA(ai, bj, At, Bt) do { if constexpr (ABL & 2) break; __builtin_amdgcn_s_setprio(1); _Pragma("unroll") for (int m = 0; m < 4; ++m) _Pragma("unroll") for (int n = 0; n < 2; ++n) _Pragma("unroll") for (int k = 0; k < 2; ++k) \
;         acc[ai][bj][m][n] = __builtin_amdgcn_mfma_f32_16x16x32_f16(Bt[n][k], At[m][k], acc[ai][bj][m][n], 0, 0, 0); __builtin_amdgcn_s_setprio(0); } while (0)
; #define PG8_WAIT_V(n) asm volatile("s_waitcnt vmcnt(" #n ")" ::: "memory")
; #define PG8_WAIT_L(n) asm volatile("s_waitcnt lgkmcnt(" #n ")" ::: "memory")
; #define PG8_BAR __builtin_amdgcn_s_barrier()
; #define PG8_SCHED __builtin_amdgcn_sched_barrier(0)
;     ...
;             if (!fin) PG8_WAIT_V(8); else PG8_WAIT_V(0); PG8_WAIT_L(0); PG8_BAR; PG8_MMA(0, 0, At, B0); PG8_MMA(0, 1, At, B1); PG8_BAR; PG8_SCHED;
;             PG8_LDA(At, 1, 1); if (!fin) { PG8_STAGE(PG8_SB(1, 0), b3, voffB); PG8_STAGE(PG8_SB(1, 1), b3 + hstep, voffB); PG8_STAGE(PG8_SA(1, 0), a3, voffA); }
.LBB0_997:
	s_waitcnt lgkmcnt(0)
	s_barrier
	v_mfma_f32_16x16x32_f16 v[114:117], v[166:169], v[198:201], v[114:117]
	s_setprio 1
	v_mfma_f32_16x16x32_f16 v[154:157], v[170:173], v[202:205], v[114:117]
	v_mfma_f32_16x16x32_f16 v[114:117], v[158:161], v[198:201], v[126:129]
	v_mfma_f32_16x16x32_f16 v[150:153], v[162:165], v[202:205], v[114:117]
	v_mfma_f32_16x16x32_f16 v[114:117], v[166:169], v[190:193], v[134:137]
	v_mfma_f32_16x16x32_f16 v[134:137], v[170:173], v[194:197], v[114:117]
	v_mfma_f32_16x16x32_f16 v[114:117], v[158:161], v[190:193], v[130:133]
	v_mfma_f32_16x16x32_f16 v[130:133], v[162:165], v[194:197], v[114:117]
	v_mfma_f32_16x16x32_f16 v[110:113], v[166:169], v[182:185], v[110:113]
	v_mfma_f32_16x16x32_f16 v[110:113], v[170:173], v[186:189], v[110:113]
	v_mfma_f32_16x16x32_f16 v[106:109], v[158:161], v[182:185], v[106:109]
	v_mfma_f32_16x16x32_f16 v[106:109], v[162:165], v[186:189], v[106:109]
	v_mfma_f32_16x16x32_f16 v[86:89], v[166:169], v[174:177], v[86:89]
	v_mfma_f32_16x16x32_f16 v[86:89], v[170:173], v[178:181], v[86:89]
	v_mfma_f32_16x16x32_f16 v[82:85], v[158:161], v[174:177], v[82:85]
	v_mfma_f32_16x16x32_f16 v[82:85], v[162:165], v[178:181], v[82:85]
	v_mfma_f32_16x16x32_f16 v[114:117], v[90:93], v[198:201], v[138:141]
	v_mfma_f32_16x16x32_f16 v[146:149], v[102:105], v[202:205], v[114:117]
	v_mfma_f32_16x16x32_f16 v[114:117], v[66:69], v[198:201], v[142:145]
	v_mfma_f32_16x16x32_f16 v[142:145], v[78:81], v[202:205], v[114:117]
	v_mfma_f32_16x16x32_f16 v[114:117], v[90:93], v[190:193], v[122:125]
	v_mfma_f32_16x16x32_f16 v[122:125], v[102:105], v[194:197], v[114:117]
	v_mfma_f32_16x16x32_f16 v[114:117], v[66:69], v[190:193], v[118:121]
	v_mfma_f32_16x16x32_f16 v[118:121], v[78:81], v[194:197], v[114:117]
	v_mfma_f32_16x16x32_f16 v[98:101], v[90:93], v[182:185], v[98:101]
	v_mfma_f32_16x16x32_f16 v[98:101], v[102:105], v[186:189], v[98:101]
	v_mfma_f32_16x16x32_f16 v[94:97], v[66:69], v[182:185], v[94:97]
	v_mfma_f32_16x16x32_f16 v[94:97], v[78:81], v[186:189], v[94:97]
	v_mfma_f32_16x16x32_f16 v[74:77], v[90:93], v[174:177], v[74:77]
	v_mfma_f32_16x16x32_f16 v[74:77], v[102:105], v[178:181], v[74:77]
	v_mfma_f32_16x16x32_f16 v[70:73], v[66:69], v[174:177], v[70:73]
	v_mfma_f32_16x16x32_f16 v[70:73], v[78:81], v[178:181], v[70:73]
	s_barrier
	s_setprio 0
	ds_read_b128 v[186:189], v215 offset:49152
	ds_read_b128 v[190:193], v215 offset:50176
	ds_read_b128 v[178:181], v215 offset:51200
	ds_read_b128 v[182:185], v215 offset:52224
	ds_read_b128 v[138:141], v215 offset:53248
	ds_read_b128 v[174:177], v215 offset:54272
	ds_read_b128 v[114:117], v215 offset:55296
	ds_read_b128 v[126:129], v215 offset:56320
	s_and_b64 vcc, exec, s[6:7]
	s_cbranch_vccnz .LBB0_988
	s_add_u32 s6, s24, 0x80
	s_addc_u32 s7, s25, 0
	s_add_u32 s24, s8, 0x80
	s_addc_u32 s25, s9, 0
	s_add_u32 m0, s28, 0x18000
	s_nop 0
	global_load_lds_dwordx4 v210, s[24:25]
	s_nop 0
	s_add_u32 m0, s28, 0x1a000
	s_nop 0
	global_load_lds_dwordx4 v212, s[24:25]
	s_add_u32 s8, s8, 0xb0080
	s_addc_u32 s9, s9, 0
	s_add_u32 m0, s28, 0x1c000
	s_nop 0
	global_load_lds_dwordx4 v210, s[8:9]
	s_nop 0
	s_add_u32 m0, s28, 0x1e000
	s_nop 0
	global_load_lds_dwordx4 v212, s[8:9]
	s_nop 0
	s_add_u32 m0, s28, 0x8000
	s_nop 0
	global_load_lds_dwordx4 v1, s[6:7]
	s_nop 0
	s_add_u32 m0, s28, 0xa000
	s_nop 0
	global_load_lds_dwordx4 v211, s[6:7]
	s_waitcnt vmcnt(8)
	s_branch .LBB0_988

; #define PG8_STAGE(bufoff, gbase, voff) do { if constexpr (ABL & 1) break; glds16s<(bufoff)>((voff)[0], (const void*)(gbase), ldsbw); glds16s<(bufoff) + 8192>((voff)[1], (const void*)(gbase), ldsbw); } while (0)
; #define PG8_LDA(dst, b, h) do { if constexpr (ABL & 4) break; _Pragma("unroll") for (int m = 0; m < 4; ++m) _Pragma("unroll") for (int k = 0; k < 2; ++k) dst[m][k] = *(const LAS f16x8*)(lds + PG8_SA(b, h) + aoff + m * 2048 + k * 1024); } while (0)
; #define PG8_LDB(dst, b, h) do { if constexpr (ABL & 4) break; _Pragma("unroll") for (int n = 0; n < 2; ++n) _Pragma("unroll") for (int k = 0; k < 2; ++k) dst[n][k] = *(const LAS f16x8*)(lds + PG8_SB(b, h) + boff + n * 2048 + k * 1024); } while (0)
; #define PG8_MMAF(ai, bj, At, Bt) do { if (t == 0) PG8_MMA0(ai, bj, At, Bt); else PG8_MMA(ai, bj, At, Bt); } while (0)
; #define PG8_WAIT_V(n) asm volatile("s_waitcnt vmcnt(" #n ")" ::: "memory")
; #define PG8_WAIT_L(n) asm volatile("s_waitcnt lgkmcnt(" #n ")" ::: "memory")
; #define PG8_BAR __builtin_amdgcn_s_barrier()
; #define PG8_SCHED __builtin_amdgcn_sched_barrier(0)
;     ...
;             PG8_LDB(B0, 0, 0); PG8_LDB(B1, 0, 1); PG8_SCHED; PG8_LDA(At, 0, 0); PG8_STAGE(PG8_SA(1, 1), a1 + hstep, voffA);
;             PG8_WAIT_V(8); PG8_WAIT_L(0); PG8_BAR; PG8_MMAF(0, 0, At, B0); PG8_MMAF(0, 1, At, B1); PG8_BAR; PG8_SCHED;
;             const bool fin = last && !has_next;
;             PG8_LDA(At, 0, 1); if (!fin) { PG8_STAGE(PG8_SB(0, 0), b2, voffB); PG8_STAGE(PG8_SB(0, 1), b2 + hstep, voffB); PG8_STAGE(PG8_SA(0, 0), a2, voffA); }
;             if (!fin) PG8_WAIT_V(8); else PG8_WAIT_V(2); PG8_WAIT_L(0); PG8_BAR; PG8_MMAF(1, 0, At, B0); PG8_MMAF(1, 1, At, B1); PG8_BAR; PG8_SCHED;
.LBB0_1111:
	s_ashr_i32 s43, s42, 31
	s_lshl_b64 s[8:9], s[42:43], 19
	s_add_u32 s44, s74, s8
	s_addc_u32 s45, s75, s9
	s_and_b64 s[8:9], exec, s[4:5]
	s_waitcnt lgkmcnt(0)
	ds_read_b128 v[2:5], v201
	ds_read_b128 v[6:9], v201 offset:1024
	ds_read_b128 v[10:13], v201 offset:2048
	ds_read_b128 v[14:17], v201 offset:3072
	ds_read_b128 v[18:21], v202
	ds_read_b128 v[22:25], v202 offset:1024
	ds_read_b128 v[26:29], v202 offset:2048
	ds_read_b128 v[30:33], v202 offset:3072
	s_cselect_b32 s43, s55, s45
	s_cselect_b32 s56, s54, s44
	s_ashr_i32 s41, s40, 31
	s_lshl_b64 s[8:9], s[40:41], 19
	s_add_u32 s46, s94, s8
	s_addc_u32 s47, s95, s9
	s_and_b64 s[8:9], exec, s[4:5]
	s_cselect_b32 s41, s7, s47
	s_cselect_b32 s57, s6, s46
	s_add_u32 s52, s54, 0x100
	s_addc_u32 s53, s55, 0
	s_add_u32 s26, s6, 0x100
	s_addc_u32 s27, s7, 0
	s_add_u32 s8, s54, 0x180
	s_addc_u32 s9, s55, 0
	ds_read_b128 v[34:37], v203
	ds_read_b128 v[38:41], v203 offset:1024
	ds_read_b128 v[42:45], v203 offset:2048
	ds_read_b128 v[46:49], v203 offset:3072
	ds_read_b128 v[50:53], v203 offset:4096
	ds_read_b128 v[54:57], v203 offset:5120
	ds_read_b128 v[58:61], v203 offset:6144
	ds_read_b128 v[62:65], v203 offset:7168
	s_add_u32 s24, s6, 0x180
	s_addc_u32 s25, s7, 0
	s_add_u32 s58, s54, 0x40080
	s_addc_u32 s59, s55, 0
	s_add_u32 m0, s28, 0xc000
	s_nop 0
	global_load_lds_dwordx4 v1, s[58:59]
	s_nop 0
	s_add_u32 m0, s28, 0xe000
	s_nop 0
	global_load_lds_dwordx4 v199, s[58:59]
	s_waitcnt vmcnt(8)
	s_waitcnt lgkmcnt(0)
	s_barrier
	v_mfma_f32_16x16x32_f16 v[90:93], v[2:5], v[58:61], 0
	s_setprio 1
	v_mfma_f32_16x16x32_f16 v[98:101], v[6:9], v[62:65], v[90:93]
	v_mfma_f32_16x16x32_f16 v[66:69], v[2:5], v[34:37], 0
	v_mfma_f32_16x16x32_f16 v[66:69], v[6:9], v[38:41], v[66:69]
	v_mfma_f32_16x16x32_f16 v[70:73], v[10:13], v[34:37], 0
	v_mfma_f32_16x16x32_f16 v[70:73], v[14:17], v[38:41], v[70:73]
	v_mfma_f32_16x16x32_f16 v[74:77], v[2:5], v[42:45], 0
	v_mfma_f32_16x16x32_f16 v[74:77], v[6:9], v[46:49], v[74:77]
	v_mfma_f32_16x16x32_f16 v[78:81], v[10:13], v[42:45], 0
	v_mfma_f32_16x16x32_f16 v[78:81], v[14:17], v[46:49], v[78:81]
	v_mfma_f32_16x16x32_f16 v[82:85], v[2:5], v[50:53], 0
	v_mfma_f32_16x16x32_f16 v[82:85], v[6:9], v[54:57], v[82:85]
	v_mfma_f32_16x16x32_f16 v[86:89], v[10:13], v[50:53], 0
	v_mfma_f32_16x16x32_f16 v[86:89], v[14:17], v[54:57], v[86:89]
	v_mfma_f32_16x16x32_f16 v[90:93], v[10:13], v[58:61], 0
	v_mfma_f32_16x16x32_f16 v[102:105], v[14:17], v[62:65], v[90:93]
	v_mfma_f32_16x16x32_f16 v[90:93], v[18:21], v[34:37], 0
	v_mfma_f32_16x16x32_f16 v[114:117], v[22:25], v[38:41], v[90:93]
	v_mfma_f32_16x16x32_f16 v[34:37], v[26:29], v[34:37], 0
	v_mfma_f32_16x16x32_f16 v[34:37], v[30:33], v[38:41], v[34:37]
	v_mfma_f32_16x16x32_f16 v[38:41], v[18:21], v[42:45], 0
	v_mfma_f32_16x16x32_f16 v[38:41], v[22:25], v[46:49], v[38:41]
	v_mfma_f32_16x16x32_f16 v[42:45], v[26:29], v[42:45], 0
	v_mfma_f32_16x16x32_f16 v[42:45], v[30:33], v[46:49], v[42:45]
	v_mfma_f32_16x16x32_f16 v[46:49], v[18:21], v[50:53], 0
	v_mfma_f32_16x16x32_f16 v[46:49], v[22:25], v[54:57], v[46:49]
	v_mfma_f32_16x16x32_f16 v[50:53], v[26:29], v[50:53], 0
	v_mfma_f32_16x16x32_f16 v[50:53], v[30:33], v[54:57], v[50:53]
	v_mfma_f32_16x16x32_f16 v[54:57], v[18:21], v[58:61], 0
	v_mfma_f32_16x16x32_f16 v[54:57], v[22:25], v[62:65], v[54:57]
	v_mfma_f32_16x16x32_f16 v[58:61], v[26:29], v[58:61], 0
	v_mfma_f32_16x16x32_f16 v[58:61], v[30:33], v[62:65], v[58:61]
	s_barrier
	s_setprio 0
	ds_read_b128 v[62:65], v203 offset:16384
	ds_read_b128 v[90:93], v203 offset:17408
	ds_read_b128 v[94:97], v203 offset:18432
	ds_read_b128 v[106:109], v203 offset:19456
	ds_read_b128 v[110:113], v203 offset:20480
	ds_read_b128 v[118:121], v203 offset:21504
	ds_read_b128 v[122:125], v203 offset:22528
	ds_read_b128 v[126:129], v203 offset:23552
	s_add_u32 m0, s28, 0x10000
	s_nop 0
	global_load_lds_dwordx4 v198, s[26:27]
	s_nop 0
	s_add_u32 m0, s28, 0x12000
	s_nop 0
	global_load_lds_dwordx4 v200, s[26:27]
	s_add_u32 s26, s6, 0x40100
	s_addc_u32 s27, s7, 0
	s_add_u32 m0, s28, 0x14000
	s_nop 0
	global_load_lds_dwordx4 v198, s[26:27]
	s_nop 0
	s_add_u32 m0, s28, 0x16000
	s_nop 0
	global_load_lds_dwordx4 v200, s[26:27]
	s_nop 0
	s_add_u32 m0, s28, 0
	s_nop 0
	global_load_lds_dwordx4 v1, s[52:53]
	s_nop 0
	s_add_u32 m0, s28, 0x2000
	s_nop 0
	global_load_lds_dwordx4 v199, s[52:53]
	s_waitcnt vmcnt(8)
	s_waitcnt lgkmcnt(0)
	s_barrier
	v_mfma_f32_16x16x32_f16 v[130:133], v[2:5], v[62:65], 0
	s_setprio 1
	v_mfma_f32_16x16x32_f16 v[130:133], v[6:9], v[90:93], v[130:133]
	v_mfma_f32_16x16x32_f16 v[138:141], v[2:5], v[94:97], 0
	v_mfma_f32_16x16x32_f16 v[138:141], v[6:9], v[106:109], v[138:141]
	v_mfma_f32_16x16x32_f16 v[146:149], v[2:5], v[110:113], 0
	v_mfma_f32_16x16x32_f16 v[146:149], v[6:9], v[118:121], v[146:149]
	v_mfma_f32_16x16x32_f16 v[2:5], v[2:5], v[122:125], 0
	v_mfma_f32_16x16x32_f16 v[2:5], v[6:9], v[126:129], v[2:5]
	v_mfma_f32_16x16x32_f16 v[6:9], v[10:13], v[122:125], 0
	v_mfma_f32_16x16x32_f16 v[6:9], v[14:17], v[126:129], v[6:9]
	v_mfma_f32_16x16x32_f16 v[134:137], v[10:13], v[62:65], 0
	v_mfma_f32_16x16x32_f16 v[134:137], v[14:17], v[90:93], v[134:137]
	v_mfma_f32_16x16x32_f16 v[142:145], v[10:13], v[94:97], 0
	v_mfma_f32_16x16x32_f16 v[142:145], v[14:17], v[106:109], v[142:145]
	v_mfma_f32_16x16x32_f16 v[150:153], v[10:13], v[110:113], 0
	v_mfma_f32_16x16x32_f16 v[150:153], v[14:17], v[118:121], v[150:153]
	v_mfma_f32_16x16x32_f16 v[10:13], v[18:21], v[62:65], 0
	v_mfma_f32_16x16x32_f16 v[154:157], v[22:25], v[90:93], v[10:13]
	v_mfma_f32_16x16x32_f16 v[10:13], v[26:29], v[62:65], 0
	v_mfma_f32_16x16x32_f16 v[158:161], v[30:33], v[90:93], v[10:13]
	v_mfma_f32_16x16x32_f16 v[10:13], v[18:21], v[94:97], 0
	v_mfma_f32_16x16x32_f16 v[162:165], v[22:25], v[106:109], v[10:13]
	v_mfma_f32_16x16x32_f16 v[10:13], v[26:29], v[94:97], 0
	v_mfma_f32_16x16x32_f16 v[166:169], v[30:33], v[106:109], v[10:13]
	v_mfma_f32_16x16x32_f16 v[10:13], v[18:21], v[110:113], 0
	v_mfma_f32_16x16x32_f16 v[170:173], v[22:25], v[118:121], v[10:13]
	v_mfma_f32_16x16x32_f16 v[10:13], v[26:29], v[110:113], 0
	v_mfma_f32_16x16x32_f16 v[174:177], v[30:33], v[118:121], v[10:13]
	v_mfma_f32_16x16x32_f16 v[10:13], v[18:21], v[122:125], 0
	v_mfma_f32_16x16x32_f16 v[178:181], v[22:25], v[126:129], v[10:13]
	v_mfma_f32_16x16x32_f16 v[10:13], v[26:29], v[122:125], 0
	v_mfma_f32_16x16x32_f16 v[182:185], v[30:33], v[126:129], v[10:13]
	s_barrier
; #define PG8_STAGE(bufoff, gbase, voff) do { if constexpr (ABL & 1) break; glds16s<(bufoff)>((voff)[0], (const void*)(gbase), ldsbw); glds16s<(bufoff) + 8192>((voff)[1], (const void*)(gbase), ldsbw); } while (0)
; #define PG8_LDA(dst, b, h) do { if constexpr (ABL & 4) break; _Pragma("unroll") for (int m = 0; m < 4; ++m) _Pragma("unroll") for (int k = 0; k < 2; ++k) dst[m][k] = *(const LAS f16x8*)(lds + PG8_SA(b, h) + aoff + m * 2048 + k * 1024); } while (0)
; #define PG8_LDB(dst, b, h) do { if constexpr (ABL & 4) break; _Pragma("unroll") for (int n = 0; n < 2; ++n) _Pragma("unroll") for (int k = 0; k < 2; ++k) dst[n][k] = *(const LAS f16x8*)(lds + PG8_SB(b, h) + boff + n * 2048 + k * 1024); } while (0)
; #define PG8_MMA(ai, bj, At, Bt) do { if constexpr (ABL & 2) break; __builtin_amdgcn_s_setprio(1); _Pragma("unroll") for (int m = 0; m < 4; ++m) _Pragma("unroll") for (int n = 0; n < 2; ++n) _Pragma("unroll") for (int k = 0; k < 2; ++k) \
;         acc[ai][bj][m][n] = __builtin_amdgcn_mfma_f32_16x16x32_f16(Bt[n][k], At[m][k], acc[ai][bj][m][n], 0, 0, 0); __builtin_amdgcn_s_setprio(0); } while (0)
; #define PG8_WAIT_V(n) asm volatile("s_waitcnt vmcnt(" #n ")" ::: "memory")
; #define PG8_WAIT_L(n) asm volatile("s_waitcnt lgkmcnt(" #n ")" ::: "memory")
; #define PG8_BAR __builtin_amdgcn_s_barrier()
; #define PG8_SCHED __builtin_amdgcn_sched_barrier(0)
;     ...
;             PG8_LDB(B0, 1, 0); PG8_LDB(B1, 1, 1); PG8_SCHED; PG8_LDA(At, 1, 0); if (!fin) PG8_STAGE(PG8_SA(0, 1), a2 + hstep, voffA);
;             if (!fin) PG8_WAIT_V(8); else PG8_WAIT_V(0); PG8_WAIT_L(0); PG8_BAR; PG8_MMA(0, 0, At, B0); PG8_MMA(0, 1, At, B1); PG8_BAR; PG8_SCHED;
;             PG8_LDA(At, 1, 1); if (!fin) { PG8_STAGE(PG8_SB(1, 0), b3, voffB); PG8_STAGE(PG8_SB(1, 1), b3 + hstep, voffB); PG8_STAGE(PG8_SA(1, 0), a3, voffA); }
;             if (!fin) PG8_WAIT_V(8); PG8_WAIT_L(0); PG8_BAR; PG8_MMA(1, 0, At, B0); PG8_MMA(1, 1, At, B1); PG8_BAR; PG8_SCHED;
	s_setprio 0
	s_nop 4
	ds_read_b128 v[10:13], v204
	ds_read_b128 v[14:17], v204 offset:1024
	ds_read_b128 v[18:21], v204 offset:2048
	ds_read_b128 v[22:25], v204 offset:3072
	ds_read_b128 v[186:189], v205
	ds_read_b128 v[190:193], v205 offset:1024
	ds_read_b128 v[210:213], v205 offset:2048
	ds_read_b128 v[214:217], v205 offset:3072
	ds_read_b128 v[26:29], v203 offset:32768
	ds_read_b128 v[30:33], v203 offset:33792
	ds_read_b128 v[62:65], v203 offset:34816
	ds_read_b128 v[218:221], v203 offset:35840
	ds_read_b128 v[222:225], v203 offset:36864
	ds_read_b128 v[226:229], v203 offset:37888
	ds_read_b128 v[230:233], v203 offset:38912
	ds_read_b128 v[234:237], v203 offset:39936
	s_add_u32 s26, s54, 0x40100
	s_addc_u32 s27, s55, 0
	s_add_u32 m0, s28, 0x4000
	s_nop 0
	global_load_lds_dwordx4 v1, s[26:27]
	s_nop 0
	s_add_u32 m0, s28, 0x6000
	s_nop 0
	global_load_lds_dwordx4 v199, s[26:27]
	s_waitcnt vmcnt(8)
	s_waitcnt lgkmcnt(0)
	s_barrier
	v_mfma_f32_16x16x32_f16 v[66:69], v[10:13], v[26:29], v[66:69]
	s_setprio 1
	v_mfma_f32_16x16x32_f16 v[126:129], v[14:17], v[30:33], v[66:69]
	v_mfma_f32_16x16x32_f16 v[66:69], v[18:21], v[26:29], v[70:73]
	v_mfma_f32_16x16x32_f16 v[122:125], v[22:25], v[30:33], v[66:69]
	v_mfma_f32_16x16x32_f16 v[66:69], v[10:13], v[62:65], v[74:77]
	v_mfma_f32_16x16x32_f16 v[110:113], v[14:17], v[218:221], v[66:69]
	v_mfma_f32_16x16x32_f16 v[66:69], v[18:21], v[62:65], v[78:81]
	v_mfma_f32_16x16x32_f16 v[106:109], v[22:25], v[218:221], v[66:69]
	v_mfma_f32_16x16x32_f16 v[66:69], v[10:13], v[222:225], v[82:85]
	v_mfma_f32_16x16x32_f16 v[94:97], v[14:17], v[226:229], v[66:69]
	v_mfma_f32_16x16x32_f16 v[66:69], v[18:21], v[222:225], v[86:89]
	v_mfma_f32_16x16x32_f16 v[90:93], v[22:25], v[226:229], v[66:69]
	v_mfma_f32_16x16x32_f16 v[66:69], v[10:13], v[230:233], v[98:101]
	v_mfma_f32_16x16x32_f16 v[78:81], v[14:17], v[234:237], v[66:69]
	v_mfma_f32_16x16x32_f16 v[66:69], v[18:21], v[230:233], v[102:105]
	v_mfma_f32_16x16x32_f16 v[74:77], v[22:25], v[234:237], v[66:69]
	v_mfma_f32_16x16x32_f16 v[66:69], v[186:189], v[26:29], v[114:117]
	v_mfma_f32_16x16x32_f16 v[118:121], v[190:193], v[30:33], v[66:69]
	v_mfma_f32_16x16x32_f16 v[26:29], v[210:213], v[26:29], v[34:37]
	v_mfma_f32_16x16x32_f16 v[114:117], v[214:217], v[30:33], v[26:29]
	v_mfma_f32_16x16x32_f16 v[26:29], v[186:189], v[62:65], v[38:41]
	v_mfma_f32_16x16x32_f16 v[102:105], v[190:193], v[218:221], v[26:29]
	v_mfma_f32_16x16x32_f16 v[26:29], v[210:213], v[62:65], v[42:45]
	v_mfma_f32_16x16x32_f16 v[98:101], v[214:217], v[218:221], v[26:29]
	v_mfma_f32_16x16x32_f16 v[26:29], v[186:189], v[222:225], v[46:49]
	v_mfma_f32_16x16x32_f16 v[86:89], v[190:193], v[226:229], v[26:29]
	v_mfma_f32_16x16x32_f16 v[26:29], v[210:213], v[222:225], v[50:53]
	v_mfma_f32_16x16x32_f16 v[82:85], v[214:217], v[226:229], v[26:29]
	v_mfma_f32_16x16x32_f16 v[26:29], v[186:189], v[230:233], v[54:57]
	v_mfma_f32_16x16x32_f16 v[70:73], v[190:193], v[234:237], v[26:29]
	v_mfma_f32_16x16x32_f16 v[26:29], v[210:213], v[230:233], v[58:61]
	v_mfma_f32_16x16x32_f16 v[66:69], v[214:217], v[234:237], v[26:29]
	s_barrier
	s_setprio 0
	ds_read_b128 v[34:37], v203 offset:49152
	ds_read_b128 v[38:41], v203 offset:50176
	ds_read_b128 v[218:221], v203 offset:51200
	ds_read_b128 v[222:225], v203 offset:52224
	ds_read_b128 v[226:229], v203 offset:53248
	ds_read_b128 v[230:233], v203 offset:54272
	ds_read_b128 v[234:237], v203 offset:55296
	ds_read_b128 v[238:241], v203 offset:56320
	s_add_u32 m0, s28, 0x18000
	s_nop 0
	global_load_lds_dwordx4 v198, s[24:25]
	s_nop 0
	s_add_u32 m0, s28, 0x1a000
	s_nop 0
	global_load_lds_dwordx4 v200, s[24:25]
	s_add_u32 s24, s6, 0x40180
	s_addc_u32 s25, s7, 0
	s_add_u32 m0, s28, 0x1c000
	s_nop 0
	global_load_lds_dwordx4 v198, s[24:25]
	s_nop 0
	s_add_u32 m0, s28, 0x1e000
	s_nop 0
	global_load_lds_dwordx4 v200, s[24:25]
	s_nop 0
	s_add_u32 m0, s28, 0x8000
	s_nop 0
	global_load_lds_dwordx4 v1, s[8:9]
	s_nop 0
	s_add_u32 m0, s28, 0xa000
	s_nop 0
	global_load_lds_dwordx4 v199, s[8:9]
	s_waitcnt vmcnt(8)
	s_waitcnt lgkmcnt(0)
	s_barrier
	v_mfma_f32_16x16x32_f16 v[26:29], v[10:13], v[34:37], v[130:133]
	s_setprio 1
	v_mfma_f32_16x16x32_f16 v[62:65], v[14:17], v[38:41], v[26:29]
	v_mfma_f32_16x16x32_f16 v[26:29], v[18:21], v[34:37], v[134:137]
	v_mfma_f32_16x16x32_f16 v[58:61], v[22:25], v[38:41], v[26:29]
	v_mfma_f32_16x16x32_f16 v[26:29], v[10:13], v[218:221], v[138:141]
	v_mfma_f32_16x16x32_f16 v[46:49], v[14:17], v[222:225], v[26:29]
	v_mfma_f32_16x16x32_f16 v[26:29], v[18:21], v[218:221], v[142:145]
	v_mfma_f32_16x16x32_f16 v[42:45], v[22:25], v[222:225], v[26:29]
	v_mfma_f32_16x16x32_f16 v[26:29], v[10:13], v[226:229], v[146:149]
	v_mfma_f32_16x16x32_f16 v[30:33], v[14:17], v[230:233], v[26:29]
	v_mfma_f32_16x16x32_f16 v[2:5], v[10:13], v[234:237], v[2:5]
	v_mfma_f32_16x16x32_f16 v[14:17], v[14:17], v[238:241], v[2:5]
	v_mfma_f32_16x16x32_f16 v[26:29], v[18:21], v[226:229], v[150:153]
	v_mfma_f32_16x16x32_f16 v[26:29], v[22:25], v[230:233], v[26:29]
	v_mfma_f32_16x16x32_f16 v[2:5], v[18:21], v[234:237], v[6:9]
	v_mfma_f32_16x16x32_f16 v[10:13], v[22:25], v[238:241], v[2:5]
	v_mfma_f32_16x16x32_f16 v[2:5], v[186:189], v[34:37], v[154:157]
	v_mfma_f32_16x16x32_f16 v[54:57], v[190:193], v[38:41], v[2:5]
	v_mfma_f32_16x16x32_f16 v[2:5], v[210:213], v[34:37], v[158:161]
	v_mfma_f32_16x16x32_f16 v[50:53], v[214:217], v[38:41], v[2:5]
	v_mfma_f32_16x16x32_f16 v[2:5], v[186:189], v[218:221], v[162:165]
	v_mfma_f32_16x16x32_f16 v[38:41], v[190:193], v[222:225], v[2:5]
	v_mfma_f32_16x16x32_f16 v[2:5], v[210:213], v[218:221], v[166:169]
	v_mfma_f32_16x16x32_f16 v[34:37], v[214:217], v[222:225], v[2:5]
	v_mfma_f32_16x16x32_f16 v[2:5], v[186:189], v[226:229], v[170:173]
	v_mfma_f32_16x16x32_f16 v[22:25], v[190:193], v[230:233], v[2:5]
	v_mfma_f32_16x16x32_f16 v[2:5], v[210:213], v[226:229], v[174:177]
	v_mfma_f32_16x16x32_f16 v[18:21], v[214:217], v[230:233], v[2:5]
	v_mfma_f32_16x16x32_f16 v[2:5], v[186:189], v[234:237], v[178:181]
	v_mfma_f32_16x16x32_f16 v[6:9], v[190:193], v[238:241], v[2:5]
	v_mfma_f32_16x16x32_f16 v[2:5], v[210:213], v[234:237], v[182:185]
	v_mfma_f32_16x16x32_f16 v[2:5], v[214:217], v[238:241], v[2:5]
	s_barrier
	s_setprio 0
	s_add_u32 s54, s6, 0x200
	s_addc_u32 s55, s7, 0
	s_mov_b32 s58, 0
	s_branch .LBB0_1113

; #define PG8_STAGE(bufoff, gbase, voff) do { if constexpr (ABL & 1) break; glds16s<(bufoff)>((voff)[0], (const void*)(gbase), ldsbw); glds16s<(bufoff) + 8192>((voff)[1], (const void*)(gbase), ldsbw); } while (0)
; #define PG8_LDA(dst, b, h) do { if constexpr (ABL & 4) break; _Pragma("unroll") for (int m = 0; m < 4; ++m) _Pragma("unroll") for (int k = 0; k < 2; ++k) dst[m][k] = *(const LAS f16x8*)(lds + PG8_SA(b, h) + aoff + m * 2048 + k * 1024); } while (0)
; #define PG8_LDB(dst, b, h) do { if constexpr (ABL & 4) break; _Pragma("unroll") for (int n = 0; n < 2; ++n) _Pragma("unroll") for (int k = 0; k < 2; ++k) dst[n][k] = *(const LAS f16x8*)(lds + PG8_SB(b, h) + boff + n * 2048 + k * 1024); } while (0)
; #define PG8_MMAF(ai, bj, At, Bt) do { if (t == 0) PG8_MMA0(ai, bj, At, Bt); else PG8_MMA(ai, bj, At, Bt); } while (0)
; #define PG8_WAIT_V(n) asm volatile("s_waitcnt vmcnt(" #n ")" ::: "memory")
; #define PG8_WAIT_L(n) asm volatile("s_waitcnt lgkmcnt(" #n ")" ::: "memory")
; #define PG8_BAR __builtin_amdgcn_s_barrier()
; #define PG8_SCHED __builtin_amdgcn_sched_barrier(0)
;     ...
;             PG8_LDB(B0, 0, 0); PG8_LDB(B1, 0, 1); PG8_SCHED; PG8_LDA(At, 0, 0); PG8_STAGE(PG8_SA(1, 1), a1 + hstep, voffA);
;             PG8_WAIT_V(8); PG8_WAIT_L(0); PG8_BAR; PG8_MMAF(0, 0, At, B0); PG8_MMAF(0, 1, At, B1); PG8_BAR; PG8_SCHED;
;             const bool fin = last && !has_next;
;             PG8_LDA(At, 0, 1); if (!fin) { PG8_STAGE(PG8_SB(0, 0), b2, voffB); PG8_STAGE(PG8_SB(0, 1), b2 + hstep, voffB); PG8_STAGE(PG8_SA(0, 0), a2, voffA); }
;             if (!fin) PG8_WAIT_V(8); else PG8_WAIT_V(2); PG8_WAIT_L(0); PG8_BAR; PG8_MMAF(1, 0, At, B0); PG8_MMAF(1, 1, At, B1); PG8_BAR; PG8_SCHED;
.LBB0_1163:
	s_ashr_i32 s49, s48, 31
	s_lshl_b64 s[6:7], s[48:49], 19
	s_add_u32 s50, s74, s6
	s_addc_u32 s51, s75, s7
	s_and_b64 s[6:7], exec, s[2:3]
	ds_read_b128 v[2:5], v213
	ds_read_b128 v[6:9], v213 offset:1024
	ds_read_b128 v[10:13], v213 offset:2048
	ds_read_b128 v[14:17], v213 offset:3072
	ds_read_b128 v[18:21], v214
	ds_read_b128 v[22:25], v214 offset:1024
	ds_read_b128 v[26:29], v214 offset:2048
	ds_read_b128 v[30:33], v214 offset:3072
	s_cselect_b32 s45, s37, s51
	s_cselect_b32 s49, s36, s50
	s_ashr_i32 s47, s46, 31
	s_lshl_b64 s[6:7], s[46:47], 19
	s_add_u32 s52, s94, s6
	s_addc_u32 s53, s95, s7
	s_and_b64 s[6:7], exec, s[2:3]
	s_cselect_b32 s47, s39, s53
	s_cselect_b32 s57, s38, s52
	s_add_u32 s24, s36, 0x100
	s_addc_u32 s25, s37, 0
	s_add_u32 s26, s38, 0x100
	s_addc_u32 s27, s39, 0
	s_add_u32 s6, s36, 0x180
	s_addc_u32 s7, s37, 0
	ds_read_b128 v[34:37], v215
	ds_read_b128 v[38:41], v215 offset:1024
	ds_read_b128 v[42:45], v215 offset:2048
	ds_read_b128 v[46:49], v215 offset:3072
	ds_read_b128 v[50:53], v215 offset:4096
	ds_read_b128 v[54:57], v215 offset:5120
	ds_read_b128 v[58:61], v215 offset:6144
	ds_read_b128 v[62:65], v215 offset:7168
	s_add_u32 s8, s38, 0x180
	s_addc_u32 s9, s39, 0
	s_add_u32 s54, s36, 0x40080
	s_addc_u32 s55, s37, 0
	s_add_u32 m0, s35, 0xc000
	s_nop 0
	global_load_lds_dwordx4 v1, s[54:55]
	s_nop 0
	s_add_u32 m0, s35, 0xe000
	s_nop 0
	global_load_lds_dwordx4 v211, s[54:55]
	s_waitcnt vmcnt(8)
	s_waitcnt lgkmcnt(0)
	s_barrier
	v_mfma_f32_16x16x32_f16 v[90:93], v[2:5], v[58:61], 0
	s_setprio 1
	v_mfma_f32_16x16x32_f16 v[98:101], v[6:9], v[62:65], v[90:93]
	v_mfma_f32_16x16x32_f16 v[66:69], v[2:5], v[34:37], 0
	v_mfma_f32_16x16x32_f16 v[66:69], v[6:9], v[38:41], v[66:69]
	v_mfma_f32_16x16x32_f16 v[70:73], v[10:13], v[34:37], 0
	v_mfma_f32_16x16x32_f16 v[70:73], v[14:17], v[38:41], v[70:73]
	v_mfma_f32_16x16x32_f16 v[74:77], v[2:5], v[42:45], 0
	v_mfma_f32_16x16x32_f16 v[74:77], v[6:9], v[46:49], v[74:77]
	v_mfma_f32_16x16x32_f16 v[78:81], v[10:13], v[42:45], 0
	v_mfma_f32_16x16x32_f16 v[78:81], v[14:17], v[46:49], v[78:81]
	v_mfma_f32_16x16x32_f16 v[82:85], v[2:5], v[50:53], 0
	v_mfma_f32_16x16x32_f16 v[82:85], v[6:9], v[54:57], v[82:85]
	v_mfma_f32_16x16x32_f16 v[86:89], v[10:13], v[50:53], 0
	v_mfma_f32_16x16x32_f16 v[86:89], v[14:17], v[54:57], v[86:89]
	v_mfma_f32_16x16x32_f16 v[90:93], v[10:13], v[58:61], 0
	v_mfma_f32_16x16x32_f16 v[102:105], v[14:17], v[62:65], v[90:93]
	v_mfma_f32_16x16x32_f16 v[90:93], v[18:21], v[34:37], 0
	v_mfma_f32_16x16x32_f16 v[114:117], v[22:25], v[38:41], v[90:93]
	v_mfma_f32_16x16x32_f16 v[34:37], v[26:29], v[34:37], 0
	v_mfma_f32_16x16x32_f16 v[34:37], v[30:33], v[38:41], v[34:37]
	v_mfma_f32_16x16x32_f16 v[38:41], v[18:21], v[42:45], 0
	v_mfma_f32_16x16x32_f16 v[38:41], v[22:25], v[46:49], v[38:41]
	v_mfma_f32_16x16x32_f16 v[42:45], v[26:29], v[42:45], 0
	v_mfma_f32_16x16x32_f16 v[42:45], v[30:33], v[46:49], v[42:45]
	v_mfma_f32_16x16x32_f16 v[46:49], v[18:21], v[50:53], 0
	v_mfma_f32_16x16x32_f16 v[46:49], v[22:25], v[54:57], v[46:49]
	v_mfma_f32_16x16x32_f16 v[50:53], v[26:29], v[50:53], 0
	v_mfma_f32_16x16x32_f16 v[50:53], v[30:33], v[54:57], v[50:53]
	v_mfma_f32_16x16x32_f16 v[54:57], v[18:21], v[58:61], 0
	v_mfma_f32_16x16x32_f16 v[54:57], v[22:25], v[62:65], v[54:57]
	v_mfma_f32_16x16x32_f16 v[58:61], v[26:29], v[58:61], 0
	v_mfma_f32_16x16x32_f16 v[58:61], v[30:33], v[62:65], v[58:61]
	s_barrier
	s_setprio 0
	ds_read_b128 v[62:65], v215 offset:16384
	ds_read_b128 v[90:93], v215 offset:17408
	ds_read_b128 v[94:97], v215 offset:18432
	ds_read_b128 v[106:109], v215 offset:19456
	ds_read_b128 v[110:113], v215 offset:20480
	ds_read_b128 v[118:121], v215 offset:21504
	ds_read_b128 v[122:125], v215 offset:22528
	ds_read_b128 v[126:129], v215 offset:23552
	s_add_u32 m0, s35, 0x10000
	s_nop 0
	global_load_lds_dwordx4 v210, s[26:27]
	s_nop 0
	s_add_u32 m0, s35, 0x12000
	s_nop 0
	global_load_lds_dwordx4 v212, s[26:27]
	s_add_u32 s26, s38, 0x40100
	s_addc_u32 s27, s39, 0
	s_add_u32 m0, s35, 0x14000
	s_nop 0
	global_load_lds_dwordx4 v210, s[26:27]
	s_nop 0
	s_add_u32 m0, s35, 0x16000
	s_nop 0
	global_load_lds_dwordx4 v212, s[26:27]
	s_nop 0
	s_add_u32 m0, s35, 0
	s_nop 0
	global_load_lds_dwordx4 v1, s[24:25]
	s_nop 0
	s_add_u32 m0, s35, 0x2000
	s_nop 0
	global_load_lds_dwordx4 v211, s[24:25]
	s_waitcnt vmcnt(8)
	s_waitcnt lgkmcnt(0)
	s_barrier
	v_mfma_f32_16x16x32_f16 v[134:137], v[10:13], v[62:65], 0
	s_setprio 1
	v_mfma_f32_16x16x32_f16 v[146:149], v[14:17], v[90:93], v[134:137]
	v_mfma_f32_16x16x32_f16 v[134:137], v[2:5], v[94:97], 0
	v_mfma_f32_16x16x32_f16 v[150:153], v[6:9], v[106:109], v[134:137]
	v_mfma_f32_16x16x32_f16 v[134:137], v[10:13], v[94:97], 0
	v_mfma_f32_16x16x32_f16 v[154:157], v[14:17], v[106:109], v[134:137]
	v_mfma_f32_16x16x32_f16 v[130:133], v[2:5], v[62:65], 0
	v_mfma_f32_16x16x32_f16 v[130:133], v[6:9], v[90:93], v[130:133]
	v_mfma_f32_16x16x32_f16 v[134:137], v[2:5], v[110:113], 0
	v_mfma_f32_16x16x32_f16 v[158:161], v[6:9], v[118:121], v[134:137]
	v_mfma_f32_16x16x32_f16 v[2:5], v[2:5], v[122:125], 0
	v_mfma_f32_16x16x32_f16 v[2:5], v[6:9], v[126:129], v[2:5]
	v_mfma_f32_16x16x32_f16 v[6:9], v[10:13], v[122:125], 0
	v_mfma_f32_16x16x32_f16 v[6:9], v[14:17], v[126:129], v[6:9]
	v_mfma_f32_16x16x32_f16 v[134:137], v[10:13], v[110:113], 0
	v_mfma_f32_16x16x32_f16 v[162:165], v[14:17], v[118:121], v[134:137]
	v_mfma_f32_16x16x32_f16 v[10:13], v[18:21], v[62:65], 0
	v_mfma_f32_16x16x32_f16 v[166:169], v[22:25], v[90:93], v[10:13]
	v_mfma_f32_16x16x32_f16 v[10:13], v[26:29], v[62:65], 0
	v_mfma_f32_16x16x32_f16 v[170:173], v[30:33], v[90:93], v[10:13]
	v_mfma_f32_16x16x32_f16 v[10:13], v[18:21], v[94:97], 0
	v_mfma_f32_16x16x32_f16 v[174:177], v[22:25], v[106:109], v[10:13]
	v_mfma_f32_16x16x32_f16 v[10:13], v[26:29], v[94:97], 0
	v_mfma_f32_16x16x32_f16 v[178:181], v[30:33], v[106:109], v[10:13]
	v_mfma_f32_16x16x32_f16 v[10:13], v[18:21], v[110:113], 0
	v_mfma_f32_16x16x32_f16 v[182:185], v[22:25], v[118:121], v[10:13]
	v_mfma_f32_16x16x32_f16 v[10:13], v[26:29], v[110:113], 0
	v_mfma_f32_16x16x32_f16 v[118:121], v[30:33], v[118:121], v[10:13]
	v_mfma_f32_16x16x32_f16 v[10:13], v[18:21], v[122:125], 0
	v_mfma_f32_16x16x32_f16 v[186:189], v[22:25], v[126:129], v[10:13]
	v_mfma_f32_16x16x32_f16 v[10:13], v[26:29], v[122:125], 0
	v_mfma_f32_16x16x32_f16 v[122:125], v[30:33], v[126:129], v[10:13]
	s_barrier
; #define PG8_STAGE(bufoff, gbase, voff) do { if constexpr (ABL & 1) break; glds16s<(bufoff)>((voff)[0], (const void*)(gbase), ldsbw); glds16s<(bufoff) + 8192>((voff)[1], (const void*)(gbase), ldsbw); } while (0)
; #define PG8_LDA(dst, b, h) do { if constexpr (ABL & 4) break; _Pragma("unroll") for (int m = 0; m < 4; ++m) _Pragma("unroll") for (int k = 0; k < 2; ++k) dst[m][k] = *(const LAS f16x8*)(lds + PG8_SA(b, h) + aoff + m * 2048 + k * 1024); } while (0)
; #define PG8_LDB(dst, b, h) do { if constexpr (ABL & 4) break; _Pragma("unroll") for (int n = 0; n < 2; ++n) _Pragma("unroll") for (int k = 0; k < 2; ++k) dst[n][k] = *(const LAS f16x8*)(lds + PG8_SB(b, h) + boff + n * 2048 + k * 1024); } while (0)
; #define PG8_MMA(ai, bj, At, Bt) do { if constexpr (ABL & 2) break; __builtin_amdgcn_s_setprio(1); _Pragma("unroll") for (int m = 0; m < 4; ++m) _Pragma("unroll") for (int n = 0; n < 2; ++n) _Pragma("unroll") for (int k = 0; k < 2; ++k) \
;         acc[ai][bj][m][n] = __builtin_amdgcn_mfma_f32_16x16x32_f16(Bt[n][k], At[m][k], acc[ai][bj][m][n], 0, 0, 0); __builtin_amdgcn_s_setprio(0); } while (0)
; #define PG8_WAIT_V(n) asm volatile("s_waitcnt vmcnt(" #n ")" ::: "memory")
; #define PG8_WAIT_L(n) asm volatile("s_waitcnt lgkmcnt(" #n ")" ::: "memory")
; #define PG8_BAR __builtin_amdgcn_s_barrier()
; #define PG8_SCHED __builtin_amdgcn_sched_barrier(0)
;     ...
;             PG8_LDB(B0, 1, 0); PG8_LDB(B1, 1, 1); PG8_SCHED; PG8_LDA(At, 1, 0); if (!fin) PG8_STAGE(PG8_SA(0, 1), a2 + hstep, voffA);
;             if (!fin) PG8_WAIT_V(8); else PG8_WAIT_V(0); PG8_WAIT_L(0); PG8_BAR; PG8_MMA(0, 0, At, B0); PG8_MMA(0, 1, At, B1); PG8_BAR; PG8_SCHED;
;             PG8_LDA(At, 1, 1); if (!fin) { PG8_STAGE(PG8_SB(1, 0), b3, voffB); PG8_STAGE(PG8_SB(1, 1), b3 + hstep, voffB); PG8_STAGE(PG8_SA(1, 0), a3, voffA); }
;             if (!fin) PG8_WAIT_V(8); PG8_WAIT_L(0); PG8_BAR; PG8_MMA(1, 0, At, B0); PG8_MMA(1, 1, At, B1); PG8_BAR; PG8_SCHED;
	s_setprio 0
	s_nop 4
	ds_read_b128 v[10:13], v216
	ds_read_b128 v[14:17], v216 offset:1024
	ds_read_b128 v[18:21], v216 offset:2048
	ds_read_b128 v[22:25], v216 offset:3072
	ds_read_b128 v[190:193], v217
	ds_read_b128 v[194:197], v217 offset:1024
	ds_read_b128 v[198:201], v217 offset:2048
	ds_read_b128 v[202:205], v217 offset:3072
	ds_read_b128 v[26:29], v215 offset:32768
	ds_read_b128 v[30:33], v215 offset:33792
	ds_read_b128 v[62:65], v215 offset:34816
	ds_read_b128 v[218:221], v215 offset:35840
	ds_read_b128 v[222:225], v215 offset:36864
	ds_read_b128 v[226:229], v215 offset:37888
	ds_read_b128 v[230:233], v215 offset:38912
	ds_read_b128 v[234:237], v215 offset:39936
	s_add_u32 s24, s36, 0x40100
	s_addc_u32 s25, s37, 0
	s_add_u32 m0, s35, 0x4000
	s_nop 0
	global_load_lds_dwordx4 v1, s[24:25]
	s_nop 0
	s_add_u32 m0, s35, 0x6000
	s_nop 0
	global_load_lds_dwordx4 v211, s[24:25]
	s_waitcnt vmcnt(8)
	s_waitcnt lgkmcnt(0)
	s_barrier
	v_mfma_f32_16x16x32_f16 v[66:69], v[10:13], v[26:29], v[66:69]
	s_setprio 1
	v_mfma_f32_16x16x32_f16 v[142:145], v[14:17], v[30:33], v[66:69]
	v_mfma_f32_16x16x32_f16 v[66:69], v[18:21], v[26:29], v[70:73]
	v_mfma_f32_16x16x32_f16 v[138:141], v[22:25], v[30:33], v[66:69]
	v_mfma_f32_16x16x32_f16 v[66:69], v[10:13], v[62:65], v[74:77]
	v_mfma_f32_16x16x32_f16 v[110:113], v[14:17], v[218:221], v[66:69]
	v_mfma_f32_16x16x32_f16 v[66:69], v[18:21], v[62:65], v[78:81]
	v_mfma_f32_16x16x32_f16 v[106:109], v[22:25], v[218:221], v[66:69]
	v_mfma_f32_16x16x32_f16 v[66:69], v[10:13], v[222:225], v[82:85]
	v_mfma_f32_16x16x32_f16 v[94:97], v[14:17], v[226:229], v[66:69]
	v_mfma_f32_16x16x32_f16 v[66:69], v[18:21], v[222:225], v[86:89]
	v_mfma_f32_16x16x32_f16 v[90:93], v[22:25], v[226:229], v[66:69]
	v_mfma_f32_16x16x32_f16 v[66:69], v[10:13], v[230:233], v[98:101]
	v_mfma_f32_16x16x32_f16 v[78:81], v[14:17], v[234:237], v[66:69]
	v_mfma_f32_16x16x32_f16 v[66:69], v[18:21], v[230:233], v[102:105]
	v_mfma_f32_16x16x32_f16 v[74:77], v[22:25], v[234:237], v[66:69]
	v_mfma_f32_16x16x32_f16 v[66:69], v[190:193], v[26:29], v[114:117]
	v_mfma_f32_16x16x32_f16 v[134:137], v[194:197], v[30:33], v[66:69]
	v_mfma_f32_16x16x32_f16 v[26:29], v[198:201], v[26:29], v[34:37]
	v_mfma_f32_16x16x32_f16 v[126:129], v[202:205], v[30:33], v[26:29]
	v_mfma_f32_16x16x32_f16 v[26:29], v[190:193], v[62:65], v[38:41]
	v_mfma_f32_16x16x32_f16 v[102:105], v[194:197], v[218:221], v[26:29]
	v_mfma_f32_16x16x32_f16 v[26:29], v[198:201], v[62:65], v[42:45]
	v_mfma_f32_16x16x32_f16 v[98:101], v[202:205], v[218:221], v[26:29]
	v_mfma_f32_16x16x32_f16 v[26:29], v[190:193], v[222:225], v[46:49]
	v_mfma_f32_16x16x32_f16 v[86:89], v[194:197], v[226:229], v[26:29]
	v_mfma_f32_16x16x32_f16 v[26:29], v[198:201], v[222:225], v[50:53]
	v_mfma_f32_16x16x32_f16 v[82:85], v[202:205], v[226:229], v[26:29]
	v_mfma_f32_16x16x32_f16 v[26:29], v[190:193], v[230:233], v[54:57]
	v_mfma_f32_16x16x32_f16 v[70:73], v[194:197], v[234:237], v[26:29]
	v_mfma_f32_16x16x32_f16 v[26:29], v[198:201], v[230:233], v[58:61]
	v_mfma_f32_16x16x32_f16 v[66:69], v[202:205], v[234:237], v[26:29]
	s_barrier
	s_setprio 0
	ds_read_b128 v[34:37], v215 offset:49152
	ds_read_b128 v[38:41], v215 offset:50176
	ds_read_b128 v[114:117], v215 offset:51200
	ds_read_b128 v[218:221], v215 offset:52224
	ds_read_b128 v[222:225], v215 offset:53248
	ds_read_b128 v[226:229], v215 offset:54272
	ds_read_b128 v[230:233], v215 offset:55296
	ds_read_b128 v[234:237], v215 offset:56320
	s_add_u32 m0, s35, 0x18000
	s_nop 0
	global_load_lds_dwordx4 v210, s[8:9]
	s_nop 0
	s_add_u32 m0, s35, 0x1a000
	s_nop 0
	global_load_lds_dwordx4 v212, s[8:9]
	s_add_u32 s8, s38, 0x40180
	s_addc_u32 s9, s39, 0
	s_add_u32 m0, s35, 0x1c000
	s_nop 0
	global_load_lds_dwordx4 v210, s[8:9]
	s_nop 0
	s_add_u32 m0, s35, 0x1e000
	s_nop 0
	global_load_lds_dwordx4 v212, s[8:9]
	s_nop 0
	s_add_u32 m0, s35, 0x8000
	s_nop 0
	global_load_lds_dwordx4 v1, s[6:7]
	s_nop 0
	s_add_u32 m0, s35, 0xa000
	s_nop 0
	global_load_lds_dwordx4 v211, s[6:7]
	s_waitcnt vmcnt(8)
	s_waitcnt lgkmcnt(0)
	s_barrier
	v_mfma_f32_16x16x32_f16 v[26:29], v[10:13], v[34:37], v[130:133]
	s_setprio 1
	v_mfma_f32_16x16x32_f16 v[62:65], v[14:17], v[38:41], v[26:29]
	v_mfma_f32_16x16x32_f16 v[26:29], v[18:21], v[34:37], v[146:149]
	v_mfma_f32_16x16x32_f16 v[58:61], v[22:25], v[38:41], v[26:29]
	v_mfma_f32_16x16x32_f16 v[26:29], v[10:13], v[114:117], v[150:153]
	v_mfma_f32_16x16x32_f16 v[46:49], v[14:17], v[218:221], v[26:29]
	v_mfma_f32_16x16x32_f16 v[26:29], v[18:21], v[114:117], v[154:157]
	v_mfma_f32_16x16x32_f16 v[42:45], v[22:25], v[218:221], v[26:29]
	v_mfma_f32_16x16x32_f16 v[26:29], v[10:13], v[222:225], v[158:161]
	v_mfma_f32_16x16x32_f16 v[30:33], v[14:17], v[226:229], v[26:29]
	v_mfma_f32_16x16x32_f16 v[2:5], v[10:13], v[230:233], v[2:5]
	v_mfma_f32_16x16x32_f16 v[14:17], v[14:17], v[234:237], v[2:5]
	v_mfma_f32_16x16x32_f16 v[26:29], v[18:21], v[222:225], v[162:165]
	v_mfma_f32_16x16x32_f16 v[26:29], v[22:25], v[226:229], v[26:29]
	v_mfma_f32_16x16x32_f16 v[2:5], v[18:21], v[230:233], v[6:9]
	v_mfma_f32_16x16x32_f16 v[10:13], v[22:25], v[234:237], v[2:5]
	v_mfma_f32_16x16x32_f16 v[2:5], v[190:193], v[34:37], v[166:169]
	v_mfma_f32_16x16x32_f16 v[54:57], v[194:197], v[38:41], v[2:5]
	v_mfma_f32_16x16x32_f16 v[2:5], v[198:201], v[34:37], v[170:173]
	v_mfma_f32_16x16x32_f16 v[50:53], v[202:205], v[38:41], v[2:5]
	v_mfma_f32_16x16x32_f16 v[2:5], v[190:193], v[114:117], v[174:177]
	v_mfma_f32_16x16x32_f16 v[38:41], v[194:197], v[218:221], v[2:5]
	v_mfma_f32_16x16x32_f16 v[2:5], v[198:201], v[114:117], v[178:181]
	v_mfma_f32_16x16x32_f16 v[34:37], v[202:205], v[218:221], v[2:5]
	v_mfma_f32_16x16x32_f16 v[2:5], v[190:193], v[222:225], v[182:185]
	v_mfma_f32_16x16x32_f16 v[22:25], v[194:197], v[226:229], v[2:5]
	v_mfma_f32_16x16x32_f16 v[2:5], v[198:201], v[222:225], v[118:121]
	v_mfma_f32_16x16x32_f16 v[18:21], v[202:205], v[226:229], v[2:5]
	v_mfma_f32_16x16x32_f16 v[2:5], v[190:193], v[230:233], v[186:189]
	v_mfma_f32_16x16x32_f16 v[6:9], v[194:197], v[234:237], v[2:5]
	v_mfma_f32_16x16x32_f16 v[2:5], v[198:201], v[230:233], v[122:125]
	v_mfma_f32_16x16x32_f16 v[2:5], v[202:205], v[234:237], v[2:5]
	s_barrier
	s_setprio 0
	s_mov_b32 s58, 0
	s_mov_b64 s[54:55], 0
	s_branch .LBB0_1165

; #define PG8_STAGE(bufoff, gbase, voff) do { if constexpr (ABL & 1) break; glds16s<(bufoff)>((voff)[0], (const void*)(gbase), ldsbw); glds16s<(bufoff) + 8192>((voff)[1], (const void*)(gbase), ldsbw); } while (0)
; #define PG8_LDA(dst, b, h) do { if constexpr (ABL & 4) break; _Pragma("unroll") for (int m = 0; m < 4; ++m) _Pragma("unroll") for (int k = 0; k < 2; ++k) dst[m][k] = *(const LAS f16x8*)(lds + PG8_SA(b, h) + aoff + m * 2048 + k * 1024); } while (0)
; #define PG8_LDB(dst, b, h) do { if constexpr (ABL & 4) break; _Pragma("unroll") for (int n = 0; n < 2; ++n) _Pragma("unroll") for (int k = 0; k < 2; ++k) dst[n][k] = *(const LAS f16x8*)(lds + PG8_SB(b, h) + boff + n * 2048 + k * 1024); } while (0)
; #define PG8_MMAF(ai, bj, At, Bt) do { if (t == 0) PG8_MMA0(ai, bj, At, Bt); else PG8_MMA(ai, bj, At, Bt); } while (0)
; #define PG8_WAIT_V(n) asm volatile("s_waitcnt vmcnt(" #n ")" ::: "memory")
; #define PG8_WAIT_L(n) asm volatile("s_waitcnt lgkmcnt(" #n ")" ::: "memory")
; #define PG8_BAR __builtin_amdgcn_s_barrier()
; #define PG8_SCHED __builtin_amdgcn_sched_barrier(0)
;     ...
;         for (int t = 0; t < nt; t += 2) {
;             const bool last = (t == nt - 2);
;             const char* a1 = cA + (size_t)(t + 1) * kstep;
;             const char* a2 = last ? nA : cA + (size_t)(t + 2) * kstep; const char* b2 = last ? nB : cB + (size_t)(t + 2) * kstep;
;             const char* a3 = a2 + kstep; const char* b3 = b2 + kstep;
;             if (last && has_next) S.a_ready(nxt);
;             if constexpr (SP2) {
;             PG8_LDB(B0, 0, 0); PG8_LDB(B1, 0, 1); PG8_SCHED; PG8_LDA(At, 0, 0); PG8_STAGE(PG8_SA(1, 1), a1 + hstep, voffA);
;             PG8_WAIT_V(8); PG8_WAIT_L(0); PG8_BAR; PG8_MMAF(0, 0, At, B0); PG8_MMAF(0, 1, At, B1); PG8_BAR; PG8_SCHED;
;             const bool fin = last && !has_next;
;             PG8_LDA(At, 0, 1); if (!fin) { PG8_STAGE(PG8_SB(0, 0), b2, voffB); PG8_STAGE(PG8_SB(0, 1), b2 + hstep, voffB); PG8_STAGE(PG8_SA(0, 0), a2, voffA); }
;             if (!fin) PG8_WAIT_V(8); else PG8_WAIT_V(2); PG8_WAIT_L(0); PG8_BAR; PG8_MMAF(1, 0, At, B0); PG8_MMAF(1, 1, At, B1); PG8_BAR; PG8_SCHED;
.LBB0_1165:
	s_add_u32 s26, s36, s54
	s_addc_u32 s27, s37, s55
	ds_read_b128 v[158:161], v213
	ds_read_b128 v[162:165], v213 offset:1024
	ds_read_b128 v[166:169], v213 offset:2048
	ds_read_b128 v[170:173], v213 offset:3072
	ds_read_b128 v[130:133], v214
	ds_read_b128 v[146:149], v214 offset:1024
	ds_read_b128 v[150:153], v214 offset:2048
	ds_read_b128 v[154:157], v214 offset:3072
	s_add_u32 s24, s26, 0x200
	s_addc_u32 s25, s27, 0
	s_add_u32 s6, s38, s54
	s_addc_u32 s7, s39, s55
	s_add_u32 s59, s6, 0x200
	s_addc_u32 s60, s7, 0
	s_cmp_eq_u32 s58, 12
	s_cselect_b64 s[6:7], -1, 0
	s_and_b64 s[8:9], s[6:7], exec
	s_cselect_b32 s25, s45, s25
	s_cselect_b32 s24, s49, s24
	s_cselect_b32 s9, s47, s60
	s_cselect_b32 s8, s57, s59
	ds_read_b128 v[174:177], v215
	ds_read_b128 v[178:181], v215 offset:1024
	ds_read_b128 v[182:185], v215 offset:2048
	ds_read_b128 v[186:189], v215 offset:3072
	ds_read_b128 v[190:193], v215 offset:4096
	ds_read_b128 v[194:197], v215 offset:5120
	ds_read_b128 v[198:201], v215 offset:6144
	ds_read_b128 v[202:205], v215 offset:7168
	s_add_u32 s26, s26, 0x40180
	s_addc_u32 s27, s27, 0
	s_add_u32 m0, s35, 0xc000
	s_nop 0
	global_load_lds_dwordx4 v1, s[26:27]
	s_nop 0
	s_add_u32 m0, s35, 0xe000
	s_nop 0
	global_load_lds_dwordx4 v211, s[26:27]
	s_waitcnt vmcnt(8)
	s_waitcnt lgkmcnt(0)
	s_barrier
	v_mfma_f32_16x16x32_f16 v[114:117], v[158:161], v[174:177], v[142:145]
	s_setprio 1
	v_mfma_f32_16x16x32_f16 v[114:117], v[162:165], v[178:181], v[114:117]
	v_mfma_f32_16x16x32_f16 v[118:121], v[166:169], v[174:177], v[138:141]
	v_mfma_f32_16x16x32_f16 v[118:121], v[170:173], v[178:181], v[118:121]
	v_mfma_f32_16x16x32_f16 v[110:113], v[158:161], v[182:185], v[110:113]
	v_mfma_f32_16x16x32_f16 v[110:113], v[162:165], v[186:189], v[110:113]
	v_mfma_f32_16x16x32_f16 v[106:109], v[166:169], v[182:185], v[106:109]
	v_mfma_f32_16x16x32_f16 v[106:109], v[170:173], v[186:189], v[106:109]
	v_mfma_f32_16x16x32_f16 v[94:97], v[158:161], v[190:193], v[94:97]
	v_mfma_f32_16x16x32_f16 v[94:97], v[162:165], v[194:197], v[94:97]
	v_mfma_f32_16x16x32_f16 v[90:93], v[166:169], v[190:193], v[90:93]
	v_mfma_f32_16x16x32_f16 v[90:93], v[170:173], v[194:197], v[90:93]
	v_mfma_f32_16x16x32_f16 v[78:81], v[158:161], v[198:201], v[78:81]
	v_mfma_f32_16x16x32_f16 v[78:81], v[162:165], v[202:205], v[78:81]
	v_mfma_f32_16x16x32_f16 v[74:77], v[166:169], v[198:201], v[74:77]
	v_mfma_f32_16x16x32_f16 v[74:77], v[170:173], v[202:205], v[74:77]
	v_mfma_f32_16x16x32_f16 v[122:125], v[130:133], v[174:177], v[134:137]
	v_mfma_f32_16x16x32_f16 v[122:125], v[146:149], v[178:181], v[122:125]
	v_mfma_f32_16x16x32_f16 v[126:129], v[150:153], v[174:177], v[126:129]
	v_mfma_f32_16x16x32_f16 v[126:129], v[154:157], v[178:181], v[126:129]
	v_mfma_f32_16x16x32_f16 v[102:105], v[130:133], v[182:185], v[102:105]
	v_mfma_f32_16x16x32_f16 v[102:105], v[146:149], v[186:189], v[102:105]
	v_mfma_f32_16x16x32_f16 v[98:101], v[150:153], v[182:185], v[98:101]
	v_mfma_f32_16x16x32_f16 v[98:101], v[154:157], v[186:189], v[98:101]
	v_mfma_f32_16x16x32_f16 v[86:89], v[130:133], v[190:193], v[86:89]
	v_mfma_f32_16x16x32_f16 v[86:89], v[146:149], v[194:197], v[86:89]
	v_mfma_f32_16x16x32_f16 v[82:85], v[150:153], v[190:193], v[82:85]
	v_mfma_f32_16x16x32_f16 v[82:85], v[154:157], v[194:197], v[82:85]
	v_mfma_f32_16x16x32_f16 v[70:73], v[130:133], v[198:201], v[70:73]
	v_mfma_f32_16x16x32_f16 v[70:73], v[146:149], v[202:205], v[70:73]
	v_mfma_f32_16x16x32_f16 v[66:69], v[150:153], v[198:201], v[66:69]
	v_mfma_f32_16x16x32_f16 v[66:69], v[154:157], v[202:205], v[66:69]
	s_barrier
	s_setprio 0
	ds_read_b128 v[186:189], v215 offset:16384
	ds_read_b128 v[190:193], v215 offset:17408
	ds_read_b128 v[178:181], v215 offset:18432
	ds_read_b128 v[182:185], v215 offset:19456
	ds_read_b128 v[142:145], v215 offset:20480
	ds_read_b128 v[174:177], v215 offset:21504
	ds_read_b128 v[134:137], v215 offset:22528
	ds_read_b128 v[138:141], v215 offset:23552
	s_and_b64 s[6:7], s[2:3], s[6:7]
	s_mov_b64 s[26:27], -1
	s_and_b64 vcc, exec, s[6:7]
	s_cbranch_vccnz .LBB0_1167
	s_add_u32 m0, s35, 0x10000
	s_nop 0
	global_load_lds_dwordx4 v210, s[8:9]
	s_nop 0
	s_add_u32 m0, s35, 0x12000
	s_nop 0
	global_load_lds_dwordx4 v212, s[8:9]
	s_add_u32 s26, s8, 0x40000
	s_addc_u32 s27, s9, 0
	s_add_u32 m0, s35, 0x14000
	s_nop 0
	global_load_lds_dwordx4 v210, s[26:27]
	s_nop 0
	s_add_u32 m0, s35, 0x16000
	s_nop 0
	global_load_lds_dwordx4 v212, s[26:27]
	s_mov_b64 s[26:27], 0
	s_add_u32 m0, s35, 0
	s_nop 0
	global_load_lds_dwordx4 v1, s[24:25]
	s_nop 0
	s_add_u32 m0, s35, 0x2000
	s_nop 0
	global_load_lds_dwordx4 v211, s[24:25]
	s_waitcnt vmcnt(8)

; #define PG8_STAGE(bufoff, gbase, voff) do { if constexpr (ABL & 1) break; glds16s<(bufoff)>((voff)[0], (const void*)(gbase), ldsbw); glds16s<(bufoff) + 8192>((voff)[1], (const void*)(gbase), ldsbw); } while (0)
; #define PG8_LDA(dst, b, h) do { if constexpr (ABL & 4) break; _Pragma("unroll") for (int m = 0; m < 4; ++m) _Pragma("unroll") for (int k = 0; k < 2; ++k) dst[m][k] = *(const LAS f16x8*)(lds + PG8_SA(b, h) + aoff + m * 2048 + k * 1024); } while (0)
; #define PG8_MMA(ai, bj, At, Bt) do { if constexpr (ABL & 2) break; __builtin_amdgcn_s_setprio(1); _Pragma("unroll") for (int m = 0; m < 4; ++m) _Pragma("unroll") for (int n = 0; n < 2; ++n) _Pragma("unroll") for (int k = 0; k < 2; ++k) \
;         acc[ai][bj][m][n] = __builtin_amdgcn_mfma_f32_16x16x32_f16(Bt[n][k], At[m][k], acc[ai][bj][m][n], 0, 0, 0); __builtin_amdgcn_s_setprio(0); } while (0)
; #define PG8_WAIT_V(n) asm volatile("s_waitcnt vmcnt(" #n ")" ::: "memory")
; #define PG8_WAIT_L(n) asm volatile("s_waitcnt lgkmcnt(" #n ")" ::: "memory")
; #define PG8_BAR __builtin_amdgcn_s_barrier()
; #define PG8_SCHED __builtin_amdgcn_sched_barrier(0)
;     ...
;             if (!fin) PG8_WAIT_V(8); else PG8_WAIT_V(0); PG8_WAIT_L(0); PG8_BAR; PG8_MMA(0, 0, At, B0); PG8_MMA(0, 1, At, B1); PG8_BAR; PG8_SCHED;
;             PG8_LDA(At, 1, 1); if (!fin) { PG8_STAGE(PG8_SB(1, 0), b3, voffB); PG8_STAGE(PG8_SB(1, 1), b3 + hstep, voffB); PG8_STAGE(PG8_SA(1, 0), a3, voffA); }
.LBB0_1173:
	s_waitcnt lgkmcnt(0)
	s_barrier
	v_mfma_f32_16x16x32_f16 v[114:117], v[158:161], v[198:201], v[114:117]
	s_setprio 1
	v_mfma_f32_16x16x32_f16 v[142:145], v[162:165], v[202:205], v[114:117]
	v_mfma_f32_16x16x32_f16 v[114:117], v[166:169], v[198:201], v[118:121]
	v_mfma_f32_16x16x32_f16 v[138:141], v[170:173], v[202:205], v[114:117]
	v_mfma_f32_16x16x32_f16 v[110:113], v[158:161], v[190:193], v[110:113]
	v_mfma_f32_16x16x32_f16 v[110:113], v[162:165], v[194:197], v[110:113]
	v_mfma_f32_16x16x32_f16 v[106:109], v[166:169], v[190:193], v[106:109]
	v_mfma_f32_16x16x32_f16 v[106:109], v[170:173], v[194:197], v[106:109]
	v_mfma_f32_16x16x32_f16 v[94:97], v[158:161], v[182:185], v[94:97]
	v_mfma_f32_16x16x32_f16 v[94:97], v[162:165], v[186:189], v[94:97]
	v_mfma_f32_16x16x32_f16 v[90:93], v[166:169], v[182:185], v[90:93]
	v_mfma_f32_16x16x32_f16 v[90:93], v[170:173], v[186:189], v[90:93]
	v_mfma_f32_16x16x32_f16 v[78:81], v[158:161], v[174:177], v[78:81]
	v_mfma_f32_16x16x32_f16 v[78:81], v[162:165], v[178:181], v[78:81]
	v_mfma_f32_16x16x32_f16 v[74:77], v[166:169], v[174:177], v[74:77]
	v_mfma_f32_16x16x32_f16 v[74:77], v[170:173], v[178:181], v[74:77]
	v_mfma_f32_16x16x32_f16 v[114:117], v[130:133], v[198:201], v[122:125]
	v_mfma_f32_16x16x32_f16 v[134:137], v[146:149], v[202:205], v[114:117]
	v_mfma_f32_16x16x32_f16 v[114:117], v[150:153], v[198:201], v[126:129]
	v_mfma_f32_16x16x32_f16 v[126:129], v[154:157], v[202:205], v[114:117]
	v_mfma_f32_16x16x32_f16 v[102:105], v[130:133], v[190:193], v[102:105]
	v_mfma_f32_16x16x32_f16 v[102:105], v[146:149], v[194:197], v[102:105]
	v_mfma_f32_16x16x32_f16 v[98:101], v[150:153], v[190:193], v[98:101]
	v_mfma_f32_16x16x32_f16 v[98:101], v[154:157], v[194:197], v[98:101]
	v_mfma_f32_16x16x32_f16 v[86:89], v[130:133], v[182:185], v[86:89]
	v_mfma_f32_16x16x32_f16 v[86:89], v[146:149], v[186:189], v[86:89]
	v_mfma_f32_16x16x32_f16 v[82:85], v[150:153], v[182:185], v[82:85]
	v_mfma_f32_16x16x32_f16 v[82:85], v[154:157], v[186:189], v[82:85]
	v_mfma_f32_16x16x32_f16 v[70:73], v[130:133], v[174:177], v[70:73]
	v_mfma_f32_16x16x32_f16 v[70:73], v[146:149], v[178:181], v[70:73]
	v_mfma_f32_16x16x32_f16 v[66:69], v[150:153], v[174:177], v[66:69]
	v_mfma_f32_16x16x32_f16 v[66:69], v[154:157], v[178:181], v[66:69]
	s_barrier
	s_setprio 0
	ds_read_b128 v[186:189], v215 offset:49152
	ds_read_b128 v[190:193], v215 offset:50176
	ds_read_b128 v[178:181], v215 offset:51200
	ds_read_b128 v[182:185], v215 offset:52224
	ds_read_b128 v[122:125], v215 offset:53248
	ds_read_b128 v[174:177], v215 offset:54272
	ds_read_b128 v[114:117], v215 offset:55296
	ds_read_b128 v[118:121], v215 offset:56320
	s_and_b64 vcc, exec, s[6:7]
	s_cbranch_vccnz .LBB0_1164
	s_add_u32 s6, s24, 0x80
	s_addc_u32 s7, s25, 0
	s_add_u32 s24, s8, 0x80
	s_addc_u32 s25, s9, 0
	s_add_u32 m0, s35, 0x18000
	s_nop 0
	global_load_lds_dwordx4 v210, s[24:25]
	s_nop 0
	s_add_u32 m0, s35, 0x1a000
	s_nop 0
	global_load_lds_dwordx4 v212, s[24:25]
	s_add_u32 s8, s8, 0x40080
	s_addc_u32 s9, s9, 0
	s_add_u32 m0, s35, 0x1c000
	s_nop 0
	global_load_lds_dwordx4 v210, s[8:9]
	s_nop 0
	s_add_u32 m0, s35, 0x1e000
	s_nop 0
	global_load_lds_dwordx4 v212, s[8:9]
	s_nop 0
	s_add_u32 m0, s35, 0x8000
	s_nop 0
	global_load_lds_dwordx4 v1, s[6:7]
	s_nop 0
	s_add_u32 m0, s35, 0xa000
	s_nop 0
	global_load_lds_dwordx4 v211, s[6:7]
	s_waitcnt vmcnt(8)
	s_branch .LBB0_1164
